# v47 with all s_setprio removed from the K-loops
# speedup vs baseline: 1.0105x; 1.0049x over previous
.LBB0_261:
	s_add_u32 s0, s76, 0xfff80080
	s_addc_u32 s1, s77, -1
	s_and_b64 s[84:85], s[84:85], exec
	s_cselect_b32 vcc_hi, s22, s1
	s_cselect_b32 vcc_lo, s23, s0
	s_cselect_b32 s85, s49, s58
	s_cselect_b32 s84, s57, s51
	s_add_i32 s0, 0, 0x10000
	s_add_i32 s1, 0, 0x14000
	v_add_u32_e32 v158, s0, v176
	v_add_u32_e32 v174, s1, v176
	ds_read_b128 v[146:149], v158
	ds_read_b128 v[150:153], v158 offset:1024
	ds_read_b128 v[154:157], v158 offset:2048
	ds_read_b128 v[158:161], v158 offset:3072
	ds_read_b128 v[162:165], v174
	ds_read_b128 v[166:169], v174 offset:1024
	ds_read_b128 v[170:173], v174 offset:2048
	ds_read_b128 v[178:181], v174 offset:3072
	s_add_i32 m0, s21, 0xc000
	ds_read_b128 v[182:185], v177
	ds_read_b128 v[186:189], v177 offset:1024
	ds_read_b128 v[190:193], v177 offset:2048
	ds_read_b128 v[204:207], v177 offset:3072
	ds_read_b128 v[208:211], v177 offset:4096
	ds_read_b128 v[212:215], v177 offset:5120
	ds_read_b128 v[216:219], v177 offset:6144
	ds_read_b128 v[220:223], v177 offset:7168
	global_load_lds_dwordx4 v138, s[76:77]
	s_add_i32 m0, s21, 0xe000
	s_nop 0
	global_load_lds_dwordx4 v140, s[76:77]
	s_waitcnt vmcnt(8)
	s_waitcnt lgkmcnt(0)
	s_barrier
	s_waitcnt lgkmcnt(0)
	v_mfma_f32_16x16x32_bf16 v[126:129], v[146:149], v[182:185], v[126:129]
	v_mfma_f32_16x16x32_bf16 v[126:129], v[150:153], v[186:189], v[126:129]
	v_mfma_f32_16x16x32_bf16 v[122:125], v[158:161], v[186:189], v[122:125]
	v_mfma_f32_16x16x32_bf16 v[122:125], v[154:157], v[182:185], v[122:125]
	v_mfma_f32_16x16x32_bf16 v[118:121], v[162:165], v[182:185], v[118:121]
	v_mfma_f32_16x16x32_bf16 v[118:121], v[166:169], v[186:189], v[118:121]
	v_mfma_f32_16x16x32_bf16 v[114:117], v[178:181], v[186:189], v[114:117]
	v_mfma_f32_16x16x32_bf16 v[114:117], v[170:173], v[182:185], v[114:117]
	v_mfma_f32_16x16x32_bf16 v[98:101], v[170:173], v[190:193], v[98:101]
	v_mfma_f32_16x16x32_bf16 v[98:101], v[178:181], v[204:207], v[98:101]
	v_mfma_f32_16x16x32_bf16 v[102:105], v[166:169], v[204:207], v[102:105]
	v_mfma_f32_16x16x32_bf16 v[102:105], v[162:165], v[190:193], v[102:105]
	v_mfma_f32_16x16x32_bf16 v[106:109], v[154:157], v[190:193], v[106:109]
	v_mfma_f32_16x16x32_bf16 v[106:109], v[158:161], v[204:207], v[106:109]
	v_mfma_f32_16x16x32_bf16 v[110:113], v[150:153], v[204:207], v[110:113]
	v_mfma_f32_16x16x32_bf16 v[110:113], v[146:149], v[190:193], v[110:113]
	v_mfma_f32_16x16x32_bf16 v[94:97], v[146:149], v[208:211], v[94:97]
	v_mfma_f32_16x16x32_bf16 v[94:97], v[150:153], v[212:215], v[94:97]
	v_mfma_f32_16x16x32_bf16 v[90:93], v[158:161], v[212:215], v[90:93]
	v_mfma_f32_16x16x32_bf16 v[90:93], v[154:157], v[208:211], v[90:93]
	v_mfma_f32_16x16x32_bf16 v[86:89], v[162:165], v[208:211], v[86:89]
	v_mfma_f32_16x16x32_bf16 v[86:89], v[166:169], v[212:215], v[86:89]
	v_mfma_f32_16x16x32_bf16 v[82:85], v[178:181], v[212:215], v[82:85]
	v_mfma_f32_16x16x32_bf16 v[82:85], v[170:173], v[208:211], v[82:85]
	v_mfma_f32_16x16x32_bf16 v[66:69], v[170:173], v[216:219], v[66:69]
	v_mfma_f32_16x16x32_bf16 v[66:69], v[178:181], v[220:223], v[66:69]
	v_mfma_f32_16x16x32_bf16 v[70:73], v[166:169], v[220:223], v[70:73]
	v_mfma_f32_16x16x32_bf16 v[70:73], v[162:165], v[216:219], v[70:73]
	v_mfma_f32_16x16x32_bf16 v[74:77], v[154:157], v[216:219], v[74:77]
	v_mfma_f32_16x16x32_bf16 v[74:77], v[158:161], v[220:223], v[74:77]
	v_mfma_f32_16x16x32_bf16 v[78:81], v[150:153], v[220:223], v[78:81]
	v_mfma_f32_16x16x32_bf16 v[78:81], v[146:149], v[216:219], v[78:81]
	s_barrier
	s_add_i32 s0, s0, s20
	s_mov_b32 m0, s0
	ds_read_b128 v[182:185], v177 offset:16384
	ds_read_b128 v[186:189], v177 offset:17408
	ds_read_b128 v[190:193], v177 offset:18432
	ds_read_b128 v[204:207], v177 offset:19456
	ds_read_b128 v[208:211], v177 offset:20480
	ds_read_b128 v[212:215], v177 offset:21504
	ds_read_b128 v[216:219], v177 offset:22528
	ds_read_b128 v[220:223], v177 offset:23552
	global_load_lds_dwordx4 v132, s[84:85]
	s_add_i32 m0, s0, 0x2000
	s_add_u32 s94, s84, 0x80000
	s_addc_u32 s95, s85, 0
	s_add_i32 s0, s1, s20
	global_load_lds_dwordx4 v130, s[84:85]
	s_mov_b32 m0, s0
	s_nop 0
	global_load_lds_dwordx4 v132, s[94:95]
	s_add_i32 m0, s0, 0x2000
	s_nop 0
	global_load_lds_dwordx4 v130, s[94:95]
	s_mov_b32 m0, s21
	s_nop 0
	global_load_lds_dwordx4 v132, vcc
	s_mov_b32 m0, s26
	s_nop 0
	global_load_lds_dwordx4 v130, vcc
	s_waitcnt vmcnt(8)
	s_waitcnt lgkmcnt(0)
	s_barrier
	s_waitcnt lgkmcnt(0)
	v_mfma_f32_16x16x32_bf16 v[62:65], v[146:149], v[182:185], v[62:65]
	v_mfma_f32_16x16x32_bf16 v[62:65], v[150:153], v[186:189], v[62:65]
	v_mfma_f32_16x16x32_bf16 v[58:61], v[158:161], v[186:189], v[58:61]
	v_mfma_f32_16x16x32_bf16 v[58:61], v[154:157], v[182:185], v[58:61]
	v_mfma_f32_16x16x32_bf16 v[54:57], v[162:165], v[182:185], v[54:57]
	v_mfma_f32_16x16x32_bf16 v[54:57], v[166:169], v[186:189], v[54:57]
	v_mfma_f32_16x16x32_bf16 v[50:53], v[178:181], v[186:189], v[50:53]
	v_mfma_f32_16x16x32_bf16 v[50:53], v[170:173], v[182:185], v[50:53]
	v_mfma_f32_16x16x32_bf16 v[34:37], v[170:173], v[190:193], v[34:37]
	v_mfma_f32_16x16x32_bf16 v[34:37], v[178:181], v[204:207], v[34:37]
	v_mfma_f32_16x16x32_bf16 v[38:41], v[166:169], v[204:207], v[38:41]
	v_mfma_f32_16x16x32_bf16 v[38:41], v[162:165], v[190:193], v[38:41]
	v_mfma_f32_16x16x32_bf16 v[42:45], v[154:157], v[190:193], v[42:45]
	v_mfma_f32_16x16x32_bf16 v[42:45], v[158:161], v[204:207], v[42:45]
	v_mfma_f32_16x16x32_bf16 v[46:49], v[150:153], v[204:207], v[46:49]
	v_mfma_f32_16x16x32_bf16 v[46:49], v[146:149], v[190:193], v[46:49]
	v_mfma_f32_16x16x32_bf16 v[30:33], v[146:149], v[208:211], v[30:33]
	v_mfma_f32_16x16x32_bf16 v[30:33], v[150:153], v[212:215], v[30:33]
	v_mfma_f32_16x16x32_bf16 v[26:29], v[158:161], v[212:215], v[26:29]
	v_mfma_f32_16x16x32_bf16 v[26:29], v[154:157], v[208:211], v[26:29]
	v_mfma_f32_16x16x32_bf16 v[22:25], v[162:165], v[208:211], v[22:25]
	v_mfma_f32_16x16x32_bf16 v[22:25], v[166:169], v[212:215], v[22:25]
	v_mfma_f32_16x16x32_bf16 v[18:21], v[178:181], v[212:215], v[18:21]
	v_mfma_f32_16x16x32_bf16 v[18:21], v[170:173], v[208:211], v[18:21]
	v_mfma_f32_16x16x32_bf16 v[2:5], v[170:173], v[216:219], v[2:5]
	v_mfma_f32_16x16x32_bf16 v[2:5], v[178:181], v[220:223], v[2:5]
	v_mfma_f32_16x16x32_bf16 v[6:9], v[166:169], v[220:223], v[6:9]
	v_mfma_f32_16x16x32_bf16 v[6:9], v[162:165], v[216:219], v[6:9]
	v_mfma_f32_16x16x32_bf16 v[10:13], v[154:157], v[216:219], v[10:13]
	v_mfma_f32_16x16x32_bf16 v[10:13], v[158:161], v[220:223], v[10:13]
	v_mfma_f32_16x16x32_bf16 v[14:17], v[150:153], v[220:223], v[14:17]
	v_mfma_f32_16x16x32_bf16 v[14:17], v[146:149], v[216:219], v[14:17]
	s_barrier
	s_add_i32 s0, 0, 0x18000
	s_add_i32 s1, 0, 0x1c000
	v_add_u32_e32 v158, s0, v176
	v_add_u32_e32 v178, s1, v176
	ds_read_b128 v[146:149], v158
	ds_read_b128 v[150:153], v158 offset:1024
	ds_read_b128 v[154:157], v158 offset:2048
	ds_read_b128 v[158:161], v158 offset:3072
	ds_read_b128 v[162:165], v178
	ds_read_b128 v[166:169], v178 offset:1024
	ds_read_b128 v[170:173], v178 offset:2048
	ds_read_b128 v[178:181], v178 offset:3072
	s_add_u32 s94, vcc_lo, 0x80000
	s_addc_u32 s95, vcc_hi, 0
	s_mov_b32 m0, s27
	ds_read_b128 v[182:185], v177 offset:32768
	ds_read_b128 v[186:189], v177 offset:33792
	ds_read_b128 v[190:193], v177 offset:34816
	ds_read_b128 v[204:207], v177 offset:35840
	ds_read_b128 v[208:211], v177 offset:36864
	ds_read_b128 v[212:215], v177 offset:37888
	ds_read_b128 v[216:219], v177 offset:38912
	ds_read_b128 v[220:223], v177 offset:39936
	global_load_lds_dwordx4 v132, s[94:95]
	s_mov_b32 m0, s29
	s_nop 0
	global_load_lds_dwordx4 v130, s[94:95]
	s_waitcnt vmcnt(8)
	s_waitcnt lgkmcnt(0)
	s_barrier
	s_waitcnt lgkmcnt(0)
	v_mfma_f32_16x16x32_bf16 v[126:129], v[146:149], v[182:185], v[126:129]
	v_mfma_f32_16x16x32_bf16 v[126:129], v[150:153], v[186:189], v[126:129]
	v_mfma_f32_16x16x32_bf16 v[122:125], v[158:161], v[186:189], v[122:125]
	v_mfma_f32_16x16x32_bf16 v[122:125], v[154:157], v[182:185], v[122:125]
	v_mfma_f32_16x16x32_bf16 v[118:121], v[162:165], v[182:185], v[118:121]
	v_mfma_f32_16x16x32_bf16 v[118:121], v[166:169], v[186:189], v[118:121]
	v_mfma_f32_16x16x32_bf16 v[114:117], v[178:181], v[186:189], v[114:117]
	v_mfma_f32_16x16x32_bf16 v[114:117], v[170:173], v[182:185], v[114:117]
	v_mfma_f32_16x16x32_bf16 v[98:101], v[170:173], v[190:193], v[98:101]
	v_mfma_f32_16x16x32_bf16 v[98:101], v[178:181], v[204:207], v[98:101]
	v_mfma_f32_16x16x32_bf16 v[102:105], v[166:169], v[204:207], v[102:105]
	v_mfma_f32_16x16x32_bf16 v[102:105], v[162:165], v[190:193], v[102:105]
	v_mfma_f32_16x16x32_bf16 v[106:109], v[154:157], v[190:193], v[106:109]
	v_mfma_f32_16x16x32_bf16 v[106:109], v[158:161], v[204:207], v[106:109]
	v_mfma_f32_16x16x32_bf16 v[110:113], v[150:153], v[204:207], v[110:113]
	v_mfma_f32_16x16x32_bf16 v[110:113], v[146:149], v[190:193], v[110:113]
	v_mfma_f32_16x16x32_bf16 v[94:97], v[146:149], v[208:211], v[94:97]
	v_mfma_f32_16x16x32_bf16 v[94:97], v[150:153], v[212:215], v[94:97]
	v_mfma_f32_16x16x32_bf16 v[90:93], v[158:161], v[212:215], v[90:93]
	v_mfma_f32_16x16x32_bf16 v[90:93], v[154:157], v[208:211], v[90:93]
	v_mfma_f32_16x16x32_bf16 v[86:89], v[162:165], v[208:211], v[86:89]
	v_mfma_f32_16x16x32_bf16 v[86:89], v[166:169], v[212:215], v[86:89]
	v_mfma_f32_16x16x32_bf16 v[82:85], v[178:181], v[212:215], v[82:85]
	v_mfma_f32_16x16x32_bf16 v[82:85], v[170:173], v[208:211], v[82:85]
	v_mfma_f32_16x16x32_bf16 v[66:69], v[170:173], v[216:219], v[66:69]
	v_mfma_f32_16x16x32_bf16 v[66:69], v[178:181], v[220:223], v[66:69]
	v_mfma_f32_16x16x32_bf16 v[70:73], v[166:169], v[220:223], v[70:73]
	v_mfma_f32_16x16x32_bf16 v[70:73], v[162:165], v[216:219], v[70:73]
	v_mfma_f32_16x16x32_bf16 v[74:77], v[154:157], v[216:219], v[74:77]
	v_mfma_f32_16x16x32_bf16 v[74:77], v[158:161], v[220:223], v[74:77]
	v_mfma_f32_16x16x32_bf16 v[78:81], v[150:153], v[220:223], v[78:81]
	v_mfma_f32_16x16x32_bf16 v[78:81], v[146:149], v[216:219], v[78:81]
	s_barrier
	s_add_u32 s98, s84, 0x80
	s_addc_u32 s99, s85, 0
	s_add_u32 s100, vcc_lo, 0x80
	s_addc_u32 s101, vcc_hi, 0
	s_add_i32 s0, s0, s20
	s_mov_b32 m0, s0
	ds_read_b128 v[182:185], v177 offset:49152
	ds_read_b128 v[186:189], v177 offset:50176
	ds_read_b128 v[190:193], v177 offset:51200
	ds_read_b128 v[204:207], v177 offset:52224
	ds_read_b128 v[208:211], v177 offset:53248
	ds_read_b128 v[212:215], v177 offset:54272
	ds_read_b128 v[216:219], v177 offset:55296
	ds_read_b128 v[220:223], v177 offset:56320
	global_load_lds_dwordx4 v132, s[98:99]
	s_add_i32 m0, s0, 0x2000
	s_add_u32 s84, s84, 0x80080
	s_addc_u32 s85, s85, 0
	s_add_i32 s0, s1, s20
	global_load_lds_dwordx4 v130, s[98:99]
	s_mov_b32 m0, s0
	s_nop 0
	global_load_lds_dwordx4 v132, s[84:85]
	s_add_i32 m0, s0, 0x2000
	s_nop 0
	global_load_lds_dwordx4 v130, s[84:85]
	s_mov_b32 m0, s40
	s_nop 0
	global_load_lds_dwordx4 v132, s[100:101]
	s_mov_b32 m0, s41
	s_nop 0
	global_load_lds_dwordx4 v130, s[100:101]
	s_waitcnt vmcnt(8)
	s_waitcnt lgkmcnt(0)
	s_barrier
	s_waitcnt lgkmcnt(0)
	v_mfma_f32_16x16x32_bf16 v[62:65], v[146:149], v[182:185], v[62:65]
	v_mfma_f32_16x16x32_bf16 v[62:65], v[150:153], v[186:189], v[62:65]
	v_mfma_f32_16x16x32_bf16 v[58:61], v[158:161], v[186:189], v[58:61]
	v_mfma_f32_16x16x32_bf16 v[58:61], v[154:157], v[182:185], v[58:61]
	v_mfma_f32_16x16x32_bf16 v[54:57], v[162:165], v[182:185], v[54:57]
	v_mfma_f32_16x16x32_bf16 v[54:57], v[166:169], v[186:189], v[54:57]
	v_mfma_f32_16x16x32_bf16 v[50:53], v[178:181], v[186:189], v[50:53]
	v_mfma_f32_16x16x32_bf16 v[50:53], v[170:173], v[182:185], v[50:53]
	v_mfma_f32_16x16x32_bf16 v[34:37], v[170:173], v[190:193], v[34:37]
	v_mfma_f32_16x16x32_bf16 v[34:37], v[178:181], v[204:207], v[34:37]
	v_mfma_f32_16x16x32_bf16 v[38:41], v[166:169], v[204:207], v[38:41]
	v_mfma_f32_16x16x32_bf16 v[38:41], v[162:165], v[190:193], v[38:41]
	v_mfma_f32_16x16x32_bf16 v[42:45], v[154:157], v[190:193], v[42:45]
	v_mfma_f32_16x16x32_bf16 v[42:45], v[158:161], v[204:207], v[42:45]
	v_mfma_f32_16x16x32_bf16 v[46:49], v[150:153], v[204:207], v[46:49]
	v_mfma_f32_16x16x32_bf16 v[46:49], v[146:149], v[190:193], v[46:49]
	v_mfma_f32_16x16x32_bf16 v[30:33], v[146:149], v[208:211], v[30:33]
	v_mfma_f32_16x16x32_bf16 v[30:33], v[150:153], v[212:215], v[30:33]
	v_mfma_f32_16x16x32_bf16 v[26:29], v[158:161], v[212:215], v[26:29]
	v_mfma_f32_16x16x32_bf16 v[26:29], v[154:157], v[208:211], v[26:29]
	v_mfma_f32_16x16x32_bf16 v[22:25], v[162:165], v[208:211], v[22:25]
	v_mfma_f32_16x16x32_bf16 v[22:25], v[166:169], v[212:215], v[22:25]
	v_mfma_f32_16x16x32_bf16 v[18:21], v[178:181], v[212:215], v[18:21]
	v_mfma_f32_16x16x32_bf16 v[18:21], v[170:173], v[208:211], v[18:21]
	v_mfma_f32_16x16x32_bf16 v[2:5], v[170:173], v[216:219], v[2:5]
	v_mfma_f32_16x16x32_bf16 v[2:5], v[178:181], v[220:223], v[2:5]
	v_mfma_f32_16x16x32_bf16 v[6:9], v[166:169], v[220:223], v[6:9]
	v_mfma_f32_16x16x32_bf16 v[6:9], v[162:165], v[216:219], v[6:9]
	v_mfma_f32_16x16x32_bf16 v[10:13], v[154:157], v[216:219], v[10:13]
	v_mfma_f32_16x16x32_bf16 v[10:13], v[158:161], v[220:223], v[10:13]
	v_mfma_f32_16x16x32_bf16 v[14:17], v[150:153], v[220:223], v[14:17]
	v_mfma_f32_16x16x32_bf16 v[14:17], v[146:149], v[216:219], v[14:17]
	s_barrier
	s_add_i32 s65, s65, 2
	s_add_u32 s76, s76, 0x100
	s_addc_u32 s77, s77, 0
	s_add_u32 s51, s51, 0x100
	s_addc_u32 s58, s58, 0
	s_cmp_gt_u32 s65, 29
	s_cbranch_scc1 .LBB0_264

.Lpeel_disp_ine:
	s_cmp_lg_u32 s65, -2
	s_cbranch_scc1 .LBB0_261
	s_add_u32 s0, s76, 0xfff80080
	s_addc_u32 s1, s77, -1
	s_and_b64 s[84:85], s[84:85], exec
	s_cselect_b32 vcc_hi, s22, s1
	s_cselect_b32 vcc_lo, s23, s0
	s_cselect_b32 s85, s49, s58
	s_cselect_b32 s84, s57, s51
	s_add_i32 s0, 0, 0x10000
	s_add_i32 s1, 0, 0x14000
	v_add_u32_e32 v158, s0, v176
	v_add_u32_e32 v174, s1, v176
	ds_read_b128 v[146:149], v158
	ds_read_b128 v[150:153], v158 offset:1024
	ds_read_b128 v[154:157], v158 offset:2048
	ds_read_b128 v[158:161], v158 offset:3072
	ds_read_b128 v[162:165], v174
	ds_read_b128 v[166:169], v174 offset:1024
	ds_read_b128 v[170:173], v174 offset:2048
	ds_read_b128 v[178:181], v174 offset:3072
	s_add_i32 m0, s21, 0xc000
	ds_read_b128 v[182:185], v177
	ds_read_b128 v[186:189], v177 offset:1024
	ds_read_b128 v[190:193], v177 offset:2048
	ds_read_b128 v[204:207], v177 offset:3072
	ds_read_b128 v[208:211], v177 offset:4096
	ds_read_b128 v[212:215], v177 offset:5120
	ds_read_b128 v[216:219], v177 offset:6144
	ds_read_b128 v[220:223], v177 offset:7168
	global_load_lds_dwordx4 v138, s[76:77]
	s_add_i32 m0, s21, 0xe000
	s_nop 0
	global_load_lds_dwordx4 v140, s[76:77]
	s_waitcnt vmcnt(8)
	s_waitcnt lgkmcnt(0)
	s_barrier
	s_waitcnt lgkmcnt(0)
	v_mfma_f32_16x16x32_bf16 v[126:129], v[146:149], v[182:185], 0
	v_mfma_f32_16x16x32_bf16 v[126:129], v[150:153], v[186:189], v[126:129]
	v_mfma_f32_16x16x32_bf16 v[122:125], v[158:161], v[186:189], 0
	v_mfma_f32_16x16x32_bf16 v[122:125], v[154:157], v[182:185], v[122:125]
	v_mfma_f32_16x16x32_bf16 v[118:121], v[162:165], v[182:185], 0
	v_mfma_f32_16x16x32_bf16 v[118:121], v[166:169], v[186:189], v[118:121]
	v_mfma_f32_16x16x32_bf16 v[114:117], v[178:181], v[186:189], 0
	v_mfma_f32_16x16x32_bf16 v[114:117], v[170:173], v[182:185], v[114:117]
	v_mfma_f32_16x16x32_bf16 v[98:101], v[170:173], v[190:193], 0
	v_mfma_f32_16x16x32_bf16 v[98:101], v[178:181], v[204:207], v[98:101]
	v_mfma_f32_16x16x32_bf16 v[102:105], v[166:169], v[204:207], 0
	v_mfma_f32_16x16x32_bf16 v[102:105], v[162:165], v[190:193], v[102:105]
	v_mfma_f32_16x16x32_bf16 v[106:109], v[154:157], v[190:193], 0
	v_mfma_f32_16x16x32_bf16 v[106:109], v[158:161], v[204:207], v[106:109]
	v_mfma_f32_16x16x32_bf16 v[110:113], v[150:153], v[204:207], 0
	v_mfma_f32_16x16x32_bf16 v[110:113], v[146:149], v[190:193], v[110:113]
	v_mfma_f32_16x16x32_bf16 v[94:97], v[146:149], v[208:211], 0
	v_mfma_f32_16x16x32_bf16 v[94:97], v[150:153], v[212:215], v[94:97]
	v_mfma_f32_16x16x32_bf16 v[90:93], v[158:161], v[212:215], 0
	v_mfma_f32_16x16x32_bf16 v[90:93], v[154:157], v[208:211], v[90:93]
	v_mfma_f32_16x16x32_bf16 v[86:89], v[162:165], v[208:211], 0
	v_mfma_f32_16x16x32_bf16 v[86:89], v[166:169], v[212:215], v[86:89]
	v_mfma_f32_16x16x32_bf16 v[82:85], v[178:181], v[212:215], 0
	v_mfma_f32_16x16x32_bf16 v[82:85], v[170:173], v[208:211], v[82:85]
	v_mfma_f32_16x16x32_bf16 v[66:69], v[170:173], v[216:219], 0
	v_mfma_f32_16x16x32_bf16 v[66:69], v[178:181], v[220:223], v[66:69]
	v_mfma_f32_16x16x32_bf16 v[70:73], v[166:169], v[220:223], 0
	v_mfma_f32_16x16x32_bf16 v[70:73], v[162:165], v[216:219], v[70:73]
	v_mfma_f32_16x16x32_bf16 v[74:77], v[154:157], v[216:219], 0
	v_mfma_f32_16x16x32_bf16 v[74:77], v[158:161], v[220:223], v[74:77]
	v_mfma_f32_16x16x32_bf16 v[78:81], v[150:153], v[220:223], 0
	v_mfma_f32_16x16x32_bf16 v[78:81], v[146:149], v[216:219], v[78:81]
	s_barrier
	s_add_i32 s0, s0, s20
	s_mov_b32 m0, s0
	ds_read_b128 v[182:185], v177 offset:16384
	ds_read_b128 v[186:189], v177 offset:17408
	ds_read_b128 v[190:193], v177 offset:18432
	ds_read_b128 v[204:207], v177 offset:19456
	ds_read_b128 v[208:211], v177 offset:20480
	ds_read_b128 v[212:215], v177 offset:21504
	ds_read_b128 v[216:219], v177 offset:22528
	ds_read_b128 v[220:223], v177 offset:23552
	global_load_lds_dwordx4 v132, s[84:85]
	s_add_i32 m0, s0, 0x2000
	s_add_u32 s94, s84, 0x80000
	s_addc_u32 s95, s85, 0
	s_add_i32 s0, s1, s20
	global_load_lds_dwordx4 v130, s[84:85]
	s_mov_b32 m0, s0
	s_nop 0
	global_load_lds_dwordx4 v132, s[94:95]
	s_add_i32 m0, s0, 0x2000
	s_nop 0
	global_load_lds_dwordx4 v130, s[94:95]
	s_mov_b32 m0, s21
	s_nop 0
	global_load_lds_dwordx4 v132, vcc
	s_mov_b32 m0, s26
	s_nop 0
	global_load_lds_dwordx4 v130, vcc
	s_waitcnt vmcnt(8)
	s_waitcnt lgkmcnt(0)
	s_barrier
	s_waitcnt lgkmcnt(0)
	v_mfma_f32_16x16x32_bf16 v[62:65], v[146:149], v[182:185], 0
	v_mfma_f32_16x16x32_bf16 v[62:65], v[150:153], v[186:189], v[62:65]
	v_mfma_f32_16x16x32_bf16 v[58:61], v[158:161], v[186:189], 0
	v_mfma_f32_16x16x32_bf16 v[58:61], v[154:157], v[182:185], v[58:61]
	v_mfma_f32_16x16x32_bf16 v[54:57], v[162:165], v[182:185], 0
	v_mfma_f32_16x16x32_bf16 v[54:57], v[166:169], v[186:189], v[54:57]
	v_mfma_f32_16x16x32_bf16 v[50:53], v[178:181], v[186:189], 0
	v_mfma_f32_16x16x32_bf16 v[50:53], v[170:173], v[182:185], v[50:53]
	v_mfma_f32_16x16x32_bf16 v[34:37], v[170:173], v[190:193], 0
	v_mfma_f32_16x16x32_bf16 v[34:37], v[178:181], v[204:207], v[34:37]
	v_mfma_f32_16x16x32_bf16 v[38:41], v[166:169], v[204:207], 0
	v_mfma_f32_16x16x32_bf16 v[38:41], v[162:165], v[190:193], v[38:41]
	v_mfma_f32_16x16x32_bf16 v[42:45], v[154:157], v[190:193], 0
	v_mfma_f32_16x16x32_bf16 v[42:45], v[158:161], v[204:207], v[42:45]
	v_mfma_f32_16x16x32_bf16 v[46:49], v[150:153], v[204:207], 0
	v_mfma_f32_16x16x32_bf16 v[46:49], v[146:149], v[190:193], v[46:49]
	v_mfma_f32_16x16x32_bf16 v[30:33], v[146:149], v[208:211], 0
	v_mfma_f32_16x16x32_bf16 v[30:33], v[150:153], v[212:215], v[30:33]
	v_mfma_f32_16x16x32_bf16 v[26:29], v[158:161], v[212:215], 0
	v_mfma_f32_16x16x32_bf16 v[26:29], v[154:157], v[208:211], v[26:29]
	v_mfma_f32_16x16x32_bf16 v[22:25], v[162:165], v[208:211], 0
	v_mfma_f32_16x16x32_bf16 v[22:25], v[166:169], v[212:215], v[22:25]
	v_mfma_f32_16x16x32_bf16 v[18:21], v[178:181], v[212:215], 0
	v_mfma_f32_16x16x32_bf16 v[18:21], v[170:173], v[208:211], v[18:21]
	v_mfma_f32_16x16x32_bf16 v[2:5], v[170:173], v[216:219], 0
	v_mfma_f32_16x16x32_bf16 v[2:5], v[178:181], v[220:223], v[2:5]
	v_mfma_f32_16x16x32_bf16 v[6:9], v[166:169], v[220:223], 0
	v_mfma_f32_16x16x32_bf16 v[6:9], v[162:165], v[216:219], v[6:9]
	v_mfma_f32_16x16x32_bf16 v[10:13], v[154:157], v[216:219], 0
	v_mfma_f32_16x16x32_bf16 v[10:13], v[158:161], v[220:223], v[10:13]
	v_mfma_f32_16x16x32_bf16 v[14:17], v[150:153], v[220:223], 0
	v_mfma_f32_16x16x32_bf16 v[14:17], v[146:149], v[216:219], v[14:17]
	s_barrier
	s_add_i32 s0, 0, 0x18000
	s_add_i32 s1, 0, 0x1c000
	v_add_u32_e32 v158, s0, v176
	v_add_u32_e32 v178, s1, v176
	ds_read_b128 v[146:149], v158
	ds_read_b128 v[150:153], v158 offset:1024
	ds_read_b128 v[154:157], v158 offset:2048
	ds_read_b128 v[158:161], v158 offset:3072
	ds_read_b128 v[162:165], v178
	ds_read_b128 v[166:169], v178 offset:1024
	ds_read_b128 v[170:173], v178 offset:2048
	ds_read_b128 v[178:181], v178 offset:3072
	s_add_u32 s94, vcc_lo, 0x80000
	s_addc_u32 s95, vcc_hi, 0
	s_mov_b32 m0, s27
	ds_read_b128 v[182:185], v177 offset:32768
	ds_read_b128 v[186:189], v177 offset:33792
	ds_read_b128 v[190:193], v177 offset:34816
	ds_read_b128 v[204:207], v177 offset:35840
	ds_read_b128 v[208:211], v177 offset:36864
	ds_read_b128 v[212:215], v177 offset:37888
	ds_read_b128 v[216:219], v177 offset:38912
	ds_read_b128 v[220:223], v177 offset:39936
	global_load_lds_dwordx4 v132, s[94:95]
	s_mov_b32 m0, s29
	s_nop 0
	global_load_lds_dwordx4 v130, s[94:95]
	s_waitcnt vmcnt(8)
	s_waitcnt lgkmcnt(0)
	s_barrier
	s_waitcnt lgkmcnt(0)
	v_mfma_f32_16x16x32_bf16 v[126:129], v[146:149], v[182:185], v[126:129]
	v_mfma_f32_16x16x32_bf16 v[126:129], v[150:153], v[186:189], v[126:129]
	v_mfma_f32_16x16x32_bf16 v[122:125], v[158:161], v[186:189], v[122:125]
	v_mfma_f32_16x16x32_bf16 v[122:125], v[154:157], v[182:185], v[122:125]
	v_mfma_f32_16x16x32_bf16 v[118:121], v[162:165], v[182:185], v[118:121]
	v_mfma_f32_16x16x32_bf16 v[118:121], v[166:169], v[186:189], v[118:121]
	v_mfma_f32_16x16x32_bf16 v[114:117], v[178:181], v[186:189], v[114:117]
	v_mfma_f32_16x16x32_bf16 v[114:117], v[170:173], v[182:185], v[114:117]
	v_mfma_f32_16x16x32_bf16 v[98:101], v[170:173], v[190:193], v[98:101]
	v_mfma_f32_16x16x32_bf16 v[98:101], v[178:181], v[204:207], v[98:101]
	v_mfma_f32_16x16x32_bf16 v[102:105], v[166:169], v[204:207], v[102:105]
	v_mfma_f32_16x16x32_bf16 v[102:105], v[162:165], v[190:193], v[102:105]
	v_mfma_f32_16x16x32_bf16 v[106:109], v[154:157], v[190:193], v[106:109]
	v_mfma_f32_16x16x32_bf16 v[106:109], v[158:161], v[204:207], v[106:109]
	v_mfma_f32_16x16x32_bf16 v[110:113], v[150:153], v[204:207], v[110:113]
	v_mfma_f32_16x16x32_bf16 v[110:113], v[146:149], v[190:193], v[110:113]
	v_mfma_f32_16x16x32_bf16 v[94:97], v[146:149], v[208:211], v[94:97]
	v_mfma_f32_16x16x32_bf16 v[94:97], v[150:153], v[212:215], v[94:97]
	v_mfma_f32_16x16x32_bf16 v[90:93], v[158:161], v[212:215], v[90:93]
	v_mfma_f32_16x16x32_bf16 v[90:93], v[154:157], v[208:211], v[90:93]
	v_mfma_f32_16x16x32_bf16 v[86:89], v[162:165], v[208:211], v[86:89]
	v_mfma_f32_16x16x32_bf16 v[86:89], v[166:169], v[212:215], v[86:89]
	v_mfma_f32_16x16x32_bf16 v[82:85], v[178:181], v[212:215], v[82:85]
	v_mfma_f32_16x16x32_bf16 v[82:85], v[170:173], v[208:211], v[82:85]
	v_mfma_f32_16x16x32_bf16 v[66:69], v[170:173], v[216:219], v[66:69]
	v_mfma_f32_16x16x32_bf16 v[66:69], v[178:181], v[220:223], v[66:69]
	v_mfma_f32_16x16x32_bf16 v[70:73], v[166:169], v[220:223], v[70:73]
	v_mfma_f32_16x16x32_bf16 v[70:73], v[162:165], v[216:219], v[70:73]
	v_mfma_f32_16x16x32_bf16 v[74:77], v[154:157], v[216:219], v[74:77]
	v_mfma_f32_16x16x32_bf16 v[74:77], v[158:161], v[220:223], v[74:77]
	v_mfma_f32_16x16x32_bf16 v[78:81], v[150:153], v[220:223], v[78:81]
	v_mfma_f32_16x16x32_bf16 v[78:81], v[146:149], v[216:219], v[78:81]
	s_barrier
	s_add_u32 s98, s84, 0x80
	s_addc_u32 s99, s85, 0
	s_add_u32 s100, vcc_lo, 0x80
	s_addc_u32 s101, vcc_hi, 0
	s_add_i32 s0, s0, s20
	s_mov_b32 m0, s0
	ds_read_b128 v[182:185], v177 offset:49152
	ds_read_b128 v[186:189], v177 offset:50176
	ds_read_b128 v[190:193], v177 offset:51200
	ds_read_b128 v[204:207], v177 offset:52224
	ds_read_b128 v[208:211], v177 offset:53248
	ds_read_b128 v[212:215], v177 offset:54272
	ds_read_b128 v[216:219], v177 offset:55296
	ds_read_b128 v[220:223], v177 offset:56320
	global_load_lds_dwordx4 v132, s[98:99]
	s_add_i32 m0, s0, 0x2000
	s_add_u32 s84, s84, 0x80080
	s_addc_u32 s85, s85, 0
	s_add_i32 s0, s1, s20
	global_load_lds_dwordx4 v130, s[98:99]
	s_mov_b32 m0, s0
	s_nop 0
	global_load_lds_dwordx4 v132, s[84:85]
	s_add_i32 m0, s0, 0x2000
	s_nop 0
	global_load_lds_dwordx4 v130, s[84:85]
	s_mov_b32 m0, s40
	s_nop 0
	global_load_lds_dwordx4 v132, s[100:101]
	s_mov_b32 m0, s41
	s_nop 0
	global_load_lds_dwordx4 v130, s[100:101]
	s_waitcnt vmcnt(8)
	s_waitcnt lgkmcnt(0)
	s_barrier
	s_waitcnt lgkmcnt(0)
	v_mfma_f32_16x16x32_bf16 v[62:65], v[146:149], v[182:185], v[62:65]
	v_mfma_f32_16x16x32_bf16 v[62:65], v[150:153], v[186:189], v[62:65]
	v_mfma_f32_16x16x32_bf16 v[58:61], v[158:161], v[186:189], v[58:61]
	v_mfma_f32_16x16x32_bf16 v[58:61], v[154:157], v[182:185], v[58:61]
	v_mfma_f32_16x16x32_bf16 v[54:57], v[162:165], v[182:185], v[54:57]
	v_mfma_f32_16x16x32_bf16 v[54:57], v[166:169], v[186:189], v[54:57]
	v_mfma_f32_16x16x32_bf16 v[50:53], v[178:181], v[186:189], v[50:53]
	v_mfma_f32_16x16x32_bf16 v[50:53], v[170:173], v[182:185], v[50:53]
	v_mfma_f32_16x16x32_bf16 v[34:37], v[170:173], v[190:193], v[34:37]
	v_mfma_f32_16x16x32_bf16 v[34:37], v[178:181], v[204:207], v[34:37]
	v_mfma_f32_16x16x32_bf16 v[38:41], v[166:169], v[204:207], v[38:41]
	v_mfma_f32_16x16x32_bf16 v[38:41], v[162:165], v[190:193], v[38:41]
	v_mfma_f32_16x16x32_bf16 v[42:45], v[154:157], v[190:193], v[42:45]
	v_mfma_f32_16x16x32_bf16 v[42:45], v[158:161], v[204:207], v[42:45]
	v_mfma_f32_16x16x32_bf16 v[46:49], v[150:153], v[204:207], v[46:49]
	v_mfma_f32_16x16x32_bf16 v[46:49], v[146:149], v[190:193], v[46:49]
	v_mfma_f32_16x16x32_bf16 v[30:33], v[146:149], v[208:211], v[30:33]
	v_mfma_f32_16x16x32_bf16 v[30:33], v[150:153], v[212:215], v[30:33]
	v_mfma_f32_16x16x32_bf16 v[26:29], v[158:161], v[212:215], v[26:29]
	v_mfma_f32_16x16x32_bf16 v[26:29], v[154:157], v[208:211], v[26:29]
	v_mfma_f32_16x16x32_bf16 v[22:25], v[162:165], v[208:211], v[22:25]
	v_mfma_f32_16x16x32_bf16 v[22:25], v[166:169], v[212:215], v[22:25]
	v_mfma_f32_16x16x32_bf16 v[18:21], v[178:181], v[212:215], v[18:21]
	v_mfma_f32_16x16x32_bf16 v[18:21], v[170:173], v[208:211], v[18:21]
	v_mfma_f32_16x16x32_bf16 v[2:5], v[170:173], v[216:219], v[2:5]
	v_mfma_f32_16x16x32_bf16 v[2:5], v[178:181], v[220:223], v[2:5]
	v_mfma_f32_16x16x32_bf16 v[6:9], v[166:169], v[220:223], v[6:9]
	v_mfma_f32_16x16x32_bf16 v[6:9], v[162:165], v[216:219], v[6:9]
	v_mfma_f32_16x16x32_bf16 v[10:13], v[154:157], v[216:219], v[10:13]
	v_mfma_f32_16x16x32_bf16 v[10:13], v[158:161], v[220:223], v[10:13]
	v_mfma_f32_16x16x32_bf16 v[14:17], v[150:153], v[220:223], v[14:17]
	v_mfma_f32_16x16x32_bf16 v[14:17], v[146:149], v[216:219], v[14:17]
	s_barrier
	s_add_i32 s65, s65, 2
	s_add_u32 s76, s76, 0x100
	s_addc_u32 s77, s77, 0
	s_add_u32 s51, s51, 0x100
	s_addc_u32 s58, s58, 0
	s_cmp_gt_u32 s65, 29
	s_cbranch_scc1 .LBB0_264
	s_branch .LBB0_262

.LBB0_285:
	s_add_u32 s0, s76, 0xfff80080
	s_addc_u32 s1, s77, -1
	s_and_b64 s[70:71], s[70:71], exec
	s_cselect_b32 vcc_hi, s21, s1
	s_cselect_b32 vcc_lo, s22, s0
	s_cselect_b32 s71, s23, s41
	s_cselect_b32 s70, s39, s7
	s_add_i32 s0, 0, 0x10000
	s_add_i32 s1, 0, 0x14000
	v_add_u32_e32 v146, s0, v1
	v_add_u32_e32 v174, s1, v1
	ds_read_b128 v[134:137], v146
	ds_read_b128 v[138:141], v146 offset:1024
	ds_read_b128 v[142:145], v146 offset:2048
	ds_read_b128 v[146:149], v146 offset:3072
	ds_read_b128 v[150:153], v174
	ds_read_b128 v[154:157], v174 offset:1024
	ds_read_b128 v[158:161], v174 offset:2048
	ds_read_b128 v[174:177], v174 offset:3072
	s_add_i32 m0, s67, 0xc000
	ds_read_b128 v[178:181], v222
	ds_read_b128 v[182:185], v222 offset:1024
	ds_read_b128 v[186:189], v222 offset:2048
	ds_read_b128 v[190:193], v222 offset:3072
	ds_read_b128 v[204:207], v222 offset:4096
	ds_read_b128 v[208:211], v222 offset:5120
	ds_read_b128 v[212:215], v222 offset:6144
	ds_read_b128 v[216:219], v222 offset:7168
	global_load_lds_dwordx4 v170, s[76:77]
	s_add_i32 m0, s67, 0xe000
	s_nop 0
	global_load_lds_dwordx4 v172, s[76:77]
	s_waitcnt vmcnt(8)
	s_waitcnt lgkmcnt(0)
	s_barrier
	s_waitcnt lgkmcnt(0)
	v_mfma_f32_16x16x32_bf16 v[126:129], v[134:137], v[178:181], v[126:129]
	v_mfma_f32_16x16x32_bf16 v[126:129], v[138:141], v[182:185], v[126:129]
	v_mfma_f32_16x16x32_bf16 v[122:125], v[146:149], v[182:185], v[122:125]
	v_mfma_f32_16x16x32_bf16 v[122:125], v[142:145], v[178:181], v[122:125]
	v_mfma_f32_16x16x32_bf16 v[118:121], v[150:153], v[178:181], v[118:121]
	v_mfma_f32_16x16x32_bf16 v[118:121], v[154:157], v[182:185], v[118:121]
	v_mfma_f32_16x16x32_bf16 v[114:117], v[174:177], v[182:185], v[114:117]
	v_mfma_f32_16x16x32_bf16 v[114:117], v[158:161], v[178:181], v[114:117]
	v_mfma_f32_16x16x32_bf16 v[98:101], v[158:161], v[186:189], v[98:101]
	v_mfma_f32_16x16x32_bf16 v[98:101], v[174:177], v[190:193], v[98:101]
	v_mfma_f32_16x16x32_bf16 v[102:105], v[154:157], v[190:193], v[102:105]
	v_mfma_f32_16x16x32_bf16 v[102:105], v[150:153], v[186:189], v[102:105]
	v_mfma_f32_16x16x32_bf16 v[106:109], v[142:145], v[186:189], v[106:109]
	v_mfma_f32_16x16x32_bf16 v[106:109], v[146:149], v[190:193], v[106:109]
	v_mfma_f32_16x16x32_bf16 v[110:113], v[138:141], v[190:193], v[110:113]
	v_mfma_f32_16x16x32_bf16 v[110:113], v[134:137], v[186:189], v[110:113]
	v_mfma_f32_16x16x32_bf16 v[94:97], v[134:137], v[204:207], v[94:97]
	v_mfma_f32_16x16x32_bf16 v[94:97], v[138:141], v[208:211], v[94:97]
	v_mfma_f32_16x16x32_bf16 v[90:93], v[146:149], v[208:211], v[90:93]
	v_mfma_f32_16x16x32_bf16 v[90:93], v[142:145], v[204:207], v[90:93]
	v_mfma_f32_16x16x32_bf16 v[86:89], v[150:153], v[204:207], v[86:89]
	v_mfma_f32_16x16x32_bf16 v[86:89], v[154:157], v[208:211], v[86:89]
	v_mfma_f32_16x16x32_bf16 v[82:85], v[174:177], v[208:211], v[82:85]
	v_mfma_f32_16x16x32_bf16 v[82:85], v[158:161], v[204:207], v[82:85]
	v_mfma_f32_16x16x32_bf16 v[66:69], v[158:161], v[212:215], v[66:69]
	v_mfma_f32_16x16x32_bf16 v[66:69], v[174:177], v[216:219], v[66:69]
	v_mfma_f32_16x16x32_bf16 v[70:73], v[154:157], v[216:219], v[70:73]
	v_mfma_f32_16x16x32_bf16 v[70:73], v[150:153], v[212:215], v[70:73]
	v_mfma_f32_16x16x32_bf16 v[74:77], v[142:145], v[212:215], v[74:77]
	v_mfma_f32_16x16x32_bf16 v[74:77], v[146:149], v[216:219], v[74:77]
	v_mfma_f32_16x16x32_bf16 v[78:81], v[138:141], v[216:219], v[78:81]
	v_mfma_f32_16x16x32_bf16 v[78:81], v[134:137], v[212:215], v[78:81]
	s_barrier
	s_add_i32 s0, s0, s54
	s_mov_b32 m0, s0
	ds_read_b128 v[178:181], v222 offset:16384
	ds_read_b128 v[182:185], v222 offset:17408
	ds_read_b128 v[186:189], v222 offset:18432
	ds_read_b128 v[190:193], v222 offset:19456
	ds_read_b128 v[204:207], v222 offset:20480
	ds_read_b128 v[208:211], v222 offset:21504
	ds_read_b128 v[212:215], v222 offset:22528
	ds_read_b128 v[216:219], v222 offset:23552
	global_load_lds_dwordx4 v164, s[70:71]
	s_add_i32 m0, s0, 0x2000
	s_add_u32 s44, s70, 0x80000
	s_addc_u32 s45, s71, 0
	s_add_i32 s0, s1, s54
	global_load_lds_dwordx4 v162, s[70:71]
	s_mov_b32 m0, s0
	s_nop 0
	global_load_lds_dwordx4 v164, s[44:45]
	s_add_i32 m0, s0, 0x2000
	s_nop 0
	global_load_lds_dwordx4 v162, s[44:45]
	s_mov_b32 m0, s67
	s_nop 0
	global_load_lds_dwordx4 v164, vcc
	s_mov_b32 m0, s68
	s_nop 0
	global_load_lds_dwordx4 v162, vcc
	s_waitcnt vmcnt(8)
	s_waitcnt lgkmcnt(0)
	s_barrier
	s_waitcnt lgkmcnt(0)
	v_mfma_f32_16x16x32_bf16 v[62:65], v[134:137], v[178:181], v[62:65]
	v_mfma_f32_16x16x32_bf16 v[62:65], v[138:141], v[182:185], v[62:65]
	v_mfma_f32_16x16x32_bf16 v[58:61], v[146:149], v[182:185], v[58:61]
	v_mfma_f32_16x16x32_bf16 v[58:61], v[142:145], v[178:181], v[58:61]
	v_mfma_f32_16x16x32_bf16 v[54:57], v[150:153], v[178:181], v[54:57]
	v_mfma_f32_16x16x32_bf16 v[54:57], v[154:157], v[182:185], v[54:57]
	v_mfma_f32_16x16x32_bf16 v[50:53], v[174:177], v[182:185], v[50:53]
	v_mfma_f32_16x16x32_bf16 v[50:53], v[158:161], v[178:181], v[50:53]
	v_mfma_f32_16x16x32_bf16 v[34:37], v[158:161], v[186:189], v[34:37]
	v_mfma_f32_16x16x32_bf16 v[34:37], v[174:177], v[190:193], v[34:37]
	v_mfma_f32_16x16x32_bf16 v[38:41], v[154:157], v[190:193], v[38:41]
	v_mfma_f32_16x16x32_bf16 v[38:41], v[150:153], v[186:189], v[38:41]
	v_mfma_f32_16x16x32_bf16 v[42:45], v[142:145], v[186:189], v[42:45]
	v_mfma_f32_16x16x32_bf16 v[42:45], v[146:149], v[190:193], v[42:45]
	v_mfma_f32_16x16x32_bf16 v[46:49], v[138:141], v[190:193], v[46:49]
	v_mfma_f32_16x16x32_bf16 v[46:49], v[134:137], v[186:189], v[46:49]
	v_mfma_f32_16x16x32_bf16 v[30:33], v[134:137], v[204:207], v[30:33]
	v_mfma_f32_16x16x32_bf16 v[30:33], v[138:141], v[208:211], v[30:33]
	v_mfma_f32_16x16x32_bf16 v[26:29], v[146:149], v[208:211], v[26:29]
	v_mfma_f32_16x16x32_bf16 v[26:29], v[142:145], v[204:207], v[26:29]
	v_mfma_f32_16x16x32_bf16 v[22:25], v[150:153], v[204:207], v[22:25]
	v_mfma_f32_16x16x32_bf16 v[22:25], v[154:157], v[208:211], v[22:25]
	v_mfma_f32_16x16x32_bf16 v[18:21], v[174:177], v[208:211], v[18:21]
	v_mfma_f32_16x16x32_bf16 v[18:21], v[158:161], v[204:207], v[18:21]
	v_mfma_f32_16x16x32_bf16 v[2:5], v[158:161], v[212:215], v[2:5]
	v_mfma_f32_16x16x32_bf16 v[2:5], v[174:177], v[216:219], v[2:5]
	v_mfma_f32_16x16x32_bf16 v[6:9], v[154:157], v[216:219], v[6:9]
	v_mfma_f32_16x16x32_bf16 v[6:9], v[150:153], v[212:215], v[6:9]
	v_mfma_f32_16x16x32_bf16 v[10:13], v[142:145], v[212:215], v[10:13]
	v_mfma_f32_16x16x32_bf16 v[10:13], v[146:149], v[216:219], v[10:13]
	v_mfma_f32_16x16x32_bf16 v[14:17], v[138:141], v[216:219], v[14:17]
	v_mfma_f32_16x16x32_bf16 v[14:17], v[134:137], v[212:215], v[14:17]
	s_barrier
	s_add_i32 s0, 0, 0x18000
	s_add_i32 s1, 0, 0x1c000
	v_add_u32_e32 v146, s0, v1
	v_add_u32_e32 v174, s1, v1
	ds_read_b128 v[134:137], v146
	ds_read_b128 v[138:141], v146 offset:1024
	ds_read_b128 v[142:145], v146 offset:2048
	ds_read_b128 v[146:149], v146 offset:3072
	ds_read_b128 v[150:153], v174
	ds_read_b128 v[154:157], v174 offset:1024
	ds_read_b128 v[158:161], v174 offset:2048
	ds_read_b128 v[174:177], v174 offset:3072
	s_add_u32 s44, vcc_lo, 0x80000
	s_addc_u32 s45, vcc_hi, 0
	s_mov_b32 m0, s8
	ds_read_b128 v[178:181], v222 offset:32768
	ds_read_b128 v[182:185], v222 offset:33792
	ds_read_b128 v[186:189], v222 offset:34816
	ds_read_b128 v[190:193], v222 offset:35840
	ds_read_b128 v[204:207], v222 offset:36864
	ds_read_b128 v[208:211], v222 offset:37888
	ds_read_b128 v[212:215], v222 offset:38912
	ds_read_b128 v[216:219], v222 offset:39936
	global_load_lds_dwordx4 v164, s[44:45]
	s_mov_b32 m0, s9
	s_nop 0
	global_load_lds_dwordx4 v162, s[44:45]
	s_waitcnt vmcnt(8)
	s_waitcnt lgkmcnt(0)
	s_barrier
	s_waitcnt lgkmcnt(0)
	v_mfma_f32_16x16x32_bf16 v[126:129], v[134:137], v[178:181], v[126:129]
	v_mfma_f32_16x16x32_bf16 v[126:129], v[138:141], v[182:185], v[126:129]
	v_mfma_f32_16x16x32_bf16 v[122:125], v[146:149], v[182:185], v[122:125]
	v_mfma_f32_16x16x32_bf16 v[122:125], v[142:145], v[178:181], v[122:125]
	v_mfma_f32_16x16x32_bf16 v[118:121], v[150:153], v[178:181], v[118:121]
	v_mfma_f32_16x16x32_bf16 v[118:121], v[154:157], v[182:185], v[118:121]
	v_mfma_f32_16x16x32_bf16 v[114:117], v[174:177], v[182:185], v[114:117]
	v_mfma_f32_16x16x32_bf16 v[114:117], v[158:161], v[178:181], v[114:117]
	v_mfma_f32_16x16x32_bf16 v[98:101], v[158:161], v[186:189], v[98:101]
	v_mfma_f32_16x16x32_bf16 v[98:101], v[174:177], v[190:193], v[98:101]
	v_mfma_f32_16x16x32_bf16 v[102:105], v[154:157], v[190:193], v[102:105]
	v_mfma_f32_16x16x32_bf16 v[102:105], v[150:153], v[186:189], v[102:105]
	v_mfma_f32_16x16x32_bf16 v[106:109], v[142:145], v[186:189], v[106:109]
	v_mfma_f32_16x16x32_bf16 v[106:109], v[146:149], v[190:193], v[106:109]
	v_mfma_f32_16x16x32_bf16 v[110:113], v[138:141], v[190:193], v[110:113]
	v_mfma_f32_16x16x32_bf16 v[110:113], v[134:137], v[186:189], v[110:113]
	v_mfma_f32_16x16x32_bf16 v[94:97], v[134:137], v[204:207], v[94:97]
	v_mfma_f32_16x16x32_bf16 v[94:97], v[138:141], v[208:211], v[94:97]
	v_mfma_f32_16x16x32_bf16 v[90:93], v[146:149], v[208:211], v[90:93]
	v_mfma_f32_16x16x32_bf16 v[90:93], v[142:145], v[204:207], v[90:93]
	v_mfma_f32_16x16x32_bf16 v[86:89], v[150:153], v[204:207], v[86:89]
	v_mfma_f32_16x16x32_bf16 v[86:89], v[154:157], v[208:211], v[86:89]
	v_mfma_f32_16x16x32_bf16 v[82:85], v[174:177], v[208:211], v[82:85]
	v_mfma_f32_16x16x32_bf16 v[82:85], v[158:161], v[204:207], v[82:85]
	v_mfma_f32_16x16x32_bf16 v[66:69], v[158:161], v[212:215], v[66:69]
	v_mfma_f32_16x16x32_bf16 v[66:69], v[174:177], v[216:219], v[66:69]
	v_mfma_f32_16x16x32_bf16 v[70:73], v[154:157], v[216:219], v[70:73]
	v_mfma_f32_16x16x32_bf16 v[70:73], v[150:153], v[212:215], v[70:73]
	v_mfma_f32_16x16x32_bf16 v[74:77], v[142:145], v[212:215], v[74:77]
	v_mfma_f32_16x16x32_bf16 v[74:77], v[146:149], v[216:219], v[74:77]
	v_mfma_f32_16x16x32_bf16 v[78:81], v[138:141], v[216:219], v[78:81]
	v_mfma_f32_16x16x32_bf16 v[78:81], v[134:137], v[212:215], v[78:81]
	s_barrier
	s_add_u32 s98, s70, 0x80
	s_addc_u32 s99, s71, 0
	s_add_u32 s100, vcc_lo, 0x80
	s_addc_u32 s101, vcc_hi, 0
	s_add_i32 s0, s0, s54
	s_mov_b32 m0, s0
	ds_read_b128 v[178:181], v222 offset:49152
	ds_read_b128 v[182:185], v222 offset:50176
	ds_read_b128 v[186:189], v222 offset:51200
	ds_read_b128 v[190:193], v222 offset:52224
	ds_read_b128 v[204:207], v222 offset:53248
	ds_read_b128 v[208:211], v222 offset:54272
	ds_read_b128 v[212:215], v222 offset:55296
	ds_read_b128 v[216:219], v222 offset:56320
	global_load_lds_dwordx4 v164, s[98:99]
	s_add_i32 m0, s0, 0x2000
	s_add_u32 s44, s70, 0x80080
	s_addc_u32 s45, s71, 0
	s_add_i32 s0, s1, s54
	global_load_lds_dwordx4 v162, s[98:99]
	s_mov_b32 m0, s0
	s_nop 0
	global_load_lds_dwordx4 v164, s[44:45]
	s_add_i32 m0, s0, 0x2000
	s_nop 0
	global_load_lds_dwordx4 v162, s[44:45]
	s_mov_b32 m0, s27
	s_nop 0
	global_load_lds_dwordx4 v164, s[100:101]
	s_mov_b32 m0, s26
	s_nop 0
	global_load_lds_dwordx4 v162, s[100:101]
	s_waitcnt vmcnt(8)
	s_waitcnt lgkmcnt(0)
	s_barrier
	s_waitcnt lgkmcnt(0)
	v_mfma_f32_16x16x32_bf16 v[62:65], v[134:137], v[178:181], v[62:65]
	v_mfma_f32_16x16x32_bf16 v[62:65], v[138:141], v[182:185], v[62:65]
	v_mfma_f32_16x16x32_bf16 v[58:61], v[146:149], v[182:185], v[58:61]
	v_mfma_f32_16x16x32_bf16 v[58:61], v[142:145], v[178:181], v[58:61]
	v_mfma_f32_16x16x32_bf16 v[54:57], v[150:153], v[178:181], v[54:57]
	v_mfma_f32_16x16x32_bf16 v[54:57], v[154:157], v[182:185], v[54:57]
	v_mfma_f32_16x16x32_bf16 v[50:53], v[174:177], v[182:185], v[50:53]
	v_mfma_f32_16x16x32_bf16 v[50:53], v[158:161], v[178:181], v[50:53]
	v_mfma_f32_16x16x32_bf16 v[34:37], v[158:161], v[186:189], v[34:37]
	v_mfma_f32_16x16x32_bf16 v[34:37], v[174:177], v[190:193], v[34:37]
	v_mfma_f32_16x16x32_bf16 v[38:41], v[154:157], v[190:193], v[38:41]
	v_mfma_f32_16x16x32_bf16 v[38:41], v[150:153], v[186:189], v[38:41]
	v_mfma_f32_16x16x32_bf16 v[42:45], v[142:145], v[186:189], v[42:45]
	v_mfma_f32_16x16x32_bf16 v[42:45], v[146:149], v[190:193], v[42:45]
	v_mfma_f32_16x16x32_bf16 v[46:49], v[138:141], v[190:193], v[46:49]
	v_mfma_f32_16x16x32_bf16 v[46:49], v[134:137], v[186:189], v[46:49]
	v_mfma_f32_16x16x32_bf16 v[30:33], v[134:137], v[204:207], v[30:33]
	v_mfma_f32_16x16x32_bf16 v[30:33], v[138:141], v[208:211], v[30:33]
	v_mfma_f32_16x16x32_bf16 v[26:29], v[146:149], v[208:211], v[26:29]
	v_mfma_f32_16x16x32_bf16 v[26:29], v[142:145], v[204:207], v[26:29]
	v_mfma_f32_16x16x32_bf16 v[22:25], v[150:153], v[204:207], v[22:25]
	v_mfma_f32_16x16x32_bf16 v[22:25], v[154:157], v[208:211], v[22:25]
	v_mfma_f32_16x16x32_bf16 v[18:21], v[174:177], v[208:211], v[18:21]
	v_mfma_f32_16x16x32_bf16 v[18:21], v[158:161], v[204:207], v[18:21]
	v_mfma_f32_16x16x32_bf16 v[2:5], v[158:161], v[212:215], v[2:5]
	v_mfma_f32_16x16x32_bf16 v[2:5], v[174:177], v[216:219], v[2:5]
	v_mfma_f32_16x16x32_bf16 v[6:9], v[154:157], v[216:219], v[6:9]
	v_mfma_f32_16x16x32_bf16 v[6:9], v[150:153], v[212:215], v[6:9]
	v_mfma_f32_16x16x32_bf16 v[10:13], v[142:145], v[212:215], v[10:13]
	v_mfma_f32_16x16x32_bf16 v[10:13], v[146:149], v[216:219], v[10:13]
	v_mfma_f32_16x16x32_bf16 v[14:17], v[138:141], v[216:219], v[14:17]
	v_mfma_f32_16x16x32_bf16 v[14:17], v[134:137], v[212:215], v[14:17]
	s_barrier
	s_add_i32 s43, s43, 2
	s_add_u32 s76, s76, 0x100
	s_addc_u32 s77, s77, 0
	s_add_u32 s7, s7, 0x100
	s_addc_u32 s41, s41, 0
	s_cmp_gt_u32 s43, 29
	s_cbranch_scc1 .LBB0_288

.Lpeel_disp_ino:
	s_cmp_lg_u32 s43, -2
	s_cbranch_scc1 .LBB0_285
	s_add_u32 s0, s76, 0xfff80080
	s_addc_u32 s1, s77, -1
	s_and_b64 s[70:71], s[70:71], exec
	s_cselect_b32 vcc_hi, s21, s1
	s_cselect_b32 vcc_lo, s22, s0
	s_cselect_b32 s71, s23, s41
	s_cselect_b32 s70, s39, s7
	s_add_i32 s0, 0, 0x10000
	s_add_i32 s1, 0, 0x14000
	v_add_u32_e32 v146, s0, v1
	v_add_u32_e32 v174, s1, v1
	ds_read_b128 v[134:137], v146
	ds_read_b128 v[138:141], v146 offset:1024
	ds_read_b128 v[142:145], v146 offset:2048
	ds_read_b128 v[146:149], v146 offset:3072
	ds_read_b128 v[150:153], v174
	ds_read_b128 v[154:157], v174 offset:1024
	ds_read_b128 v[158:161], v174 offset:2048
	ds_read_b128 v[174:177], v174 offset:3072
	s_add_i32 m0, s67, 0xc000
	ds_read_b128 v[178:181], v222
	ds_read_b128 v[182:185], v222 offset:1024
	ds_read_b128 v[186:189], v222 offset:2048
	ds_read_b128 v[190:193], v222 offset:3072
	ds_read_b128 v[204:207], v222 offset:4096
	ds_read_b128 v[208:211], v222 offset:5120
	ds_read_b128 v[212:215], v222 offset:6144
	ds_read_b128 v[216:219], v222 offset:7168
	global_load_lds_dwordx4 v170, s[76:77]
	s_add_i32 m0, s67, 0xe000
	s_nop 0
	global_load_lds_dwordx4 v172, s[76:77]
	s_waitcnt vmcnt(8)
	s_waitcnt lgkmcnt(0)
	s_barrier
	s_waitcnt lgkmcnt(0)
	v_mfma_f32_16x16x32_bf16 v[126:129], v[134:137], v[178:181], 0
	v_mfma_f32_16x16x32_bf16 v[126:129], v[138:141], v[182:185], v[126:129]
	v_mfma_f32_16x16x32_bf16 v[122:125], v[146:149], v[182:185], 0
	v_mfma_f32_16x16x32_bf16 v[122:125], v[142:145], v[178:181], v[122:125]
	v_mfma_f32_16x16x32_bf16 v[118:121], v[150:153], v[178:181], 0
	v_mfma_f32_16x16x32_bf16 v[118:121], v[154:157], v[182:185], v[118:121]
	v_mfma_f32_16x16x32_bf16 v[114:117], v[174:177], v[182:185], 0
	v_mfma_f32_16x16x32_bf16 v[114:117], v[158:161], v[178:181], v[114:117]
	v_mfma_f32_16x16x32_bf16 v[98:101], v[158:161], v[186:189], 0
	v_mfma_f32_16x16x32_bf16 v[98:101], v[174:177], v[190:193], v[98:101]
	v_mfma_f32_16x16x32_bf16 v[102:105], v[154:157], v[190:193], 0
	v_mfma_f32_16x16x32_bf16 v[102:105], v[150:153], v[186:189], v[102:105]
	v_mfma_f32_16x16x32_bf16 v[106:109], v[142:145], v[186:189], 0
	v_mfma_f32_16x16x32_bf16 v[106:109], v[146:149], v[190:193], v[106:109]
	v_mfma_f32_16x16x32_bf16 v[110:113], v[138:141], v[190:193], 0
	v_mfma_f32_16x16x32_bf16 v[110:113], v[134:137], v[186:189], v[110:113]
	v_mfma_f32_16x16x32_bf16 v[94:97], v[134:137], v[204:207], 0
	v_mfma_f32_16x16x32_bf16 v[94:97], v[138:141], v[208:211], v[94:97]
	v_mfma_f32_16x16x32_bf16 v[90:93], v[146:149], v[208:211], 0
	v_mfma_f32_16x16x32_bf16 v[90:93], v[142:145], v[204:207], v[90:93]
	v_mfma_f32_16x16x32_bf16 v[86:89], v[150:153], v[204:207], 0
	v_mfma_f32_16x16x32_bf16 v[86:89], v[154:157], v[208:211], v[86:89]
	v_mfma_f32_16x16x32_bf16 v[82:85], v[174:177], v[208:211], 0
	v_mfma_f32_16x16x32_bf16 v[82:85], v[158:161], v[204:207], v[82:85]
	v_mfma_f32_16x16x32_bf16 v[66:69], v[158:161], v[212:215], 0
	v_mfma_f32_16x16x32_bf16 v[66:69], v[174:177], v[216:219], v[66:69]
	v_mfma_f32_16x16x32_bf16 v[70:73], v[154:157], v[216:219], 0
	v_mfma_f32_16x16x32_bf16 v[70:73], v[150:153], v[212:215], v[70:73]
	v_mfma_f32_16x16x32_bf16 v[74:77], v[142:145], v[212:215], 0
	v_mfma_f32_16x16x32_bf16 v[74:77], v[146:149], v[216:219], v[74:77]
	v_mfma_f32_16x16x32_bf16 v[78:81], v[138:141], v[216:219], 0
	v_mfma_f32_16x16x32_bf16 v[78:81], v[134:137], v[212:215], v[78:81]
	s_barrier
	s_add_i32 s0, s0, s54
	s_mov_b32 m0, s0
	ds_read_b128 v[178:181], v222 offset:16384
	ds_read_b128 v[182:185], v222 offset:17408
	ds_read_b128 v[186:189], v222 offset:18432
	ds_read_b128 v[190:193], v222 offset:19456
	ds_read_b128 v[204:207], v222 offset:20480
	ds_read_b128 v[208:211], v222 offset:21504
	ds_read_b128 v[212:215], v222 offset:22528
	ds_read_b128 v[216:219], v222 offset:23552
	global_load_lds_dwordx4 v164, s[70:71]
	s_add_i32 m0, s0, 0x2000
	s_add_u32 s44, s70, 0x80000
	s_addc_u32 s45, s71, 0
	s_add_i32 s0, s1, s54
	global_load_lds_dwordx4 v162, s[70:71]
	s_mov_b32 m0, s0
	s_nop 0
	global_load_lds_dwordx4 v164, s[44:45]
	s_add_i32 m0, s0, 0x2000
	s_nop 0
	global_load_lds_dwordx4 v162, s[44:45]
	s_mov_b32 m0, s67
	s_nop 0
	global_load_lds_dwordx4 v164, vcc
	s_mov_b32 m0, s68
	s_nop 0
	global_load_lds_dwordx4 v162, vcc
	s_waitcnt vmcnt(8)
	s_waitcnt lgkmcnt(0)
	s_barrier
	s_waitcnt lgkmcnt(0)
	v_mfma_f32_16x16x32_bf16 v[62:65], v[134:137], v[178:181], 0
	v_mfma_f32_16x16x32_bf16 v[62:65], v[138:141], v[182:185], v[62:65]
	v_mfma_f32_16x16x32_bf16 v[58:61], v[146:149], v[182:185], 0
	v_mfma_f32_16x16x32_bf16 v[58:61], v[142:145], v[178:181], v[58:61]
	v_mfma_f32_16x16x32_bf16 v[54:57], v[150:153], v[178:181], 0
	v_mfma_f32_16x16x32_bf16 v[54:57], v[154:157], v[182:185], v[54:57]
	v_mfma_f32_16x16x32_bf16 v[50:53], v[174:177], v[182:185], 0
	v_mfma_f32_16x16x32_bf16 v[50:53], v[158:161], v[178:181], v[50:53]
	v_mfma_f32_16x16x32_bf16 v[34:37], v[158:161], v[186:189], 0
	v_mfma_f32_16x16x32_bf16 v[34:37], v[174:177], v[190:193], v[34:37]
	v_mfma_f32_16x16x32_bf16 v[38:41], v[154:157], v[190:193], 0
	v_mfma_f32_16x16x32_bf16 v[38:41], v[150:153], v[186:189], v[38:41]
	v_mfma_f32_16x16x32_bf16 v[42:45], v[142:145], v[186:189], 0
	v_mfma_f32_16x16x32_bf16 v[42:45], v[146:149], v[190:193], v[42:45]
	v_mfma_f32_16x16x32_bf16 v[46:49], v[138:141], v[190:193], 0
	v_mfma_f32_16x16x32_bf16 v[46:49], v[134:137], v[186:189], v[46:49]
	v_mfma_f32_16x16x32_bf16 v[30:33], v[134:137], v[204:207], 0
	v_mfma_f32_16x16x32_bf16 v[30:33], v[138:141], v[208:211], v[30:33]
	v_mfma_f32_16x16x32_bf16 v[26:29], v[146:149], v[208:211], 0
	v_mfma_f32_16x16x32_bf16 v[26:29], v[142:145], v[204:207], v[26:29]
	v_mfma_f32_16x16x32_bf16 v[22:25], v[150:153], v[204:207], 0
	v_mfma_f32_16x16x32_bf16 v[22:25], v[154:157], v[208:211], v[22:25]
	v_mfma_f32_16x16x32_bf16 v[18:21], v[174:177], v[208:211], 0
	v_mfma_f32_16x16x32_bf16 v[18:21], v[158:161], v[204:207], v[18:21]
	v_mfma_f32_16x16x32_bf16 v[2:5], v[158:161], v[212:215], 0
	v_mfma_f32_16x16x32_bf16 v[2:5], v[174:177], v[216:219], v[2:5]
	v_mfma_f32_16x16x32_bf16 v[6:9], v[154:157], v[216:219], 0
	v_mfma_f32_16x16x32_bf16 v[6:9], v[150:153], v[212:215], v[6:9]
	v_mfma_f32_16x16x32_bf16 v[10:13], v[142:145], v[212:215], 0
	v_mfma_f32_16x16x32_bf16 v[10:13], v[146:149], v[216:219], v[10:13]
	v_mfma_f32_16x16x32_bf16 v[14:17], v[138:141], v[216:219], 0
	v_mfma_f32_16x16x32_bf16 v[14:17], v[134:137], v[212:215], v[14:17]
	s_barrier
	s_add_i32 s0, 0, 0x18000
	s_add_i32 s1, 0, 0x1c000
	v_add_u32_e32 v146, s0, v1
	v_add_u32_e32 v174, s1, v1
	ds_read_b128 v[134:137], v146
	ds_read_b128 v[138:141], v146 offset:1024
	ds_read_b128 v[142:145], v146 offset:2048
	ds_read_b128 v[146:149], v146 offset:3072
	ds_read_b128 v[150:153], v174
	ds_read_b128 v[154:157], v174 offset:1024
	ds_read_b128 v[158:161], v174 offset:2048
	ds_read_b128 v[174:177], v174 offset:3072
	s_add_u32 s44, vcc_lo, 0x80000
	s_addc_u32 s45, vcc_hi, 0
	s_mov_b32 m0, s8
	ds_read_b128 v[178:181], v222 offset:32768
	ds_read_b128 v[182:185], v222 offset:33792
	ds_read_b128 v[186:189], v222 offset:34816
	ds_read_b128 v[190:193], v222 offset:35840
	ds_read_b128 v[204:207], v222 offset:36864
	ds_read_b128 v[208:211], v222 offset:37888
	ds_read_b128 v[212:215], v222 offset:38912
	ds_read_b128 v[216:219], v222 offset:39936
	global_load_lds_dwordx4 v164, s[44:45]
	s_mov_b32 m0, s9
	s_nop 0
	global_load_lds_dwordx4 v162, s[44:45]
	s_waitcnt vmcnt(8)
	s_waitcnt lgkmcnt(0)
	s_barrier
	s_waitcnt lgkmcnt(0)
	v_mfma_f32_16x16x32_bf16 v[126:129], v[134:137], v[178:181], v[126:129]
	v_mfma_f32_16x16x32_bf16 v[126:129], v[138:141], v[182:185], v[126:129]
	v_mfma_f32_16x16x32_bf16 v[122:125], v[146:149], v[182:185], v[122:125]
	v_mfma_f32_16x16x32_bf16 v[122:125], v[142:145], v[178:181], v[122:125]
	v_mfma_f32_16x16x32_bf16 v[118:121], v[150:153], v[178:181], v[118:121]
	v_mfma_f32_16x16x32_bf16 v[118:121], v[154:157], v[182:185], v[118:121]
	v_mfma_f32_16x16x32_bf16 v[114:117], v[174:177], v[182:185], v[114:117]
	v_mfma_f32_16x16x32_bf16 v[114:117], v[158:161], v[178:181], v[114:117]
	v_mfma_f32_16x16x32_bf16 v[98:101], v[158:161], v[186:189], v[98:101]
	v_mfma_f32_16x16x32_bf16 v[98:101], v[174:177], v[190:193], v[98:101]
	v_mfma_f32_16x16x32_bf16 v[102:105], v[154:157], v[190:193], v[102:105]
	v_mfma_f32_16x16x32_bf16 v[102:105], v[150:153], v[186:189], v[102:105]
	v_mfma_f32_16x16x32_bf16 v[106:109], v[142:145], v[186:189], v[106:109]
	v_mfma_f32_16x16x32_bf16 v[106:109], v[146:149], v[190:193], v[106:109]
	v_mfma_f32_16x16x32_bf16 v[110:113], v[138:141], v[190:193], v[110:113]
	v_mfma_f32_16x16x32_bf16 v[110:113], v[134:137], v[186:189], v[110:113]
	v_mfma_f32_16x16x32_bf16 v[94:97], v[134:137], v[204:207], v[94:97]
	v_mfma_f32_16x16x32_bf16 v[94:97], v[138:141], v[208:211], v[94:97]
	v_mfma_f32_16x16x32_bf16 v[90:93], v[146:149], v[208:211], v[90:93]
	v_mfma_f32_16x16x32_bf16 v[90:93], v[142:145], v[204:207], v[90:93]
	v_mfma_f32_16x16x32_bf16 v[86:89], v[150:153], v[204:207], v[86:89]
	v_mfma_f32_16x16x32_bf16 v[86:89], v[154:157], v[208:211], v[86:89]
	v_mfma_f32_16x16x32_bf16 v[82:85], v[174:177], v[208:211], v[82:85]
	v_mfma_f32_16x16x32_bf16 v[82:85], v[158:161], v[204:207], v[82:85]
	v_mfma_f32_16x16x32_bf16 v[66:69], v[158:161], v[212:215], v[66:69]
	v_mfma_f32_16x16x32_bf16 v[66:69], v[174:177], v[216:219], v[66:69]
	v_mfma_f32_16x16x32_bf16 v[70:73], v[154:157], v[216:219], v[70:73]
	v_mfma_f32_16x16x32_bf16 v[70:73], v[150:153], v[212:215], v[70:73]
	v_mfma_f32_16x16x32_bf16 v[74:77], v[142:145], v[212:215], v[74:77]
	v_mfma_f32_16x16x32_bf16 v[74:77], v[146:149], v[216:219], v[74:77]
	v_mfma_f32_16x16x32_bf16 v[78:81], v[138:141], v[216:219], v[78:81]
	v_mfma_f32_16x16x32_bf16 v[78:81], v[134:137], v[212:215], v[78:81]
	s_barrier
	s_add_u32 s98, s70, 0x80
	s_addc_u32 s99, s71, 0
	s_add_u32 s100, vcc_lo, 0x80
	s_addc_u32 s101, vcc_hi, 0
	s_add_i32 s0, s0, s54
	s_mov_b32 m0, s0
	ds_read_b128 v[178:181], v222 offset:49152
	ds_read_b128 v[182:185], v222 offset:50176
	ds_read_b128 v[186:189], v222 offset:51200
	ds_read_b128 v[190:193], v222 offset:52224
	ds_read_b128 v[204:207], v222 offset:53248
	ds_read_b128 v[208:211], v222 offset:54272
	ds_read_b128 v[212:215], v222 offset:55296
	ds_read_b128 v[216:219], v222 offset:56320
	global_load_lds_dwordx4 v164, s[98:99]
	s_add_i32 m0, s0, 0x2000
	s_add_u32 s44, s70, 0x80080
	s_addc_u32 s45, s71, 0
	s_add_i32 s0, s1, s54
	global_load_lds_dwordx4 v162, s[98:99]
	s_mov_b32 m0, s0
	s_nop 0
	global_load_lds_dwordx4 v164, s[44:45]
	s_add_i32 m0, s0, 0x2000
	s_nop 0
	global_load_lds_dwordx4 v162, s[44:45]
	s_mov_b32 m0, s27
	s_nop 0
	global_load_lds_dwordx4 v164, s[100:101]
	s_mov_b32 m0, s26
	s_nop 0
	global_load_lds_dwordx4 v162, s[100:101]
	s_waitcnt vmcnt(8)
	s_waitcnt lgkmcnt(0)
	s_barrier
	s_waitcnt lgkmcnt(0)
	v_mfma_f32_16x16x32_bf16 v[62:65], v[134:137], v[178:181], v[62:65]
	v_mfma_f32_16x16x32_bf16 v[62:65], v[138:141], v[182:185], v[62:65]
	v_mfma_f32_16x16x32_bf16 v[58:61], v[146:149], v[182:185], v[58:61]
	v_mfma_f32_16x16x32_bf16 v[58:61], v[142:145], v[178:181], v[58:61]
	v_mfma_f32_16x16x32_bf16 v[54:57], v[150:153], v[178:181], v[54:57]
	v_mfma_f32_16x16x32_bf16 v[54:57], v[154:157], v[182:185], v[54:57]
	v_mfma_f32_16x16x32_bf16 v[50:53], v[174:177], v[182:185], v[50:53]
	v_mfma_f32_16x16x32_bf16 v[50:53], v[158:161], v[178:181], v[50:53]
	v_mfma_f32_16x16x32_bf16 v[34:37], v[158:161], v[186:189], v[34:37]
	v_mfma_f32_16x16x32_bf16 v[34:37], v[174:177], v[190:193], v[34:37]
	v_mfma_f32_16x16x32_bf16 v[38:41], v[154:157], v[190:193], v[38:41]
	v_mfma_f32_16x16x32_bf16 v[38:41], v[150:153], v[186:189], v[38:41]
	v_mfma_f32_16x16x32_bf16 v[42:45], v[142:145], v[186:189], v[42:45]
	v_mfma_f32_16x16x32_bf16 v[42:45], v[146:149], v[190:193], v[42:45]
	v_mfma_f32_16x16x32_bf16 v[46:49], v[138:141], v[190:193], v[46:49]
	v_mfma_f32_16x16x32_bf16 v[46:49], v[134:137], v[186:189], v[46:49]
	v_mfma_f32_16x16x32_bf16 v[30:33], v[134:137], v[204:207], v[30:33]
	v_mfma_f32_16x16x32_bf16 v[30:33], v[138:141], v[208:211], v[30:33]
	v_mfma_f32_16x16x32_bf16 v[26:29], v[146:149], v[208:211], v[26:29]
	v_mfma_f32_16x16x32_bf16 v[26:29], v[142:145], v[204:207], v[26:29]
	v_mfma_f32_16x16x32_bf16 v[22:25], v[150:153], v[204:207], v[22:25]
	v_mfma_f32_16x16x32_bf16 v[22:25], v[154:157], v[208:211], v[22:25]
	v_mfma_f32_16x16x32_bf16 v[18:21], v[174:177], v[208:211], v[18:21]
	v_mfma_f32_16x16x32_bf16 v[18:21], v[158:161], v[204:207], v[18:21]
	v_mfma_f32_16x16x32_bf16 v[2:5], v[158:161], v[212:215], v[2:5]
	v_mfma_f32_16x16x32_bf16 v[2:5], v[174:177], v[216:219], v[2:5]
	v_mfma_f32_16x16x32_bf16 v[6:9], v[154:157], v[216:219], v[6:9]
	v_mfma_f32_16x16x32_bf16 v[6:9], v[150:153], v[212:215], v[6:9]
	v_mfma_f32_16x16x32_bf16 v[10:13], v[142:145], v[212:215], v[10:13]
	v_mfma_f32_16x16x32_bf16 v[10:13], v[146:149], v[216:219], v[10:13]
	v_mfma_f32_16x16x32_bf16 v[14:17], v[138:141], v[216:219], v[14:17]
	v_mfma_f32_16x16x32_bf16 v[14:17], v[134:137], v[212:215], v[14:17]
	s_barrier
	s_add_i32 s43, s43, 2
	s_add_u32 s76, s76, 0x100
	s_addc_u32 s77, s77, 0
	s_add_u32 s7, s7, 0x100
	s_addc_u32 s41, s41, 0
	s_cmp_gt_u32 s43, 29
	s_cbranch_scc1 .LBB0_288
	s_branch .LBB0_286

.LBB0_509:
	s_add_u32 s90, s76, 0x100
	s_addc_u32 s91, s77, 0
	s_and_b64 s[0:1], s[70:71], exec
	s_cselect_b32 vcc_hi, s22, s91
	s_cselect_b32 vcc_lo, s23, s90
	s_cselect_b32 s71, s41, s53
	s_cselect_b32 s70, s44, s51
	s_add_i32 s0, 0, 0x10000
	s_add_i32 s18, 0, 0x14000
	v_add_u32_e32 v114, s0, v1
	v_add_u32_e32 v154, s18, v1
	ds_read_b128 v[78:81], v114
	ds_read_b128 v[90:93], v114 offset:1024
	ds_read_b128 v[102:105], v114 offset:2048
	ds_read_b128 v[114:117], v114 offset:3072
	ds_read_b128 v[126:129], v154
	ds_read_b128 v[134:137], v154 offset:1024
	ds_read_b128 v[142:145], v154 offset:2048
	ds_read_b128 v[154:157], v154 offset:3072
	s_add_i32 m0, s29, 0xc000
	ds_read_b128 v[158:161], v237
	ds_read_b128 v[162:165], v237 offset:1024
	ds_read_b128 v[166:169], v237 offset:2048
	ds_read_b128 v[178:181], v237 offset:3072
	ds_read_b128 v[182:185], v237 offset:4096
	ds_read_b128 v[186:189], v237 offset:5120
	ds_read_b128 v[190:193], v237 offset:6144
	ds_read_b128 v[214:217], v237 offset:7168
	global_load_lds_dwordx4 v210, s[76:77]
	s_add_i32 m0, s29, 0xe000
	s_nop 0
	global_load_lds_dwordx4 v212, s[76:77]
	s_waitcnt vmcnt(8)
	s_waitcnt lgkmcnt(0)
	s_barrier
	s_waitcnt lgkmcnt(0)
	v_mfma_f32_16x16x32_bf16 v[174:177], v[78:81], v[158:161], v[174:177]
	v_mfma_f32_16x16x32_bf16 v[174:177], v[90:93], v[162:165], v[174:177]
	v_mfma_f32_16x16x32_bf16 v[170:173], v[114:117], v[162:165], v[170:173]
	v_mfma_f32_16x16x32_bf16 v[170:173], v[102:105], v[158:161], v[170:173]
	v_mfma_f32_16x16x32_bf16 v[150:153], v[126:129], v[158:161], v[150:153]
	v_mfma_f32_16x16x32_bf16 v[150:153], v[134:137], v[162:165], v[150:153]
	v_mfma_f32_16x16x32_bf16 v[146:149], v[154:157], v[162:165], v[146:149]
	v_mfma_f32_16x16x32_bf16 v[146:149], v[142:145], v[158:161], v[146:149]
	v_mfma_f32_16x16x32_bf16 v[118:121], v[142:145], v[166:169], v[118:121]
	v_mfma_f32_16x16x32_bf16 v[118:121], v[154:157], v[178:181], v[118:121]
	v_mfma_f32_16x16x32_bf16 v[122:125], v[134:137], v[178:181], v[122:125]
	v_mfma_f32_16x16x32_bf16 v[122:125], v[126:129], v[166:169], v[122:125]
	v_mfma_f32_16x16x32_bf16 v[130:133], v[102:105], v[166:169], v[130:133]
	v_mfma_f32_16x16x32_bf16 v[130:133], v[114:117], v[178:181], v[130:133]
	v_mfma_f32_16x16x32_bf16 v[138:141], v[90:93], v[178:181], v[138:141]
	v_mfma_f32_16x16x32_bf16 v[138:141], v[78:81], v[166:169], v[138:141]
	v_mfma_f32_16x16x32_bf16 v[110:113], v[78:81], v[182:185], v[110:113]
	v_mfma_f32_16x16x32_bf16 v[110:113], v[90:93], v[186:189], v[110:113]
	v_mfma_f32_16x16x32_bf16 v[106:109], v[114:117], v[186:189], v[106:109]
	v_mfma_f32_16x16x32_bf16 v[106:109], v[102:105], v[182:185], v[106:109]
	v_mfma_f32_16x16x32_bf16 v[98:101], v[126:129], v[182:185], v[98:101]
	v_mfma_f32_16x16x32_bf16 v[98:101], v[134:137], v[186:189], v[98:101]
	v_mfma_f32_16x16x32_bf16 v[94:97], v[154:157], v[186:189], v[94:97]
	v_mfma_f32_16x16x32_bf16 v[94:97], v[142:145], v[182:185], v[94:97]
	v_mfma_f32_16x16x32_bf16 v[66:69], v[142:145], v[190:193], v[66:69]
	v_mfma_f32_16x16x32_bf16 v[66:69], v[154:157], v[214:217], v[66:69]
	v_mfma_f32_16x16x32_bf16 v[74:77], v[134:137], v[214:217], v[74:77]
	v_mfma_f32_16x16x32_bf16 v[74:77], v[126:129], v[190:193], v[74:77]
	v_mfma_f32_16x16x32_bf16 v[82:85], v[102:105], v[190:193], v[82:85]
	v_mfma_f32_16x16x32_bf16 v[82:85], v[114:117], v[214:217], v[82:85]
	v_mfma_f32_16x16x32_bf16 v[86:89], v[90:93], v[214:217], v[86:89]
	v_mfma_f32_16x16x32_bf16 v[86:89], v[78:81], v[190:193], v[86:89]
	s_barrier
	s_add_i32 s0, s0, s28
	s_mov_b32 m0, s0
	ds_read_b128 v[158:161], v237 offset:16384
	ds_read_b128 v[162:165], v237 offset:17408
	ds_read_b128 v[166:169], v237 offset:18432
	ds_read_b128 v[178:181], v237 offset:19456
	ds_read_b128 v[182:185], v237 offset:20480
	ds_read_b128 v[186:189], v237 offset:21504
	ds_read_b128 v[190:193], v237 offset:22528
	ds_read_b128 v[214:217], v237 offset:23552
	global_load_lds_dwordx4 v194, s[70:71]
	s_add_i32 m0, s0, 0x2000
	s_add_u32 s0, s70, 0x80000
	s_addc_u32 s1, s71, 0
	s_add_i32 s18, s18, s28
	global_load_lds_dwordx4 v204, s[70:71]
	s_mov_b32 m0, s18
	s_nop 0
	global_load_lds_dwordx4 v194, s[0:1]
	s_add_i32 m0, s18, 0x2000
	s_nop 0
	global_load_lds_dwordx4 v204, s[0:1]
	s_mov_b32 m0, s29
	s_nop 0
	global_load_lds_dwordx4 v194, vcc
	s_mov_b32 m0, s31
	s_nop 0
	global_load_lds_dwordx4 v204, vcc
	s_waitcnt vmcnt(8)
	s_waitcnt lgkmcnt(0)
	s_barrier
	s_waitcnt lgkmcnt(0)
	v_mfma_f32_16x16x32_bf16 v[62:65], v[78:81], v[158:161], v[62:65]
	v_mfma_f32_16x16x32_bf16 v[62:65], v[90:93], v[162:165], v[62:65]
	v_mfma_f32_16x16x32_bf16 v[58:61], v[114:117], v[162:165], v[58:61]
	v_mfma_f32_16x16x32_bf16 v[58:61], v[102:105], v[158:161], v[58:61]
	v_mfma_f32_16x16x32_bf16 v[54:57], v[126:129], v[158:161], v[54:57]
	v_mfma_f32_16x16x32_bf16 v[54:57], v[134:137], v[162:165], v[54:57]
	v_mfma_f32_16x16x32_bf16 v[50:53], v[154:157], v[162:165], v[50:53]
	v_mfma_f32_16x16x32_bf16 v[50:53], v[142:145], v[158:161], v[50:53]
	v_mfma_f32_16x16x32_bf16 v[34:37], v[142:145], v[166:169], v[34:37]
	v_mfma_f32_16x16x32_bf16 v[34:37], v[154:157], v[178:181], v[34:37]
	v_mfma_f32_16x16x32_bf16 v[38:41], v[134:137], v[178:181], v[38:41]
	v_mfma_f32_16x16x32_bf16 v[38:41], v[126:129], v[166:169], v[38:41]
	v_mfma_f32_16x16x32_bf16 v[42:45], v[102:105], v[166:169], v[42:45]
	v_mfma_f32_16x16x32_bf16 v[42:45], v[114:117], v[178:181], v[42:45]
	v_mfma_f32_16x16x32_bf16 v[46:49], v[90:93], v[178:181], v[46:49]
	v_mfma_f32_16x16x32_bf16 v[46:49], v[78:81], v[166:169], v[46:49]
	v_mfma_f32_16x16x32_bf16 v[30:33], v[78:81], v[182:185], v[30:33]
	v_mfma_f32_16x16x32_bf16 v[30:33], v[90:93], v[186:189], v[30:33]
	v_mfma_f32_16x16x32_bf16 v[26:29], v[114:117], v[186:189], v[26:29]
	v_mfma_f32_16x16x32_bf16 v[26:29], v[102:105], v[182:185], v[26:29]
	v_mfma_f32_16x16x32_bf16 v[22:25], v[126:129], v[182:185], v[22:25]
	v_mfma_f32_16x16x32_bf16 v[22:25], v[134:137], v[186:189], v[22:25]
	v_mfma_f32_16x16x32_bf16 v[18:21], v[154:157], v[186:189], v[18:21]
	v_mfma_f32_16x16x32_bf16 v[18:21], v[142:145], v[182:185], v[18:21]
	v_mfma_f32_16x16x32_bf16 v[2:5], v[142:145], v[190:193], v[2:5]
	v_mfma_f32_16x16x32_bf16 v[2:5], v[154:157], v[214:217], v[2:5]
	v_mfma_f32_16x16x32_bf16 v[6:9], v[134:137], v[214:217], v[6:9]
	v_mfma_f32_16x16x32_bf16 v[6:9], v[126:129], v[190:193], v[6:9]
	v_mfma_f32_16x16x32_bf16 v[10:13], v[102:105], v[190:193], v[10:13]
	v_mfma_f32_16x16x32_bf16 v[10:13], v[114:117], v[214:217], v[10:13]
	v_mfma_f32_16x16x32_bf16 v[14:17], v[90:93], v[214:217], v[14:17]
	v_mfma_f32_16x16x32_bf16 v[14:17], v[78:81], v[190:193], v[14:17]
	s_barrier
	s_add_i32 s18, 0, 0x18000
	s_add_i32 s19, 0, 0x1c000
	v_add_u32_e32 v114, s18, v1
	v_add_u32_e32 v154, s19, v1
	ds_read_b128 v[78:81], v114
	ds_read_b128 v[90:93], v114 offset:1024
	ds_read_b128 v[102:105], v114 offset:2048
	ds_read_b128 v[114:117], v114 offset:3072
	ds_read_b128 v[126:129], v154
	ds_read_b128 v[134:137], v154 offset:1024
	ds_read_b128 v[142:145], v154 offset:2048
	ds_read_b128 v[154:157], v154 offset:3072
	s_add_u32 s0, vcc_lo, 0x80000
	s_addc_u32 s1, vcc_hi, 0
	s_mov_b32 m0, s33
	ds_read_b128 v[158:161], v237 offset:32768
	ds_read_b128 v[162:165], v237 offset:33792
	ds_read_b128 v[166:169], v237 offset:34816
	ds_read_b128 v[178:181], v237 offset:35840
	ds_read_b128 v[182:185], v237 offset:36864
	ds_read_b128 v[186:189], v237 offset:37888
	ds_read_b128 v[190:193], v237 offset:38912
	ds_read_b128 v[214:217], v237 offset:39936
	global_load_lds_dwordx4 v194, s[0:1]
	s_mov_b32 m0, s43
	s_nop 0
	global_load_lds_dwordx4 v204, s[0:1]
	s_waitcnt vmcnt(8)
	s_waitcnt lgkmcnt(0)
	s_barrier
	s_waitcnt lgkmcnt(0)
	v_mfma_f32_16x16x32_bf16 v[174:177], v[78:81], v[158:161], v[174:177]
	v_mfma_f32_16x16x32_bf16 v[174:177], v[90:93], v[162:165], v[174:177]
	v_mfma_f32_16x16x32_bf16 v[170:173], v[114:117], v[162:165], v[170:173]
	v_mfma_f32_16x16x32_bf16 v[170:173], v[102:105], v[158:161], v[170:173]
	v_mfma_f32_16x16x32_bf16 v[150:153], v[126:129], v[158:161], v[150:153]
	v_mfma_f32_16x16x32_bf16 v[150:153], v[134:137], v[162:165], v[150:153]
	v_mfma_f32_16x16x32_bf16 v[146:149], v[154:157], v[162:165], v[146:149]
	v_mfma_f32_16x16x32_bf16 v[146:149], v[142:145], v[158:161], v[146:149]
	v_mfma_f32_16x16x32_bf16 v[118:121], v[142:145], v[166:169], v[118:121]
	v_mfma_f32_16x16x32_bf16 v[118:121], v[154:157], v[178:181], v[118:121]
	v_mfma_f32_16x16x32_bf16 v[122:125], v[134:137], v[178:181], v[122:125]
	v_mfma_f32_16x16x32_bf16 v[122:125], v[126:129], v[166:169], v[122:125]
	v_mfma_f32_16x16x32_bf16 v[130:133], v[102:105], v[166:169], v[130:133]
	v_mfma_f32_16x16x32_bf16 v[130:133], v[114:117], v[178:181], v[130:133]
	v_mfma_f32_16x16x32_bf16 v[138:141], v[90:93], v[178:181], v[138:141]
	v_mfma_f32_16x16x32_bf16 v[138:141], v[78:81], v[166:169], v[138:141]
	v_mfma_f32_16x16x32_bf16 v[110:113], v[78:81], v[182:185], v[110:113]
	v_mfma_f32_16x16x32_bf16 v[110:113], v[90:93], v[186:189], v[110:113]
	v_mfma_f32_16x16x32_bf16 v[106:109], v[114:117], v[186:189], v[106:109]
	v_mfma_f32_16x16x32_bf16 v[106:109], v[102:105], v[182:185], v[106:109]
	v_mfma_f32_16x16x32_bf16 v[98:101], v[126:129], v[182:185], v[98:101]
	v_mfma_f32_16x16x32_bf16 v[98:101], v[134:137], v[186:189], v[98:101]
	v_mfma_f32_16x16x32_bf16 v[94:97], v[154:157], v[186:189], v[94:97]
	v_mfma_f32_16x16x32_bf16 v[94:97], v[142:145], v[182:185], v[94:97]
	v_mfma_f32_16x16x32_bf16 v[66:69], v[142:145], v[190:193], v[66:69]
	v_mfma_f32_16x16x32_bf16 v[66:69], v[154:157], v[214:217], v[66:69]
	v_mfma_f32_16x16x32_bf16 v[74:77], v[134:137], v[214:217], v[74:77]
	v_mfma_f32_16x16x32_bf16 v[74:77], v[126:129], v[190:193], v[74:77]
	v_mfma_f32_16x16x32_bf16 v[82:85], v[102:105], v[190:193], v[82:85]
	v_mfma_f32_16x16x32_bf16 v[82:85], v[114:117], v[214:217], v[82:85]
	v_mfma_f32_16x16x32_bf16 v[86:89], v[90:93], v[214:217], v[86:89]
	v_mfma_f32_16x16x32_bf16 v[86:89], v[78:81], v[190:193], v[86:89]
	s_barrier
	s_add_u32 s98, s70, 0x80
	s_addc_u32 s99, s71, 0
	s_add_u32 s100, vcc_lo, 0x80
	s_addc_u32 s101, vcc_hi, 0
	s_add_i32 s0, s18, s28
	s_mov_b32 m0, s0
	ds_read_b128 v[158:161], v237 offset:49152
	ds_read_b128 v[162:165], v237 offset:50176
	ds_read_b128 v[166:169], v237 offset:51200
	ds_read_b128 v[178:181], v237 offset:52224
	ds_read_b128 v[182:185], v237 offset:53248
	ds_read_b128 v[186:189], v237 offset:54272
	ds_read_b128 v[190:193], v237 offset:55296
	ds_read_b128 v[214:217], v237 offset:56320
	global_load_lds_dwordx4 v194, s[98:99]
	s_add_i32 m0, s0, 0x2000
	s_add_u32 s0, s70, 0x80080
	s_addc_u32 s1, s71, 0
	s_add_i32 s18, s19, s28
	global_load_lds_dwordx4 v204, s[98:99]
	s_mov_b32 m0, s18
	s_nop 0
	global_load_lds_dwordx4 v194, s[0:1]
	s_add_i32 m0, s18, 0x2000
	s_nop 0
	global_load_lds_dwordx4 v204, s[0:1]
	s_mov_b32 m0, s68
	s_nop 0
	global_load_lds_dwordx4 v194, s[100:101]
	s_mov_b32 m0, s79
	s_nop 0
	global_load_lds_dwordx4 v204, s[100:101]
	s_waitcnt vmcnt(8)
	s_waitcnt lgkmcnt(0)
	s_barrier
	s_waitcnt lgkmcnt(0)
	v_mfma_f32_16x16x32_bf16 v[62:65], v[78:81], v[158:161], v[62:65]
	v_mfma_f32_16x16x32_bf16 v[62:65], v[90:93], v[162:165], v[62:65]
	v_mfma_f32_16x16x32_bf16 v[58:61], v[114:117], v[162:165], v[58:61]
	v_mfma_f32_16x16x32_bf16 v[58:61], v[102:105], v[158:161], v[58:61]
	v_mfma_f32_16x16x32_bf16 v[54:57], v[126:129], v[158:161], v[54:57]
	v_mfma_f32_16x16x32_bf16 v[54:57], v[134:137], v[162:165], v[54:57]
	v_mfma_f32_16x16x32_bf16 v[50:53], v[154:157], v[162:165], v[50:53]
	v_mfma_f32_16x16x32_bf16 v[50:53], v[142:145], v[158:161], v[50:53]
	v_mfma_f32_16x16x32_bf16 v[34:37], v[142:145], v[166:169], v[34:37]
	v_mfma_f32_16x16x32_bf16 v[34:37], v[154:157], v[178:181], v[34:37]
	v_mfma_f32_16x16x32_bf16 v[38:41], v[134:137], v[178:181], v[38:41]
	v_mfma_f32_16x16x32_bf16 v[38:41], v[126:129], v[166:169], v[38:41]
	v_mfma_f32_16x16x32_bf16 v[42:45], v[102:105], v[166:169], v[42:45]
	v_mfma_f32_16x16x32_bf16 v[42:45], v[114:117], v[178:181], v[42:45]
	v_mfma_f32_16x16x32_bf16 v[46:49], v[90:93], v[178:181], v[46:49]
	v_mfma_f32_16x16x32_bf16 v[46:49], v[78:81], v[166:169], v[46:49]
	v_mfma_f32_16x16x32_bf16 v[30:33], v[78:81], v[182:185], v[30:33]
	v_mfma_f32_16x16x32_bf16 v[30:33], v[90:93], v[186:189], v[30:33]
	v_mfma_f32_16x16x32_bf16 v[26:29], v[114:117], v[186:189], v[26:29]
	v_mfma_f32_16x16x32_bf16 v[26:29], v[102:105], v[182:185], v[26:29]
	v_mfma_f32_16x16x32_bf16 v[22:25], v[126:129], v[182:185], v[22:25]
	v_mfma_f32_16x16x32_bf16 v[22:25], v[134:137], v[186:189], v[22:25]
	v_mfma_f32_16x16x32_bf16 v[18:21], v[154:157], v[186:189], v[18:21]
	v_mfma_f32_16x16x32_bf16 v[18:21], v[142:145], v[182:185], v[18:21]
	v_mfma_f32_16x16x32_bf16 v[2:5], v[142:145], v[190:193], v[2:5]
	v_mfma_f32_16x16x32_bf16 v[2:5], v[154:157], v[214:217], v[2:5]
	v_mfma_f32_16x16x32_bf16 v[6:9], v[134:137], v[214:217], v[6:9]
	v_mfma_f32_16x16x32_bf16 v[6:9], v[126:129], v[190:193], v[6:9]
	v_mfma_f32_16x16x32_bf16 v[10:13], v[102:105], v[190:193], v[10:13]
	v_mfma_f32_16x16x32_bf16 v[10:13], v[114:117], v[214:217], v[10:13]
	v_mfma_f32_16x16x32_bf16 v[14:17], v[90:93], v[214:217], v[14:17]
	v_mfma_f32_16x16x32_bf16 v[14:17], v[78:81], v[190:193], v[14:17]
	s_barrier
	s_add_i32 s57, s57, 2
	s_add_u32 s51, s51, 0x100
	s_addc_u32 s53, s53, 0
	s_cmp_gt_u32 s57, 29
	s_mov_b64 s[76:77], s[90:91]
	s_cbranch_scc1 .LBB0_512

.Lpeel_disp_out:
	s_cmp_lg_u32 s57, -2
	s_cbranch_scc1 .LBB0_509
	s_add_u32 s90, s76, 0x100
	s_addc_u32 s91, s77, 0
	s_and_b64 s[0:1], s[70:71], exec
	s_cselect_b32 vcc_hi, s22, s91
	s_cselect_b32 vcc_lo, s23, s90
	s_cselect_b32 s71, s41, s53
	s_cselect_b32 s70, s44, s51
	s_add_i32 s0, 0, 0x10000
	s_add_i32 s18, 0, 0x14000
	v_add_u32_e32 v114, s0, v1
	v_add_u32_e32 v154, s18, v1
	ds_read_b128 v[78:81], v114
	ds_read_b128 v[90:93], v114 offset:1024
	ds_read_b128 v[102:105], v114 offset:2048
	ds_read_b128 v[114:117], v114 offset:3072
	ds_read_b128 v[126:129], v154
	ds_read_b128 v[134:137], v154 offset:1024
	ds_read_b128 v[142:145], v154 offset:2048
	ds_read_b128 v[154:157], v154 offset:3072
	s_add_i32 m0, s29, 0xc000
	ds_read_b128 v[158:161], v237
	ds_read_b128 v[162:165], v237 offset:1024
	ds_read_b128 v[166:169], v237 offset:2048
	ds_read_b128 v[178:181], v237 offset:3072
	ds_read_b128 v[182:185], v237 offset:4096
	ds_read_b128 v[186:189], v237 offset:5120
	ds_read_b128 v[190:193], v237 offset:6144
	ds_read_b128 v[214:217], v237 offset:7168
	global_load_lds_dwordx4 v210, s[76:77]
	s_add_i32 m0, s29, 0xe000
	s_nop 0
	global_load_lds_dwordx4 v212, s[76:77]
	s_waitcnt vmcnt(8)
	s_waitcnt lgkmcnt(0)
	s_barrier
	s_waitcnt lgkmcnt(0)
	v_mfma_f32_16x16x32_bf16 v[174:177], v[78:81], v[158:161], 0
	v_mfma_f32_16x16x32_bf16 v[174:177], v[90:93], v[162:165], v[174:177]
	v_mfma_f32_16x16x32_bf16 v[170:173], v[114:117], v[162:165], 0
	v_mfma_f32_16x16x32_bf16 v[170:173], v[102:105], v[158:161], v[170:173]
	v_mfma_f32_16x16x32_bf16 v[150:153], v[126:129], v[158:161], 0
	v_mfma_f32_16x16x32_bf16 v[150:153], v[134:137], v[162:165], v[150:153]
	v_mfma_f32_16x16x32_bf16 v[146:149], v[154:157], v[162:165], 0
	v_mfma_f32_16x16x32_bf16 v[146:149], v[142:145], v[158:161], v[146:149]
	v_mfma_f32_16x16x32_bf16 v[118:121], v[142:145], v[166:169], 0
	v_mfma_f32_16x16x32_bf16 v[118:121], v[154:157], v[178:181], v[118:121]
	v_mfma_f32_16x16x32_bf16 v[122:125], v[134:137], v[178:181], 0
	v_mfma_f32_16x16x32_bf16 v[122:125], v[126:129], v[166:169], v[122:125]
	v_mfma_f32_16x16x32_bf16 v[130:133], v[102:105], v[166:169], 0
	v_mfma_f32_16x16x32_bf16 v[130:133], v[114:117], v[178:181], v[130:133]
	v_mfma_f32_16x16x32_bf16 v[138:141], v[90:93], v[178:181], 0
	v_mfma_f32_16x16x32_bf16 v[138:141], v[78:81], v[166:169], v[138:141]
	v_mfma_f32_16x16x32_bf16 v[110:113], v[78:81], v[182:185], 0
	v_mfma_f32_16x16x32_bf16 v[110:113], v[90:93], v[186:189], v[110:113]
	v_mfma_f32_16x16x32_bf16 v[106:109], v[114:117], v[186:189], 0
	v_mfma_f32_16x16x32_bf16 v[106:109], v[102:105], v[182:185], v[106:109]
	v_mfma_f32_16x16x32_bf16 v[98:101], v[126:129], v[182:185], 0
	v_mfma_f32_16x16x32_bf16 v[98:101], v[134:137], v[186:189], v[98:101]
	v_mfma_f32_16x16x32_bf16 v[94:97], v[154:157], v[186:189], 0
	v_mfma_f32_16x16x32_bf16 v[94:97], v[142:145], v[182:185], v[94:97]
	v_mfma_f32_16x16x32_bf16 v[66:69], v[142:145], v[190:193], 0
	v_mfma_f32_16x16x32_bf16 v[66:69], v[154:157], v[214:217], v[66:69]
	v_mfma_f32_16x16x32_bf16 v[74:77], v[134:137], v[214:217], 0
	v_mfma_f32_16x16x32_bf16 v[74:77], v[126:129], v[190:193], v[74:77]
	v_mfma_f32_16x16x32_bf16 v[82:85], v[102:105], v[190:193], 0
	v_mfma_f32_16x16x32_bf16 v[82:85], v[114:117], v[214:217], v[82:85]
	v_mfma_f32_16x16x32_bf16 v[86:89], v[90:93], v[214:217], 0
	v_mfma_f32_16x16x32_bf16 v[86:89], v[78:81], v[190:193], v[86:89]
	s_barrier
	s_add_i32 s0, s0, s28
	s_mov_b32 m0, s0
	ds_read_b128 v[158:161], v237 offset:16384
	ds_read_b128 v[162:165], v237 offset:17408
	ds_read_b128 v[166:169], v237 offset:18432
	ds_read_b128 v[178:181], v237 offset:19456
	ds_read_b128 v[182:185], v237 offset:20480
	ds_read_b128 v[186:189], v237 offset:21504
	ds_read_b128 v[190:193], v237 offset:22528
	ds_read_b128 v[214:217], v237 offset:23552
	global_load_lds_dwordx4 v194, s[70:71]
	s_add_i32 m0, s0, 0x2000
	s_add_u32 s0, s70, 0x80000
	s_addc_u32 s1, s71, 0
	s_add_i32 s18, s18, s28
	global_load_lds_dwordx4 v204, s[70:71]
	s_mov_b32 m0, s18
	s_nop 0
	global_load_lds_dwordx4 v194, s[0:1]
	s_add_i32 m0, s18, 0x2000
	s_nop 0
	global_load_lds_dwordx4 v204, s[0:1]
	s_mov_b32 m0, s29
	s_nop 0
	global_load_lds_dwordx4 v194, vcc
	s_mov_b32 m0, s31
	s_nop 0
	global_load_lds_dwordx4 v204, vcc
	s_waitcnt vmcnt(8)
	s_waitcnt lgkmcnt(0)
	s_barrier
	s_waitcnt lgkmcnt(0)
	v_mfma_f32_16x16x32_bf16 v[62:65], v[78:81], v[158:161], 0
	v_mfma_f32_16x16x32_bf16 v[62:65], v[90:93], v[162:165], v[62:65]
	v_mfma_f32_16x16x32_bf16 v[58:61], v[114:117], v[162:165], 0
	v_mfma_f32_16x16x32_bf16 v[58:61], v[102:105], v[158:161], v[58:61]
	v_mfma_f32_16x16x32_bf16 v[54:57], v[126:129], v[158:161], 0
	v_mfma_f32_16x16x32_bf16 v[54:57], v[134:137], v[162:165], v[54:57]
	v_mfma_f32_16x16x32_bf16 v[50:53], v[154:157], v[162:165], 0
	v_mfma_f32_16x16x32_bf16 v[50:53], v[142:145], v[158:161], v[50:53]
	v_mfma_f32_16x16x32_bf16 v[34:37], v[142:145], v[166:169], 0
	v_mfma_f32_16x16x32_bf16 v[34:37], v[154:157], v[178:181], v[34:37]
	v_mfma_f32_16x16x32_bf16 v[38:41], v[134:137], v[178:181], 0
	v_mfma_f32_16x16x32_bf16 v[38:41], v[126:129], v[166:169], v[38:41]
	v_mfma_f32_16x16x32_bf16 v[42:45], v[102:105], v[166:169], 0
	v_mfma_f32_16x16x32_bf16 v[42:45], v[114:117], v[178:181], v[42:45]
	v_mfma_f32_16x16x32_bf16 v[46:49], v[90:93], v[178:181], 0
	v_mfma_f32_16x16x32_bf16 v[46:49], v[78:81], v[166:169], v[46:49]
	v_mfma_f32_16x16x32_bf16 v[30:33], v[78:81], v[182:185], 0
	v_mfma_f32_16x16x32_bf16 v[30:33], v[90:93], v[186:189], v[30:33]
	v_mfma_f32_16x16x32_bf16 v[26:29], v[114:117], v[186:189], 0
	v_mfma_f32_16x16x32_bf16 v[26:29], v[102:105], v[182:185], v[26:29]
	v_mfma_f32_16x16x32_bf16 v[22:25], v[126:129], v[182:185], 0
	v_mfma_f32_16x16x32_bf16 v[22:25], v[134:137], v[186:189], v[22:25]
	v_mfma_f32_16x16x32_bf16 v[18:21], v[154:157], v[186:189], 0
	v_mfma_f32_16x16x32_bf16 v[18:21], v[142:145], v[182:185], v[18:21]
	v_mfma_f32_16x16x32_bf16 v[2:5], v[142:145], v[190:193], 0
	v_mfma_f32_16x16x32_bf16 v[2:5], v[154:157], v[214:217], v[2:5]
	v_mfma_f32_16x16x32_bf16 v[6:9], v[134:137], v[214:217], 0
	v_mfma_f32_16x16x32_bf16 v[6:9], v[126:129], v[190:193], v[6:9]
	v_mfma_f32_16x16x32_bf16 v[10:13], v[102:105], v[190:193], 0
	v_mfma_f32_16x16x32_bf16 v[10:13], v[114:117], v[214:217], v[10:13]
	v_mfma_f32_16x16x32_bf16 v[14:17], v[90:93], v[214:217], 0
	v_mfma_f32_16x16x32_bf16 v[14:17], v[78:81], v[190:193], v[14:17]
	s_barrier
	s_add_i32 s18, 0, 0x18000
	s_add_i32 s19, 0, 0x1c000
	v_add_u32_e32 v114, s18, v1
	v_add_u32_e32 v154, s19, v1
	ds_read_b128 v[78:81], v114
	ds_read_b128 v[90:93], v114 offset:1024
	ds_read_b128 v[102:105], v114 offset:2048
	ds_read_b128 v[114:117], v114 offset:3072
	ds_read_b128 v[126:129], v154
	ds_read_b128 v[134:137], v154 offset:1024
	ds_read_b128 v[142:145], v154 offset:2048
	ds_read_b128 v[154:157], v154 offset:3072
	s_add_u32 s0, vcc_lo, 0x80000
	s_addc_u32 s1, vcc_hi, 0
	s_mov_b32 m0, s33
	ds_read_b128 v[158:161], v237 offset:32768
	ds_read_b128 v[162:165], v237 offset:33792
	ds_read_b128 v[166:169], v237 offset:34816
	ds_read_b128 v[178:181], v237 offset:35840
	ds_read_b128 v[182:185], v237 offset:36864
	ds_read_b128 v[186:189], v237 offset:37888
	ds_read_b128 v[190:193], v237 offset:38912
	ds_read_b128 v[214:217], v237 offset:39936
	global_load_lds_dwordx4 v194, s[0:1]
	s_mov_b32 m0, s43
	s_nop 0
	global_load_lds_dwordx4 v204, s[0:1]
	s_waitcnt vmcnt(8)
	s_waitcnt lgkmcnt(0)
	s_barrier
	s_waitcnt lgkmcnt(0)
	v_mfma_f32_16x16x32_bf16 v[174:177], v[78:81], v[158:161], v[174:177]
	v_mfma_f32_16x16x32_bf16 v[174:177], v[90:93], v[162:165], v[174:177]
	v_mfma_f32_16x16x32_bf16 v[170:173], v[114:117], v[162:165], v[170:173]
	v_mfma_f32_16x16x32_bf16 v[170:173], v[102:105], v[158:161], v[170:173]
	v_mfma_f32_16x16x32_bf16 v[150:153], v[126:129], v[158:161], v[150:153]
	v_mfma_f32_16x16x32_bf16 v[150:153], v[134:137], v[162:165], v[150:153]
	v_mfma_f32_16x16x32_bf16 v[146:149], v[154:157], v[162:165], v[146:149]
	v_mfma_f32_16x16x32_bf16 v[146:149], v[142:145], v[158:161], v[146:149]
	v_mfma_f32_16x16x32_bf16 v[118:121], v[142:145], v[166:169], v[118:121]
	v_mfma_f32_16x16x32_bf16 v[118:121], v[154:157], v[178:181], v[118:121]
	v_mfma_f32_16x16x32_bf16 v[122:125], v[134:137], v[178:181], v[122:125]
	v_mfma_f32_16x16x32_bf16 v[122:125], v[126:129], v[166:169], v[122:125]
	v_mfma_f32_16x16x32_bf16 v[130:133], v[102:105], v[166:169], v[130:133]
	v_mfma_f32_16x16x32_bf16 v[130:133], v[114:117], v[178:181], v[130:133]
	v_mfma_f32_16x16x32_bf16 v[138:141], v[90:93], v[178:181], v[138:141]
	v_mfma_f32_16x16x32_bf16 v[138:141], v[78:81], v[166:169], v[138:141]
	v_mfma_f32_16x16x32_bf16 v[110:113], v[78:81], v[182:185], v[110:113]
	v_mfma_f32_16x16x32_bf16 v[110:113], v[90:93], v[186:189], v[110:113]
	v_mfma_f32_16x16x32_bf16 v[106:109], v[114:117], v[186:189], v[106:109]
	v_mfma_f32_16x16x32_bf16 v[106:109], v[102:105], v[182:185], v[106:109]
	v_mfma_f32_16x16x32_bf16 v[98:101], v[126:129], v[182:185], v[98:101]
	v_mfma_f32_16x16x32_bf16 v[98:101], v[134:137], v[186:189], v[98:101]
	v_mfma_f32_16x16x32_bf16 v[94:97], v[154:157], v[186:189], v[94:97]
	v_mfma_f32_16x16x32_bf16 v[94:97], v[142:145], v[182:185], v[94:97]
	v_mfma_f32_16x16x32_bf16 v[66:69], v[142:145], v[190:193], v[66:69]
	v_mfma_f32_16x16x32_bf16 v[66:69], v[154:157], v[214:217], v[66:69]
	v_mfma_f32_16x16x32_bf16 v[74:77], v[134:137], v[214:217], v[74:77]
	v_mfma_f32_16x16x32_bf16 v[74:77], v[126:129], v[190:193], v[74:77]
	v_mfma_f32_16x16x32_bf16 v[82:85], v[102:105], v[190:193], v[82:85]
	v_mfma_f32_16x16x32_bf16 v[82:85], v[114:117], v[214:217], v[82:85]
	v_mfma_f32_16x16x32_bf16 v[86:89], v[90:93], v[214:217], v[86:89]
	v_mfma_f32_16x16x32_bf16 v[86:89], v[78:81], v[190:193], v[86:89]
	s_barrier
	s_add_u32 s98, s70, 0x80
	s_addc_u32 s99, s71, 0
	s_add_u32 s100, vcc_lo, 0x80
	s_addc_u32 s101, vcc_hi, 0
	s_add_i32 s0, s18, s28
	s_mov_b32 m0, s0
	ds_read_b128 v[158:161], v237 offset:49152
	ds_read_b128 v[162:165], v237 offset:50176
	ds_read_b128 v[166:169], v237 offset:51200
	ds_read_b128 v[178:181], v237 offset:52224
	ds_read_b128 v[182:185], v237 offset:53248
	ds_read_b128 v[186:189], v237 offset:54272
	ds_read_b128 v[190:193], v237 offset:55296
	ds_read_b128 v[214:217], v237 offset:56320
	global_load_lds_dwordx4 v194, s[98:99]
	s_add_i32 m0, s0, 0x2000
	s_add_u32 s0, s70, 0x80080
	s_addc_u32 s1, s71, 0
	s_add_i32 s18, s19, s28
	global_load_lds_dwordx4 v204, s[98:99]
	s_mov_b32 m0, s18
	s_nop 0
	global_load_lds_dwordx4 v194, s[0:1]
	s_add_i32 m0, s18, 0x2000
	s_nop 0
	global_load_lds_dwordx4 v204, s[0:1]
	s_mov_b32 m0, s68
	s_nop 0
	global_load_lds_dwordx4 v194, s[100:101]
	s_mov_b32 m0, s79
	s_nop 0
	global_load_lds_dwordx4 v204, s[100:101]
	s_waitcnt vmcnt(8)
	s_waitcnt lgkmcnt(0)
	s_barrier
	s_waitcnt lgkmcnt(0)
	v_mfma_f32_16x16x32_bf16 v[62:65], v[78:81], v[158:161], v[62:65]
	v_mfma_f32_16x16x32_bf16 v[62:65], v[90:93], v[162:165], v[62:65]
	v_mfma_f32_16x16x32_bf16 v[58:61], v[114:117], v[162:165], v[58:61]
	v_mfma_f32_16x16x32_bf16 v[58:61], v[102:105], v[158:161], v[58:61]
	v_mfma_f32_16x16x32_bf16 v[54:57], v[126:129], v[158:161], v[54:57]
	v_mfma_f32_16x16x32_bf16 v[54:57], v[134:137], v[162:165], v[54:57]
	v_mfma_f32_16x16x32_bf16 v[50:53], v[154:157], v[162:165], v[50:53]
	v_mfma_f32_16x16x32_bf16 v[50:53], v[142:145], v[158:161], v[50:53]
	v_mfma_f32_16x16x32_bf16 v[34:37], v[142:145], v[166:169], v[34:37]
	v_mfma_f32_16x16x32_bf16 v[34:37], v[154:157], v[178:181], v[34:37]
	v_mfma_f32_16x16x32_bf16 v[38:41], v[134:137], v[178:181], v[38:41]
	v_mfma_f32_16x16x32_bf16 v[38:41], v[126:129], v[166:169], v[38:41]
	v_mfma_f32_16x16x32_bf16 v[42:45], v[102:105], v[166:169], v[42:45]
	v_mfma_f32_16x16x32_bf16 v[42:45], v[114:117], v[178:181], v[42:45]
	v_mfma_f32_16x16x32_bf16 v[46:49], v[90:93], v[178:181], v[46:49]
	v_mfma_f32_16x16x32_bf16 v[46:49], v[78:81], v[166:169], v[46:49]
	v_mfma_f32_16x16x32_bf16 v[30:33], v[78:81], v[182:185], v[30:33]
	v_mfma_f32_16x16x32_bf16 v[30:33], v[90:93], v[186:189], v[30:33]
	v_mfma_f32_16x16x32_bf16 v[26:29], v[114:117], v[186:189], v[26:29]
	v_mfma_f32_16x16x32_bf16 v[26:29], v[102:105], v[182:185], v[26:29]
	v_mfma_f32_16x16x32_bf16 v[22:25], v[126:129], v[182:185], v[22:25]
	v_mfma_f32_16x16x32_bf16 v[22:25], v[134:137], v[186:189], v[22:25]
	v_mfma_f32_16x16x32_bf16 v[18:21], v[154:157], v[186:189], v[18:21]
	v_mfma_f32_16x16x32_bf16 v[18:21], v[142:145], v[182:185], v[18:21]
	v_mfma_f32_16x16x32_bf16 v[2:5], v[142:145], v[190:193], v[2:5]
	v_mfma_f32_16x16x32_bf16 v[2:5], v[154:157], v[214:217], v[2:5]
	v_mfma_f32_16x16x32_bf16 v[6:9], v[134:137], v[214:217], v[6:9]
	v_mfma_f32_16x16x32_bf16 v[6:9], v[126:129], v[190:193], v[6:9]
	v_mfma_f32_16x16x32_bf16 v[10:13], v[102:105], v[190:193], v[10:13]
	v_mfma_f32_16x16x32_bf16 v[10:13], v[114:117], v[214:217], v[10:13]
	v_mfma_f32_16x16x32_bf16 v[14:17], v[90:93], v[214:217], v[14:17]
	v_mfma_f32_16x16x32_bf16 v[14:17], v[78:81], v[190:193], v[14:17]
	s_barrier
	s_add_i32 s57, s57, 2
	s_add_u32 s51, s51, 0x100
	s_addc_u32 s53, s53, 0
	s_cmp_gt_u32 s57, 29
	s_mov_b64 s[76:77], s[90:91]
	s_cbranch_scc1 .LBB0_512
	s_branch .LBB0_510

.LBB0_581:
	s_add_u32 s18, s62, 0xfff80080
	s_addc_u32 s19, s63, -1
	s_and_b64 s[0:1], s[64:65], exec
	s_cselect_b32 s71, s22, s19
	s_cselect_b32 s70, s23, s18
	s_cselect_b32 s65, s39, s58
	s_cselect_b32 s64, s47, s53
	s_add_i32 s0, 0, 0x10000
	v_add_u32_e32 v153, s0, v1
	s_add_i32 s18, 0, 0x14000
	ds_read_b128 v[144:147], v153
	ds_read_b128 v[148:151], v153 offset:1024
	ds_read_b128 v[154:157], v153 offset:2048
	ds_read_b128 v[158:161], v153 offset:3072
	v_add_u32_e32 v153, s18, v1
	ds_read_b128 v[162:165], v153
	ds_read_b128 v[166:169], v153 offset:1024
	ds_read_b128 v[170:173], v153 offset:2048
	ds_read_b128 v[174:177], v153 offset:3072
	s_add_i32 m0, s29, 0xc000
	ds_read_b128 v[178:181], v152
	ds_read_b128 v[182:185], v152 offset:1024
	ds_read_b128 v[186:189], v152 offset:2048
	ds_read_b128 v[190:193], v152 offset:3072
	ds_read_b128 v[204:207], v152 offset:4096
	ds_read_b128 v[208:211], v152 offset:5120
	ds_read_b128 v[212:215], v152 offset:6144
	ds_read_b128 v[216:219], v152 offset:7168
	global_load_lds_dwordx4 v136, s[62:63]
	s_add_i32 m0, s29, 0xe000
	s_nop 0
	global_load_lds_dwordx4 v138, s[62:63]
	s_waitcnt vmcnt(8)
	s_waitcnt lgkmcnt(0)
	s_barrier
	s_waitcnt lgkmcnt(0)
	v_mfma_f32_16x16x32_bf16 v[126:129], v[144:147], v[178:181], v[126:129]
	v_mfma_f32_16x16x32_bf16 v[126:129], v[148:151], v[182:185], v[126:129]
	v_mfma_f32_16x16x32_bf16 v[122:125], v[158:161], v[182:185], v[122:125]
	v_mfma_f32_16x16x32_bf16 v[122:125], v[154:157], v[178:181], v[122:125]
	v_mfma_f32_16x16x32_bf16 v[118:121], v[162:165], v[178:181], v[118:121]
	v_mfma_f32_16x16x32_bf16 v[118:121], v[166:169], v[182:185], v[118:121]
	v_mfma_f32_16x16x32_bf16 v[114:117], v[174:177], v[182:185], v[114:117]
	v_mfma_f32_16x16x32_bf16 v[114:117], v[170:173], v[178:181], v[114:117]
	v_mfma_f32_16x16x32_bf16 v[98:101], v[170:173], v[186:189], v[98:101]
	v_mfma_f32_16x16x32_bf16 v[98:101], v[174:177], v[190:193], v[98:101]
	v_mfma_f32_16x16x32_bf16 v[102:105], v[166:169], v[190:193], v[102:105]
	v_mfma_f32_16x16x32_bf16 v[102:105], v[162:165], v[186:189], v[102:105]
	v_mfma_f32_16x16x32_bf16 v[106:109], v[154:157], v[186:189], v[106:109]
	v_mfma_f32_16x16x32_bf16 v[106:109], v[158:161], v[190:193], v[106:109]
	v_mfma_f32_16x16x32_bf16 v[110:113], v[148:151], v[190:193], v[110:113]
	v_mfma_f32_16x16x32_bf16 v[110:113], v[144:147], v[186:189], v[110:113]
	v_mfma_f32_16x16x32_bf16 v[94:97], v[144:147], v[204:207], v[94:97]
	v_mfma_f32_16x16x32_bf16 v[94:97], v[148:151], v[208:211], v[94:97]
	v_mfma_f32_16x16x32_bf16 v[90:93], v[158:161], v[208:211], v[90:93]
	v_mfma_f32_16x16x32_bf16 v[90:93], v[154:157], v[204:207], v[90:93]
	v_mfma_f32_16x16x32_bf16 v[86:89], v[162:165], v[204:207], v[86:89]
	v_mfma_f32_16x16x32_bf16 v[86:89], v[166:169], v[208:211], v[86:89]
	v_mfma_f32_16x16x32_bf16 v[82:85], v[174:177], v[208:211], v[82:85]
	v_mfma_f32_16x16x32_bf16 v[82:85], v[170:173], v[204:207], v[82:85]
	v_mfma_f32_16x16x32_bf16 v[66:69], v[170:173], v[212:215], v[66:69]
	v_mfma_f32_16x16x32_bf16 v[66:69], v[174:177], v[216:219], v[66:69]
	v_mfma_f32_16x16x32_bf16 v[70:73], v[166:169], v[216:219], v[70:73]
	v_mfma_f32_16x16x32_bf16 v[70:73], v[162:165], v[212:215], v[70:73]
	v_mfma_f32_16x16x32_bf16 v[74:77], v[154:157], v[212:215], v[74:77]
	v_mfma_f32_16x16x32_bf16 v[74:77], v[158:161], v[216:219], v[74:77]
	v_mfma_f32_16x16x32_bf16 v[78:81], v[148:151], v[216:219], v[78:81]
	v_mfma_f32_16x16x32_bf16 v[78:81], v[144:147], v[212:215], v[78:81]
	s_barrier
	s_add_i32 s0, s0, s28
	s_mov_b32 m0, s0
	ds_read_b128 v[178:181], v152 offset:16384
	ds_read_b128 v[182:185], v152 offset:17408
	ds_read_b128 v[186:189], v152 offset:18432
	ds_read_b128 v[190:193], v152 offset:19456
	ds_read_b128 v[204:207], v152 offset:20480
	ds_read_b128 v[208:211], v152 offset:21504
	ds_read_b128 v[212:215], v152 offset:22528
	ds_read_b128 v[216:219], v152 offset:23552
	global_load_lds_dwordx4 v194, s[64:65]
	s_add_i32 m0, s0, 0x2000
	s_add_u32 s0, s64, 0x80000
	s_addc_u32 s1, s65, 0
	s_add_i32 s18, s18, s28
	global_load_lds_dwordx4 v130, s[64:65]
	s_mov_b32 m0, s18
	s_nop 0
	global_load_lds_dwordx4 v194, s[0:1]
	s_add_i32 m0, s18, 0x2000
	s_nop 0
	global_load_lds_dwordx4 v130, s[0:1]
	s_mov_b32 m0, s29
	s_nop 0
	global_load_lds_dwordx4 v194, s[70:71]
	s_mov_b32 m0, s31
	s_nop 0
	global_load_lds_dwordx4 v130, s[70:71]
	s_waitcnt vmcnt(8)
	s_waitcnt lgkmcnt(0)
	s_barrier
	s_waitcnt lgkmcnt(0)
	v_mfma_f32_16x16x32_bf16 v[62:65], v[144:147], v[178:181], v[62:65]
	v_mfma_f32_16x16x32_bf16 v[62:65], v[148:151], v[182:185], v[62:65]
	v_mfma_f32_16x16x32_bf16 v[58:61], v[158:161], v[182:185], v[58:61]
	v_mfma_f32_16x16x32_bf16 v[58:61], v[154:157], v[178:181], v[58:61]
	v_mfma_f32_16x16x32_bf16 v[54:57], v[162:165], v[178:181], v[54:57]
	v_mfma_f32_16x16x32_bf16 v[54:57], v[166:169], v[182:185], v[54:57]
	v_mfma_f32_16x16x32_bf16 v[50:53], v[174:177], v[182:185], v[50:53]
	v_mfma_f32_16x16x32_bf16 v[50:53], v[170:173], v[178:181], v[50:53]
	v_mfma_f32_16x16x32_bf16 v[34:37], v[170:173], v[186:189], v[34:37]
	v_mfma_f32_16x16x32_bf16 v[34:37], v[174:177], v[190:193], v[34:37]
	v_mfma_f32_16x16x32_bf16 v[38:41], v[166:169], v[190:193], v[38:41]
	v_mfma_f32_16x16x32_bf16 v[38:41], v[162:165], v[186:189], v[38:41]
	v_mfma_f32_16x16x32_bf16 v[42:45], v[154:157], v[186:189], v[42:45]
	v_mfma_f32_16x16x32_bf16 v[42:45], v[158:161], v[190:193], v[42:45]
	v_mfma_f32_16x16x32_bf16 v[46:49], v[148:151], v[190:193], v[46:49]
	v_mfma_f32_16x16x32_bf16 v[46:49], v[144:147], v[186:189], v[46:49]
	v_mfma_f32_16x16x32_bf16 v[30:33], v[144:147], v[204:207], v[30:33]
	v_mfma_f32_16x16x32_bf16 v[30:33], v[148:151], v[208:211], v[30:33]
	v_mfma_f32_16x16x32_bf16 v[26:29], v[158:161], v[208:211], v[26:29]
	v_mfma_f32_16x16x32_bf16 v[26:29], v[154:157], v[204:207], v[26:29]
	v_mfma_f32_16x16x32_bf16 v[22:25], v[162:165], v[204:207], v[22:25]
	v_mfma_f32_16x16x32_bf16 v[22:25], v[166:169], v[208:211], v[22:25]
	v_mfma_f32_16x16x32_bf16 v[18:21], v[174:177], v[208:211], v[18:21]
	v_mfma_f32_16x16x32_bf16 v[18:21], v[170:173], v[204:207], v[18:21]
	v_mfma_f32_16x16x32_bf16 v[2:5], v[170:173], v[212:215], v[2:5]
	v_mfma_f32_16x16x32_bf16 v[2:5], v[174:177], v[216:219], v[2:5]
	v_mfma_f32_16x16x32_bf16 v[6:9], v[166:169], v[216:219], v[6:9]
	v_mfma_f32_16x16x32_bf16 v[6:9], v[162:165], v[212:215], v[6:9]
	v_mfma_f32_16x16x32_bf16 v[10:13], v[154:157], v[212:215], v[10:13]
	v_mfma_f32_16x16x32_bf16 v[10:13], v[158:161], v[216:219], v[10:13]
	v_mfma_f32_16x16x32_bf16 v[14:17], v[148:151], v[216:219], v[14:17]
	v_mfma_f32_16x16x32_bf16 v[14:17], v[144:147], v[212:215], v[14:17]
	s_barrier
	s_add_i32 s18, 0, 0x18000
	v_add_u32_e32 v153, s18, v1
	s_add_i32 s19, 0, 0x1c000
	ds_read_b128 v[144:147], v153
	ds_read_b128 v[148:151], v153 offset:1024
	ds_read_b128 v[154:157], v153 offset:2048
	ds_read_b128 v[158:161], v153 offset:3072
	v_add_u32_e32 v153, s19, v1
	ds_read_b128 v[162:165], v153
	ds_read_b128 v[166:169], v153 offset:1024
	ds_read_b128 v[170:173], v153 offset:2048
	ds_read_b128 v[174:177], v153 offset:3072
	s_add_u32 s0, s70, 0x80000
	s_addc_u32 s1, s71, 0
	s_mov_b32 m0, s33
	ds_read_b128 v[178:181], v152 offset:32768
	ds_read_b128 v[182:185], v152 offset:33792
	ds_read_b128 v[186:189], v152 offset:34816
	ds_read_b128 v[190:193], v152 offset:35840
	ds_read_b128 v[204:207], v152 offset:36864
	ds_read_b128 v[208:211], v152 offset:37888
	ds_read_b128 v[212:215], v152 offset:38912
	ds_read_b128 v[216:219], v152 offset:39936
	global_load_lds_dwordx4 v194, s[0:1]
	s_mov_b32 m0, s40
	s_nop 0
	global_load_lds_dwordx4 v130, s[0:1]
	s_waitcnt vmcnt(8)
	s_waitcnt lgkmcnt(0)
	s_barrier
	s_waitcnt lgkmcnt(0)
	v_mfma_f32_16x16x32_bf16 v[126:129], v[144:147], v[178:181], v[126:129]
	v_mfma_f32_16x16x32_bf16 v[126:129], v[148:151], v[182:185], v[126:129]
	v_mfma_f32_16x16x32_bf16 v[122:125], v[158:161], v[182:185], v[122:125]
	v_mfma_f32_16x16x32_bf16 v[122:125], v[154:157], v[178:181], v[122:125]
	v_mfma_f32_16x16x32_bf16 v[118:121], v[162:165], v[178:181], v[118:121]
	v_mfma_f32_16x16x32_bf16 v[118:121], v[166:169], v[182:185], v[118:121]
	v_mfma_f32_16x16x32_bf16 v[114:117], v[174:177], v[182:185], v[114:117]
	v_mfma_f32_16x16x32_bf16 v[114:117], v[170:173], v[178:181], v[114:117]
	v_mfma_f32_16x16x32_bf16 v[98:101], v[170:173], v[186:189], v[98:101]
	v_mfma_f32_16x16x32_bf16 v[98:101], v[174:177], v[190:193], v[98:101]
	v_mfma_f32_16x16x32_bf16 v[102:105], v[166:169], v[190:193], v[102:105]
	v_mfma_f32_16x16x32_bf16 v[102:105], v[162:165], v[186:189], v[102:105]
	v_mfma_f32_16x16x32_bf16 v[106:109], v[154:157], v[186:189], v[106:109]
	v_mfma_f32_16x16x32_bf16 v[106:109], v[158:161], v[190:193], v[106:109]
	v_mfma_f32_16x16x32_bf16 v[110:113], v[148:151], v[190:193], v[110:113]
	v_mfma_f32_16x16x32_bf16 v[110:113], v[144:147], v[186:189], v[110:113]
	v_mfma_f32_16x16x32_bf16 v[94:97], v[144:147], v[204:207], v[94:97]
	v_mfma_f32_16x16x32_bf16 v[94:97], v[148:151], v[208:211], v[94:97]
	v_mfma_f32_16x16x32_bf16 v[90:93], v[158:161], v[208:211], v[90:93]
	v_mfma_f32_16x16x32_bf16 v[90:93], v[154:157], v[204:207], v[90:93]
	v_mfma_f32_16x16x32_bf16 v[86:89], v[162:165], v[204:207], v[86:89]
	v_mfma_f32_16x16x32_bf16 v[86:89], v[166:169], v[208:211], v[86:89]
	v_mfma_f32_16x16x32_bf16 v[82:85], v[174:177], v[208:211], v[82:85]
	v_mfma_f32_16x16x32_bf16 v[82:85], v[170:173], v[204:207], v[82:85]
	v_mfma_f32_16x16x32_bf16 v[66:69], v[170:173], v[212:215], v[66:69]
	v_mfma_f32_16x16x32_bf16 v[66:69], v[174:177], v[216:219], v[66:69]
	v_mfma_f32_16x16x32_bf16 v[70:73], v[166:169], v[216:219], v[70:73]
	v_mfma_f32_16x16x32_bf16 v[70:73], v[162:165], v[212:215], v[70:73]
	v_mfma_f32_16x16x32_bf16 v[74:77], v[154:157], v[212:215], v[74:77]
	v_mfma_f32_16x16x32_bf16 v[74:77], v[158:161], v[216:219], v[74:77]
	v_mfma_f32_16x16x32_bf16 v[78:81], v[148:151], v[216:219], v[78:81]
	v_mfma_f32_16x16x32_bf16 v[78:81], v[144:147], v[212:215], v[78:81]
	s_barrier
	s_add_u32 s98, s64, 0x80
	s_addc_u32 s99, s65, 0
	s_add_u32 s100, s70, 0x80
	s_addc_u32 s101, s71, 0
	s_add_i32 s0, s18, s28
	s_mov_b32 m0, s0
	ds_read_b128 v[178:181], v152 offset:49152
	ds_read_b128 v[182:185], v152 offset:50176
	ds_read_b128 v[186:189], v152 offset:51200
	ds_read_b128 v[190:193], v152 offset:52224
	ds_read_b128 v[204:207], v152 offset:53248
	ds_read_b128 v[208:211], v152 offset:54272
	ds_read_b128 v[212:215], v152 offset:55296
	ds_read_b128 v[216:219], v152 offset:56320
	global_load_lds_dwordx4 v194, s[98:99]
	s_add_i32 m0, s0, 0x2000
	s_add_u32 s0, s64, 0x80080
	s_addc_u32 s1, s65, 0
	s_add_i32 s18, s19, s28
	global_load_lds_dwordx4 v130, s[98:99]
	s_mov_b32 m0, s18
	s_nop 0
	global_load_lds_dwordx4 v194, s[0:1]
	s_add_i32 m0, s18, 0x2000
	s_nop 0
	global_load_lds_dwordx4 v130, s[0:1]
	s_mov_b32 m0, s54
	s_nop 0
	global_load_lds_dwordx4 v194, s[100:101]
	s_mov_b32 m0, s57
	s_nop 0
	global_load_lds_dwordx4 v130, s[100:101]
	s_waitcnt vmcnt(8)
	s_waitcnt lgkmcnt(0)
	s_barrier
	s_waitcnt lgkmcnt(0)
	v_mfma_f32_16x16x32_bf16 v[62:65], v[144:147], v[178:181], v[62:65]
	v_mfma_f32_16x16x32_bf16 v[62:65], v[148:151], v[182:185], v[62:65]
	v_mfma_f32_16x16x32_bf16 v[58:61], v[158:161], v[182:185], v[58:61]
	v_mfma_f32_16x16x32_bf16 v[58:61], v[154:157], v[178:181], v[58:61]
	v_mfma_f32_16x16x32_bf16 v[54:57], v[162:165], v[178:181], v[54:57]
	v_mfma_f32_16x16x32_bf16 v[54:57], v[166:169], v[182:185], v[54:57]
	v_mfma_f32_16x16x32_bf16 v[50:53], v[174:177], v[182:185], v[50:53]
	v_mfma_f32_16x16x32_bf16 v[50:53], v[170:173], v[178:181], v[50:53]
	v_mfma_f32_16x16x32_bf16 v[34:37], v[170:173], v[186:189], v[34:37]
	v_mfma_f32_16x16x32_bf16 v[34:37], v[174:177], v[190:193], v[34:37]
	v_mfma_f32_16x16x32_bf16 v[38:41], v[166:169], v[190:193], v[38:41]
	v_mfma_f32_16x16x32_bf16 v[38:41], v[162:165], v[186:189], v[38:41]
	v_mfma_f32_16x16x32_bf16 v[42:45], v[154:157], v[186:189], v[42:45]
	v_mfma_f32_16x16x32_bf16 v[42:45], v[158:161], v[190:193], v[42:45]
	v_mfma_f32_16x16x32_bf16 v[46:49], v[148:151], v[190:193], v[46:49]
	v_mfma_f32_16x16x32_bf16 v[46:49], v[144:147], v[186:189], v[46:49]
	v_mfma_f32_16x16x32_bf16 v[30:33], v[144:147], v[204:207], v[30:33]
	v_mfma_f32_16x16x32_bf16 v[30:33], v[148:151], v[208:211], v[30:33]
	v_mfma_f32_16x16x32_bf16 v[26:29], v[158:161], v[208:211], v[26:29]
	v_mfma_f32_16x16x32_bf16 v[26:29], v[154:157], v[204:207], v[26:29]
	v_mfma_f32_16x16x32_bf16 v[22:25], v[162:165], v[204:207], v[22:25]
	v_mfma_f32_16x16x32_bf16 v[22:25], v[166:169], v[208:211], v[22:25]
	v_mfma_f32_16x16x32_bf16 v[18:21], v[174:177], v[208:211], v[18:21]
	v_mfma_f32_16x16x32_bf16 v[18:21], v[170:173], v[204:207], v[18:21]
	v_mfma_f32_16x16x32_bf16 v[2:5], v[170:173], v[212:215], v[2:5]
	v_mfma_f32_16x16x32_bf16 v[2:5], v[174:177], v[216:219], v[2:5]
	v_mfma_f32_16x16x32_bf16 v[6:9], v[166:169], v[216:219], v[6:9]
	v_mfma_f32_16x16x32_bf16 v[6:9], v[162:165], v[212:215], v[6:9]
	v_mfma_f32_16x16x32_bf16 v[10:13], v[154:157], v[212:215], v[10:13]
	v_mfma_f32_16x16x32_bf16 v[10:13], v[158:161], v[216:219], v[10:13]
	v_mfma_f32_16x16x32_bf16 v[14:17], v[148:151], v[216:219], v[14:17]
	v_mfma_f32_16x16x32_bf16 v[14:17], v[144:147], v[212:215], v[14:17]
	s_barrier
	s_add_i32 s76, s76, 2
	s_add_u32 s62, s62, 0x100
	s_addc_u32 s63, s63, 0
	s_add_u32 s53, s53, 0x100
	s_addc_u32 s58, s58, 0
	s_cmp_gt_u32 s76, 29
	s_cbranch_scc1 .LBB0_584

.Lpeel_disp_gu:
	s_cmp_lg_u32 s76, -2
	s_cbranch_scc1 .LBB0_581
	s_add_u32 s18, s62, 0xfff80080
	s_addc_u32 s19, s63, -1
	s_and_b64 s[0:1], s[64:65], exec
	s_cselect_b32 s71, s22, s19
	s_cselect_b32 s70, s23, s18
	s_cselect_b32 s65, s39, s58
	s_cselect_b32 s64, s47, s53
	s_add_i32 s0, 0, 0x10000
	v_add_u32_e32 v153, s0, v1
	s_add_i32 s18, 0, 0x14000
	ds_read_b128 v[144:147], v153
	ds_read_b128 v[148:151], v153 offset:1024
	ds_read_b128 v[154:157], v153 offset:2048
	ds_read_b128 v[158:161], v153 offset:3072
	v_add_u32_e32 v153, s18, v1
	ds_read_b128 v[162:165], v153
	ds_read_b128 v[166:169], v153 offset:1024
	ds_read_b128 v[170:173], v153 offset:2048
	ds_read_b128 v[174:177], v153 offset:3072
	s_add_i32 m0, s29, 0xc000
	ds_read_b128 v[178:181], v152
	ds_read_b128 v[182:185], v152 offset:1024
	ds_read_b128 v[186:189], v152 offset:2048
	ds_read_b128 v[190:193], v152 offset:3072
	ds_read_b128 v[204:207], v152 offset:4096
	ds_read_b128 v[208:211], v152 offset:5120
	ds_read_b128 v[212:215], v152 offset:6144
	ds_read_b128 v[216:219], v152 offset:7168
	global_load_lds_dwordx4 v136, s[62:63]
	s_add_i32 m0, s29, 0xe000
	s_nop 0
	global_load_lds_dwordx4 v138, s[62:63]
	s_waitcnt vmcnt(8)
	s_waitcnt lgkmcnt(0)
	s_barrier
	s_waitcnt lgkmcnt(0)
	v_mfma_f32_16x16x32_bf16 v[126:129], v[144:147], v[178:181], 0
	v_mfma_f32_16x16x32_bf16 v[126:129], v[148:151], v[182:185], v[126:129]
	v_mfma_f32_16x16x32_bf16 v[122:125], v[158:161], v[182:185], 0
	v_mfma_f32_16x16x32_bf16 v[122:125], v[154:157], v[178:181], v[122:125]
	v_mfma_f32_16x16x32_bf16 v[118:121], v[162:165], v[178:181], 0
	v_mfma_f32_16x16x32_bf16 v[118:121], v[166:169], v[182:185], v[118:121]
	v_mfma_f32_16x16x32_bf16 v[114:117], v[174:177], v[182:185], 0
	v_mfma_f32_16x16x32_bf16 v[114:117], v[170:173], v[178:181], v[114:117]
	v_mfma_f32_16x16x32_bf16 v[98:101], v[170:173], v[186:189], 0
	v_mfma_f32_16x16x32_bf16 v[98:101], v[174:177], v[190:193], v[98:101]
	v_mfma_f32_16x16x32_bf16 v[102:105], v[166:169], v[190:193], 0
	v_mfma_f32_16x16x32_bf16 v[102:105], v[162:165], v[186:189], v[102:105]
	v_mfma_f32_16x16x32_bf16 v[106:109], v[154:157], v[186:189], 0
	v_mfma_f32_16x16x32_bf16 v[106:109], v[158:161], v[190:193], v[106:109]
	v_mfma_f32_16x16x32_bf16 v[110:113], v[148:151], v[190:193], 0
	v_mfma_f32_16x16x32_bf16 v[110:113], v[144:147], v[186:189], v[110:113]
	v_mfma_f32_16x16x32_bf16 v[94:97], v[144:147], v[204:207], 0
	v_mfma_f32_16x16x32_bf16 v[94:97], v[148:151], v[208:211], v[94:97]
	v_mfma_f32_16x16x32_bf16 v[90:93], v[158:161], v[208:211], 0
	v_mfma_f32_16x16x32_bf16 v[90:93], v[154:157], v[204:207], v[90:93]
	v_mfma_f32_16x16x32_bf16 v[86:89], v[162:165], v[204:207], 0
	v_mfma_f32_16x16x32_bf16 v[86:89], v[166:169], v[208:211], v[86:89]
	v_mfma_f32_16x16x32_bf16 v[82:85], v[174:177], v[208:211], 0
	v_mfma_f32_16x16x32_bf16 v[82:85], v[170:173], v[204:207], v[82:85]
	v_mfma_f32_16x16x32_bf16 v[66:69], v[170:173], v[212:215], 0
	v_mfma_f32_16x16x32_bf16 v[66:69], v[174:177], v[216:219], v[66:69]
	v_mfma_f32_16x16x32_bf16 v[70:73], v[166:169], v[216:219], 0
	v_mfma_f32_16x16x32_bf16 v[70:73], v[162:165], v[212:215], v[70:73]
	v_mfma_f32_16x16x32_bf16 v[74:77], v[154:157], v[212:215], 0
	v_mfma_f32_16x16x32_bf16 v[74:77], v[158:161], v[216:219], v[74:77]
	v_mfma_f32_16x16x32_bf16 v[78:81], v[148:151], v[216:219], 0
	v_mfma_f32_16x16x32_bf16 v[78:81], v[144:147], v[212:215], v[78:81]
	s_barrier
	s_add_i32 s0, s0, s28
	s_mov_b32 m0, s0
	ds_read_b128 v[178:181], v152 offset:16384
	ds_read_b128 v[182:185], v152 offset:17408
	ds_read_b128 v[186:189], v152 offset:18432
	ds_read_b128 v[190:193], v152 offset:19456
	ds_read_b128 v[204:207], v152 offset:20480
	ds_read_b128 v[208:211], v152 offset:21504
	ds_read_b128 v[212:215], v152 offset:22528
	ds_read_b128 v[216:219], v152 offset:23552
	global_load_lds_dwordx4 v194, s[64:65]
	s_add_i32 m0, s0, 0x2000
	s_add_u32 s0, s64, 0x80000
	s_addc_u32 s1, s65, 0
	s_add_i32 s18, s18, s28
	global_load_lds_dwordx4 v130, s[64:65]
	s_mov_b32 m0, s18
	s_nop 0
	global_load_lds_dwordx4 v194, s[0:1]
	s_add_i32 m0, s18, 0x2000
	s_nop 0
	global_load_lds_dwordx4 v130, s[0:1]
	s_mov_b32 m0, s29
	s_nop 0
	global_load_lds_dwordx4 v194, s[70:71]
	s_mov_b32 m0, s31
	s_nop 0
	global_load_lds_dwordx4 v130, s[70:71]
	s_waitcnt vmcnt(8)
	s_waitcnt lgkmcnt(0)
	s_barrier
	s_waitcnt lgkmcnt(0)
	v_mfma_f32_16x16x32_bf16 v[62:65], v[144:147], v[178:181], 0
	v_mfma_f32_16x16x32_bf16 v[62:65], v[148:151], v[182:185], v[62:65]
	v_mfma_f32_16x16x32_bf16 v[58:61], v[158:161], v[182:185], 0
	v_mfma_f32_16x16x32_bf16 v[58:61], v[154:157], v[178:181], v[58:61]
	v_mfma_f32_16x16x32_bf16 v[54:57], v[162:165], v[178:181], 0
	v_mfma_f32_16x16x32_bf16 v[54:57], v[166:169], v[182:185], v[54:57]
	v_mfma_f32_16x16x32_bf16 v[50:53], v[174:177], v[182:185], 0
	v_mfma_f32_16x16x32_bf16 v[50:53], v[170:173], v[178:181], v[50:53]
	v_mfma_f32_16x16x32_bf16 v[34:37], v[170:173], v[186:189], 0
	v_mfma_f32_16x16x32_bf16 v[34:37], v[174:177], v[190:193], v[34:37]
	v_mfma_f32_16x16x32_bf16 v[38:41], v[166:169], v[190:193], 0
	v_mfma_f32_16x16x32_bf16 v[38:41], v[162:165], v[186:189], v[38:41]
	v_mfma_f32_16x16x32_bf16 v[42:45], v[154:157], v[186:189], 0
	v_mfma_f32_16x16x32_bf16 v[42:45], v[158:161], v[190:193], v[42:45]
	v_mfma_f32_16x16x32_bf16 v[46:49], v[148:151], v[190:193], 0
	v_mfma_f32_16x16x32_bf16 v[46:49], v[144:147], v[186:189], v[46:49]
	v_mfma_f32_16x16x32_bf16 v[30:33], v[144:147], v[204:207], 0
	v_mfma_f32_16x16x32_bf16 v[30:33], v[148:151], v[208:211], v[30:33]
	v_mfma_f32_16x16x32_bf16 v[26:29], v[158:161], v[208:211], 0
	v_mfma_f32_16x16x32_bf16 v[26:29], v[154:157], v[204:207], v[26:29]
	v_mfma_f32_16x16x32_bf16 v[22:25], v[162:165], v[204:207], 0
	v_mfma_f32_16x16x32_bf16 v[22:25], v[166:169], v[208:211], v[22:25]
	v_mfma_f32_16x16x32_bf16 v[18:21], v[174:177], v[208:211], 0
	v_mfma_f32_16x16x32_bf16 v[18:21], v[170:173], v[204:207], v[18:21]
	v_mfma_f32_16x16x32_bf16 v[2:5], v[170:173], v[212:215], 0
	v_mfma_f32_16x16x32_bf16 v[2:5], v[174:177], v[216:219], v[2:5]
	v_mfma_f32_16x16x32_bf16 v[6:9], v[166:169], v[216:219], 0
	v_mfma_f32_16x16x32_bf16 v[6:9], v[162:165], v[212:215], v[6:9]
	v_mfma_f32_16x16x32_bf16 v[10:13], v[154:157], v[212:215], 0
	v_mfma_f32_16x16x32_bf16 v[10:13], v[158:161], v[216:219], v[10:13]
	v_mfma_f32_16x16x32_bf16 v[14:17], v[148:151], v[216:219], 0
	v_mfma_f32_16x16x32_bf16 v[14:17], v[144:147], v[212:215], v[14:17]
	s_barrier
	s_add_i32 s18, 0, 0x18000
	v_add_u32_e32 v153, s18, v1
	s_add_i32 s19, 0, 0x1c000
	ds_read_b128 v[144:147], v153
	ds_read_b128 v[148:151], v153 offset:1024
	ds_read_b128 v[154:157], v153 offset:2048
	ds_read_b128 v[158:161], v153 offset:3072
	v_add_u32_e32 v153, s19, v1
	ds_read_b128 v[162:165], v153
	ds_read_b128 v[166:169], v153 offset:1024
	ds_read_b128 v[170:173], v153 offset:2048
	ds_read_b128 v[174:177], v153 offset:3072
	s_add_u32 s0, s70, 0x80000
	s_addc_u32 s1, s71, 0
	s_mov_b32 m0, s33
	ds_read_b128 v[178:181], v152 offset:32768
	ds_read_b128 v[182:185], v152 offset:33792
	ds_read_b128 v[186:189], v152 offset:34816
	ds_read_b128 v[190:193], v152 offset:35840
	ds_read_b128 v[204:207], v152 offset:36864
	ds_read_b128 v[208:211], v152 offset:37888
	ds_read_b128 v[212:215], v152 offset:38912
	ds_read_b128 v[216:219], v152 offset:39936
	global_load_lds_dwordx4 v194, s[0:1]
	s_mov_b32 m0, s40
	s_nop 0
	global_load_lds_dwordx4 v130, s[0:1]
	s_waitcnt vmcnt(8)
	s_waitcnt lgkmcnt(0)
	s_barrier
	s_waitcnt lgkmcnt(0)
	v_mfma_f32_16x16x32_bf16 v[126:129], v[144:147], v[178:181], v[126:129]
	v_mfma_f32_16x16x32_bf16 v[126:129], v[148:151], v[182:185], v[126:129]
	v_mfma_f32_16x16x32_bf16 v[122:125], v[158:161], v[182:185], v[122:125]
	v_mfma_f32_16x16x32_bf16 v[122:125], v[154:157], v[178:181], v[122:125]
	v_mfma_f32_16x16x32_bf16 v[118:121], v[162:165], v[178:181], v[118:121]
	v_mfma_f32_16x16x32_bf16 v[118:121], v[166:169], v[182:185], v[118:121]
	v_mfma_f32_16x16x32_bf16 v[114:117], v[174:177], v[182:185], v[114:117]
	v_mfma_f32_16x16x32_bf16 v[114:117], v[170:173], v[178:181], v[114:117]
	v_mfma_f32_16x16x32_bf16 v[98:101], v[170:173], v[186:189], v[98:101]
	v_mfma_f32_16x16x32_bf16 v[98:101], v[174:177], v[190:193], v[98:101]
	v_mfma_f32_16x16x32_bf16 v[102:105], v[166:169], v[190:193], v[102:105]
	v_mfma_f32_16x16x32_bf16 v[102:105], v[162:165], v[186:189], v[102:105]
	v_mfma_f32_16x16x32_bf16 v[106:109], v[154:157], v[186:189], v[106:109]
	v_mfma_f32_16x16x32_bf16 v[106:109], v[158:161], v[190:193], v[106:109]
	v_mfma_f32_16x16x32_bf16 v[110:113], v[148:151], v[190:193], v[110:113]
	v_mfma_f32_16x16x32_bf16 v[110:113], v[144:147], v[186:189], v[110:113]
	v_mfma_f32_16x16x32_bf16 v[94:97], v[144:147], v[204:207], v[94:97]
	v_mfma_f32_16x16x32_bf16 v[94:97], v[148:151], v[208:211], v[94:97]
	v_mfma_f32_16x16x32_bf16 v[90:93], v[158:161], v[208:211], v[90:93]
	v_mfma_f32_16x16x32_bf16 v[90:93], v[154:157], v[204:207], v[90:93]
	v_mfma_f32_16x16x32_bf16 v[86:89], v[162:165], v[204:207], v[86:89]
	v_mfma_f32_16x16x32_bf16 v[86:89], v[166:169], v[208:211], v[86:89]
	v_mfma_f32_16x16x32_bf16 v[82:85], v[174:177], v[208:211], v[82:85]
	v_mfma_f32_16x16x32_bf16 v[82:85], v[170:173], v[204:207], v[82:85]
	v_mfma_f32_16x16x32_bf16 v[66:69], v[170:173], v[212:215], v[66:69]
	v_mfma_f32_16x16x32_bf16 v[66:69], v[174:177], v[216:219], v[66:69]
	v_mfma_f32_16x16x32_bf16 v[70:73], v[166:169], v[216:219], v[70:73]
	v_mfma_f32_16x16x32_bf16 v[70:73], v[162:165], v[212:215], v[70:73]
	v_mfma_f32_16x16x32_bf16 v[74:77], v[154:157], v[212:215], v[74:77]
	v_mfma_f32_16x16x32_bf16 v[74:77], v[158:161], v[216:219], v[74:77]
	v_mfma_f32_16x16x32_bf16 v[78:81], v[148:151], v[216:219], v[78:81]
	v_mfma_f32_16x16x32_bf16 v[78:81], v[144:147], v[212:215], v[78:81]
	s_barrier
	s_add_u32 s98, s64, 0x80
	s_addc_u32 s99, s65, 0
	s_add_u32 s100, s70, 0x80
	s_addc_u32 s101, s71, 0
	s_add_i32 s0, s18, s28
	s_mov_b32 m0, s0
	ds_read_b128 v[178:181], v152 offset:49152
	ds_read_b128 v[182:185], v152 offset:50176
	ds_read_b128 v[186:189], v152 offset:51200
	ds_read_b128 v[190:193], v152 offset:52224
	ds_read_b128 v[204:207], v152 offset:53248
	ds_read_b128 v[208:211], v152 offset:54272
	ds_read_b128 v[212:215], v152 offset:55296
	ds_read_b128 v[216:219], v152 offset:56320
	global_load_lds_dwordx4 v194, s[98:99]
	s_add_i32 m0, s0, 0x2000
	s_add_u32 s0, s64, 0x80080
	s_addc_u32 s1, s65, 0
	s_add_i32 s18, s19, s28
	global_load_lds_dwordx4 v130, s[98:99]
	s_mov_b32 m0, s18
	s_nop 0
	global_load_lds_dwordx4 v194, s[0:1]
	s_add_i32 m0, s18, 0x2000
	s_nop 0
	global_load_lds_dwordx4 v130, s[0:1]
	s_mov_b32 m0, s54
	s_nop 0
	global_load_lds_dwordx4 v194, s[100:101]
	s_mov_b32 m0, s57
	s_nop 0
	global_load_lds_dwordx4 v130, s[100:101]
	s_waitcnt vmcnt(8)
	s_waitcnt lgkmcnt(0)
	s_barrier
	s_waitcnt lgkmcnt(0)
	v_mfma_f32_16x16x32_bf16 v[62:65], v[144:147], v[178:181], v[62:65]
	v_mfma_f32_16x16x32_bf16 v[62:65], v[148:151], v[182:185], v[62:65]
	v_mfma_f32_16x16x32_bf16 v[58:61], v[158:161], v[182:185], v[58:61]
	v_mfma_f32_16x16x32_bf16 v[58:61], v[154:157], v[178:181], v[58:61]
	v_mfma_f32_16x16x32_bf16 v[54:57], v[162:165], v[178:181], v[54:57]
	v_mfma_f32_16x16x32_bf16 v[54:57], v[166:169], v[182:185], v[54:57]
	v_mfma_f32_16x16x32_bf16 v[50:53], v[174:177], v[182:185], v[50:53]
	v_mfma_f32_16x16x32_bf16 v[50:53], v[170:173], v[178:181], v[50:53]
	v_mfma_f32_16x16x32_bf16 v[34:37], v[170:173], v[186:189], v[34:37]
	v_mfma_f32_16x16x32_bf16 v[34:37], v[174:177], v[190:193], v[34:37]
	v_mfma_f32_16x16x32_bf16 v[38:41], v[166:169], v[190:193], v[38:41]
	v_mfma_f32_16x16x32_bf16 v[38:41], v[162:165], v[186:189], v[38:41]
	v_mfma_f32_16x16x32_bf16 v[42:45], v[154:157], v[186:189], v[42:45]
	v_mfma_f32_16x16x32_bf16 v[42:45], v[158:161], v[190:193], v[42:45]
	v_mfma_f32_16x16x32_bf16 v[46:49], v[148:151], v[190:193], v[46:49]
	v_mfma_f32_16x16x32_bf16 v[46:49], v[144:147], v[186:189], v[46:49]
	v_mfma_f32_16x16x32_bf16 v[30:33], v[144:147], v[204:207], v[30:33]
	v_mfma_f32_16x16x32_bf16 v[30:33], v[148:151], v[208:211], v[30:33]
	v_mfma_f32_16x16x32_bf16 v[26:29], v[158:161], v[208:211], v[26:29]
	v_mfma_f32_16x16x32_bf16 v[26:29], v[154:157], v[204:207], v[26:29]
	v_mfma_f32_16x16x32_bf16 v[22:25], v[162:165], v[204:207], v[22:25]
	v_mfma_f32_16x16x32_bf16 v[22:25], v[166:169], v[208:211], v[22:25]
	v_mfma_f32_16x16x32_bf16 v[18:21], v[174:177], v[208:211], v[18:21]
	v_mfma_f32_16x16x32_bf16 v[18:21], v[170:173], v[204:207], v[18:21]
	v_mfma_f32_16x16x32_bf16 v[2:5], v[170:173], v[212:215], v[2:5]
	v_mfma_f32_16x16x32_bf16 v[2:5], v[174:177], v[216:219], v[2:5]
	v_mfma_f32_16x16x32_bf16 v[6:9], v[166:169], v[216:219], v[6:9]
	v_mfma_f32_16x16x32_bf16 v[6:9], v[162:165], v[212:215], v[6:9]
	v_mfma_f32_16x16x32_bf16 v[10:13], v[154:157], v[212:215], v[10:13]
	v_mfma_f32_16x16x32_bf16 v[10:13], v[158:161], v[216:219], v[10:13]
	v_mfma_f32_16x16x32_bf16 v[14:17], v[148:151], v[216:219], v[14:17]
	v_mfma_f32_16x16x32_bf16 v[14:17], v[144:147], v[212:215], v[14:17]
	s_barrier
	s_add_i32 s76, s76, 2
	s_add_u32 s62, s62, 0x100
	s_addc_u32 s63, s63, 0
	s_add_u32 s53, s53, 0x100
	s_addc_u32 s58, s58, 0
	s_cmp_gt_u32 s76, 29
	s_cbranch_scc1 .LBB0_584
	s_branch .LBB0_582

.LBB0_645:
	s_add_u32 s64, s8, 0x100
	s_addc_u32 s65, s9, 0
	s_and_b64 s[0:1], s[70:71], exec
	s_cselect_b32 s77, s63, s65
	s_cselect_b32 s76, s62, s64
	s_cselect_b32 s71, s85, s23
	s_cselect_b32 s70, s84, s7
	s_add_i32 s0, 0, 0x10000
	s_add_i32 s18, 0, 0x14000
	v_add_u32_e32 v106, s0, v1
	v_add_u32_e32 v154, s18, v1
	ds_read_b128 v[70:73], v106
	ds_read_b128 v[82:85], v106 offset:1024
	ds_read_b128 v[94:97], v106 offset:2048
	ds_read_b128 v[106:109], v106 offset:3072
	ds_read_b128 v[118:121], v154
	ds_read_b128 v[130:133], v154 offset:1024
	ds_read_b128 v[142:145], v154 offset:2048
	ds_read_b128 v[154:157], v154 offset:3072
	s_add_i32 m0, s29, 0xc000
	ds_read_b128 v[158:161], v237
	ds_read_b128 v[170:173], v237 offset:1024
	ds_read_b128 v[174:177], v237 offset:2048
	ds_read_b128 v[178:181], v237 offset:3072
	ds_read_b128 v[182:185], v237 offset:4096
	ds_read_b128 v[186:189], v237 offset:5120
	ds_read_b128 v[210:213], v237 offset:6144
	ds_read_b128 v[214:217], v237 offset:7168
	global_load_lds_dwordx4 v206, s[8:9]
	s_add_i32 m0, s29, 0xe000
	s_nop 0
	global_load_lds_dwordx4 v208, s[8:9]
	s_waitcnt vmcnt(8)
	s_waitcnt lgkmcnt(0)
	s_barrier
	s_waitcnt lgkmcnt(0)
	v_mfma_f32_16x16x32_bf16 v[166:169], v[70:73], v[158:161], v[166:169]
	v_mfma_f32_16x16x32_bf16 v[166:169], v[82:85], v[170:173], v[166:169]
	v_mfma_f32_16x16x32_bf16 v[162:165], v[106:109], v[170:173], v[162:165]
	v_mfma_f32_16x16x32_bf16 v[162:165], v[94:97], v[158:161], v[162:165]
	v_mfma_f32_16x16x32_bf16 v[150:153], v[118:121], v[158:161], v[150:153]
	v_mfma_f32_16x16x32_bf16 v[150:153], v[130:133], v[170:173], v[150:153]
	v_mfma_f32_16x16x32_bf16 v[146:149], v[154:157], v[170:173], v[146:149]
	v_mfma_f32_16x16x32_bf16 v[146:149], v[142:145], v[158:161], v[146:149]
	v_mfma_f32_16x16x32_bf16 v[122:125], v[142:145], v[174:177], v[122:125]
	v_mfma_f32_16x16x32_bf16 v[122:125], v[154:157], v[178:181], v[122:125]
	v_mfma_f32_16x16x32_bf16 v[126:129], v[130:133], v[178:181], v[126:129]
	v_mfma_f32_16x16x32_bf16 v[126:129], v[118:121], v[174:177], v[126:129]
	v_mfma_f32_16x16x32_bf16 v[134:137], v[94:97], v[174:177], v[134:137]
	v_mfma_f32_16x16x32_bf16 v[134:137], v[106:109], v[178:181], v[134:137]
	v_mfma_f32_16x16x32_bf16 v[138:141], v[82:85], v[178:181], v[138:141]
	v_mfma_f32_16x16x32_bf16 v[138:141], v[70:73], v[174:177], v[138:141]
	v_mfma_f32_16x16x32_bf16 v[114:117], v[70:73], v[182:185], v[114:117]
	v_mfma_f32_16x16x32_bf16 v[114:117], v[82:85], v[186:189], v[114:117]
	v_mfma_f32_16x16x32_bf16 v[110:113], v[106:109], v[186:189], v[110:113]
	v_mfma_f32_16x16x32_bf16 v[110:113], v[94:97], v[182:185], v[110:113]
	v_mfma_f32_16x16x32_bf16 v[102:105], v[118:121], v[182:185], v[102:105]
	v_mfma_f32_16x16x32_bf16 v[102:105], v[130:133], v[186:189], v[102:105]
	v_mfma_f32_16x16x32_bf16 v[98:101], v[154:157], v[186:189], v[98:101]
	v_mfma_f32_16x16x32_bf16 v[98:101], v[142:145], v[182:185], v[98:101]
	v_mfma_f32_16x16x32_bf16 v[74:77], v[142:145], v[210:213], v[74:77]
	v_mfma_f32_16x16x32_bf16 v[74:77], v[154:157], v[214:217], v[74:77]
	v_mfma_f32_16x16x32_bf16 v[78:81], v[130:133], v[214:217], v[78:81]
	v_mfma_f32_16x16x32_bf16 v[78:81], v[118:121], v[210:213], v[78:81]
	v_mfma_f32_16x16x32_bf16 v[86:89], v[94:97], v[210:213], v[86:89]
	v_mfma_f32_16x16x32_bf16 v[86:89], v[106:109], v[214:217], v[86:89]
	v_mfma_f32_16x16x32_bf16 v[90:93], v[82:85], v[214:217], v[90:93]
	v_mfma_f32_16x16x32_bf16 v[90:93], v[70:73], v[210:213], v[90:93]
	s_barrier
	s_add_i32 s0, s0, s28
	s_mov_b32 m0, s0
	ds_read_b128 v[158:161], v237 offset:16384
	ds_read_b128 v[170:173], v237 offset:17408
	ds_read_b128 v[174:177], v237 offset:18432
	ds_read_b128 v[178:181], v237 offset:19456
	ds_read_b128 v[182:185], v237 offset:20480
	ds_read_b128 v[186:189], v237 offset:21504
	ds_read_b128 v[210:213], v237 offset:22528
	ds_read_b128 v[214:217], v237 offset:23552
	global_load_lds_dwordx4 v192, s[70:71]
	s_add_i32 m0, s0, 0x2000
	s_add_u32 s0, s70, 0x160000
	s_addc_u32 s1, s71, 0
	s_add_i32 s8, s18, s28
	global_load_lds_dwordx4 v190, s[70:71]
	s_mov_b32 m0, s8
	s_nop 0
	global_load_lds_dwordx4 v192, s[0:1]
	s_add_i32 m0, s8, 0x2000
	s_nop 0
	global_load_lds_dwordx4 v190, s[0:1]
	s_mov_b32 m0, s29
	s_nop 0
	global_load_lds_dwordx4 v192, s[76:77]
	s_mov_b32 m0, s31
	s_nop 0
	global_load_lds_dwordx4 v190, s[76:77]
	s_waitcnt vmcnt(8)
	s_waitcnt lgkmcnt(0)
	s_barrier
	s_waitcnt lgkmcnt(0)
	v_mfma_f32_16x16x32_bf16 v[62:65], v[70:73], v[158:161], v[62:65]
	v_mfma_f32_16x16x32_bf16 v[62:65], v[82:85], v[170:173], v[62:65]
	v_mfma_f32_16x16x32_bf16 v[58:61], v[106:109], v[170:173], v[58:61]
	v_mfma_f32_16x16x32_bf16 v[58:61], v[94:97], v[158:161], v[58:61]
	v_mfma_f32_16x16x32_bf16 v[54:57], v[118:121], v[158:161], v[54:57]
	v_mfma_f32_16x16x32_bf16 v[54:57], v[130:133], v[170:173], v[54:57]
	v_mfma_f32_16x16x32_bf16 v[50:53], v[154:157], v[170:173], v[50:53]
	v_mfma_f32_16x16x32_bf16 v[50:53], v[142:145], v[158:161], v[50:53]
	v_mfma_f32_16x16x32_bf16 v[34:37], v[142:145], v[174:177], v[34:37]
	v_mfma_f32_16x16x32_bf16 v[34:37], v[154:157], v[178:181], v[34:37]
	v_mfma_f32_16x16x32_bf16 v[38:41], v[130:133], v[178:181], v[38:41]
	v_mfma_f32_16x16x32_bf16 v[38:41], v[118:121], v[174:177], v[38:41]
	v_mfma_f32_16x16x32_bf16 v[42:45], v[94:97], v[174:177], v[42:45]
	v_mfma_f32_16x16x32_bf16 v[42:45], v[106:109], v[178:181], v[42:45]
	v_mfma_f32_16x16x32_bf16 v[46:49], v[82:85], v[178:181], v[46:49]
	v_mfma_f32_16x16x32_bf16 v[46:49], v[70:73], v[174:177], v[46:49]
	v_mfma_f32_16x16x32_bf16 v[30:33], v[70:73], v[182:185], v[30:33]
	v_mfma_f32_16x16x32_bf16 v[30:33], v[82:85], v[186:189], v[30:33]
	v_mfma_f32_16x16x32_bf16 v[26:29], v[106:109], v[186:189], v[26:29]
	v_mfma_f32_16x16x32_bf16 v[26:29], v[94:97], v[182:185], v[26:29]
	v_mfma_f32_16x16x32_bf16 v[22:25], v[118:121], v[182:185], v[22:25]
	v_mfma_f32_16x16x32_bf16 v[22:25], v[130:133], v[186:189], v[22:25]
	v_mfma_f32_16x16x32_bf16 v[18:21], v[154:157], v[186:189], v[18:21]
	v_mfma_f32_16x16x32_bf16 v[18:21], v[142:145], v[182:185], v[18:21]
	v_mfma_f32_16x16x32_bf16 v[2:5], v[142:145], v[210:213], v[2:5]
	v_mfma_f32_16x16x32_bf16 v[2:5], v[154:157], v[214:217], v[2:5]
	v_mfma_f32_16x16x32_bf16 v[6:9], v[130:133], v[214:217], v[6:9]
	v_mfma_f32_16x16x32_bf16 v[6:9], v[118:121], v[210:213], v[6:9]
	v_mfma_f32_16x16x32_bf16 v[10:13], v[94:97], v[210:213], v[10:13]
	v_mfma_f32_16x16x32_bf16 v[10:13], v[106:109], v[214:217], v[10:13]
	v_mfma_f32_16x16x32_bf16 v[14:17], v[82:85], v[214:217], v[14:17]
	v_mfma_f32_16x16x32_bf16 v[14:17], v[70:73], v[210:213], v[14:17]
	s_barrier
	s_add_i32 s8, 0, 0x18000
	s_add_i32 s9, 0, 0x1c000
	v_add_u32_e32 v106, s8, v1
	v_add_u32_e32 v154, s9, v1
	ds_read_b128 v[70:73], v106
	ds_read_b128 v[82:85], v106 offset:1024
	ds_read_b128 v[94:97], v106 offset:2048
	ds_read_b128 v[106:109], v106 offset:3072
	ds_read_b128 v[118:121], v154
	ds_read_b128 v[130:133], v154 offset:1024
	ds_read_b128 v[142:145], v154 offset:2048
	ds_read_b128 v[154:157], v154 offset:3072
	s_add_u32 s0, s76, 0x160000
	s_addc_u32 s1, s77, 0
	s_mov_b32 m0, s33
	ds_read_b128 v[158:161], v237 offset:32768
	ds_read_b128 v[170:173], v237 offset:33792
	ds_read_b128 v[174:177], v237 offset:34816
	ds_read_b128 v[178:181], v237 offset:35840
	ds_read_b128 v[182:185], v237 offset:36864
	ds_read_b128 v[186:189], v237 offset:37888
	ds_read_b128 v[210:213], v237 offset:38912
	ds_read_b128 v[214:217], v237 offset:39936
	global_load_lds_dwordx4 v192, s[0:1]
	s_mov_b32 m0, s43
	s_nop 0
	global_load_lds_dwordx4 v190, s[0:1]
	s_waitcnt vmcnt(8)
	s_waitcnt lgkmcnt(0)
	s_barrier
	s_waitcnt lgkmcnt(0)
	v_mfma_f32_16x16x32_bf16 v[166:169], v[70:73], v[158:161], v[166:169]
	v_mfma_f32_16x16x32_bf16 v[166:169], v[82:85], v[170:173], v[166:169]
	v_mfma_f32_16x16x32_bf16 v[162:165], v[106:109], v[170:173], v[162:165]
	v_mfma_f32_16x16x32_bf16 v[162:165], v[94:97], v[158:161], v[162:165]
	v_mfma_f32_16x16x32_bf16 v[150:153], v[118:121], v[158:161], v[150:153]
	v_mfma_f32_16x16x32_bf16 v[150:153], v[130:133], v[170:173], v[150:153]
	v_mfma_f32_16x16x32_bf16 v[146:149], v[154:157], v[170:173], v[146:149]
	v_mfma_f32_16x16x32_bf16 v[146:149], v[142:145], v[158:161], v[146:149]
	v_mfma_f32_16x16x32_bf16 v[122:125], v[142:145], v[174:177], v[122:125]
	v_mfma_f32_16x16x32_bf16 v[122:125], v[154:157], v[178:181], v[122:125]
	v_mfma_f32_16x16x32_bf16 v[126:129], v[130:133], v[178:181], v[126:129]
	v_mfma_f32_16x16x32_bf16 v[126:129], v[118:121], v[174:177], v[126:129]
	v_mfma_f32_16x16x32_bf16 v[134:137], v[94:97], v[174:177], v[134:137]
	v_mfma_f32_16x16x32_bf16 v[134:137], v[106:109], v[178:181], v[134:137]
	v_mfma_f32_16x16x32_bf16 v[138:141], v[82:85], v[178:181], v[138:141]
	v_mfma_f32_16x16x32_bf16 v[138:141], v[70:73], v[174:177], v[138:141]
	v_mfma_f32_16x16x32_bf16 v[114:117], v[70:73], v[182:185], v[114:117]
	v_mfma_f32_16x16x32_bf16 v[114:117], v[82:85], v[186:189], v[114:117]
	v_mfma_f32_16x16x32_bf16 v[110:113], v[106:109], v[186:189], v[110:113]
	v_mfma_f32_16x16x32_bf16 v[110:113], v[94:97], v[182:185], v[110:113]
	v_mfma_f32_16x16x32_bf16 v[102:105], v[118:121], v[182:185], v[102:105]
	v_mfma_f32_16x16x32_bf16 v[102:105], v[130:133], v[186:189], v[102:105]
	v_mfma_f32_16x16x32_bf16 v[98:101], v[154:157], v[186:189], v[98:101]
	v_mfma_f32_16x16x32_bf16 v[98:101], v[142:145], v[182:185], v[98:101]
	v_mfma_f32_16x16x32_bf16 v[74:77], v[142:145], v[210:213], v[74:77]
	v_mfma_f32_16x16x32_bf16 v[74:77], v[154:157], v[214:217], v[74:77]
	v_mfma_f32_16x16x32_bf16 v[78:81], v[130:133], v[214:217], v[78:81]
	v_mfma_f32_16x16x32_bf16 v[78:81], v[118:121], v[210:213], v[78:81]
	v_mfma_f32_16x16x32_bf16 v[86:89], v[94:97], v[210:213], v[86:89]
	v_mfma_f32_16x16x32_bf16 v[86:89], v[106:109], v[214:217], v[86:89]
	v_mfma_f32_16x16x32_bf16 v[90:93], v[82:85], v[214:217], v[90:93]
	v_mfma_f32_16x16x32_bf16 v[90:93], v[70:73], v[210:213], v[90:93]
	s_barrier
	s_add_u32 s98, s70, 0x80
	s_addc_u32 s99, s71, 0
	s_add_u32 s100, s76, 0x80
	s_addc_u32 s101, s77, 0
	s_add_i32 s0, s8, s28
	s_mov_b32 m0, s0
	ds_read_b128 v[158:161], v237 offset:49152
	ds_read_b128 v[170:173], v237 offset:50176
	ds_read_b128 v[174:177], v237 offset:51200
	ds_read_b128 v[178:181], v237 offset:52224
	ds_read_b128 v[182:185], v237 offset:53248
	ds_read_b128 v[186:189], v237 offset:54272
	ds_read_b128 v[210:213], v237 offset:55296
	ds_read_b128 v[214:217], v237 offset:56320
	global_load_lds_dwordx4 v192, s[98:99]
	s_add_i32 m0, s0, 0x2000
	s_add_u32 s0, s70, 0x160080
	s_addc_u32 s1, s71, 0
	s_add_i32 s8, s9, s28
	global_load_lds_dwordx4 v190, s[98:99]
	s_mov_b32 m0, s8
	s_nop 0
	global_load_lds_dwordx4 v192, s[0:1]
	s_add_i32 m0, s8, 0x2000
	s_nop 0
	global_load_lds_dwordx4 v190, s[0:1]
	s_mov_b32 m0, s68
	s_nop 0
	global_load_lds_dwordx4 v192, s[100:101]
	s_mov_b32 m0, s79
	s_nop 0
	global_load_lds_dwordx4 v190, s[100:101]
	s_waitcnt vmcnt(8)
	s_waitcnt lgkmcnt(0)
	s_barrier
	s_waitcnt lgkmcnt(0)
	v_mfma_f32_16x16x32_bf16 v[62:65], v[70:73], v[158:161], v[62:65]
	v_mfma_f32_16x16x32_bf16 v[62:65], v[82:85], v[170:173], v[62:65]
	v_mfma_f32_16x16x32_bf16 v[58:61], v[106:109], v[170:173], v[58:61]
	v_mfma_f32_16x16x32_bf16 v[58:61], v[94:97], v[158:161], v[58:61]
	v_mfma_f32_16x16x32_bf16 v[54:57], v[118:121], v[158:161], v[54:57]
	v_mfma_f32_16x16x32_bf16 v[54:57], v[130:133], v[170:173], v[54:57]
	v_mfma_f32_16x16x32_bf16 v[50:53], v[154:157], v[170:173], v[50:53]
	v_mfma_f32_16x16x32_bf16 v[50:53], v[142:145], v[158:161], v[50:53]
	v_mfma_f32_16x16x32_bf16 v[34:37], v[142:145], v[174:177], v[34:37]
	v_mfma_f32_16x16x32_bf16 v[34:37], v[154:157], v[178:181], v[34:37]
	v_mfma_f32_16x16x32_bf16 v[38:41], v[130:133], v[178:181], v[38:41]
	v_mfma_f32_16x16x32_bf16 v[38:41], v[118:121], v[174:177], v[38:41]
	v_mfma_f32_16x16x32_bf16 v[42:45], v[94:97], v[174:177], v[42:45]
	v_mfma_f32_16x16x32_bf16 v[42:45], v[106:109], v[178:181], v[42:45]
	v_mfma_f32_16x16x32_bf16 v[46:49], v[82:85], v[178:181], v[46:49]
	v_mfma_f32_16x16x32_bf16 v[46:49], v[70:73], v[174:177], v[46:49]
	v_mfma_f32_16x16x32_bf16 v[30:33], v[70:73], v[182:185], v[30:33]
	v_mfma_f32_16x16x32_bf16 v[30:33], v[82:85], v[186:189], v[30:33]
	v_mfma_f32_16x16x32_bf16 v[26:29], v[106:109], v[186:189], v[26:29]
	v_mfma_f32_16x16x32_bf16 v[26:29], v[94:97], v[182:185], v[26:29]
	v_mfma_f32_16x16x32_bf16 v[22:25], v[118:121], v[182:185], v[22:25]
	v_mfma_f32_16x16x32_bf16 v[22:25], v[130:133], v[186:189], v[22:25]
	v_mfma_f32_16x16x32_bf16 v[18:21], v[154:157], v[186:189], v[18:21]
	v_mfma_f32_16x16x32_bf16 v[18:21], v[142:145], v[182:185], v[18:21]
	v_mfma_f32_16x16x32_bf16 v[2:5], v[142:145], v[210:213], v[2:5]
	v_mfma_f32_16x16x32_bf16 v[2:5], v[154:157], v[214:217], v[2:5]
	v_mfma_f32_16x16x32_bf16 v[6:9], v[130:133], v[214:217], v[6:9]
	v_mfma_f32_16x16x32_bf16 v[6:9], v[118:121], v[210:213], v[6:9]
	v_mfma_f32_16x16x32_bf16 v[10:13], v[94:97], v[210:213], v[10:13]
	v_mfma_f32_16x16x32_bf16 v[10:13], v[106:109], v[214:217], v[10:13]
	v_mfma_f32_16x16x32_bf16 v[14:17], v[82:85], v[214:217], v[14:17]
	v_mfma_f32_16x16x32_bf16 v[14:17], v[70:73], v[210:213], v[14:17]
	s_barrier
	s_add_i32 s41, s41, 2
	s_add_u32 s7, s7, 0x100
	s_addc_u32 s23, s23, 0
	s_cmpk_gt_u32 s41, 0x55
	s_mov_b64 s[8:9], s[64:65]
	s_cbranch_scc1 .LBB0_648

.Lpeel_disp_down:
	s_cmp_lg_u32 s41, -2
	s_cbranch_scc1 .LBB0_645
	s_add_u32 s64, s8, 0x100
	s_addc_u32 s65, s9, 0
	s_and_b64 s[0:1], s[70:71], exec
	s_cselect_b32 s77, s63, s65
	s_cselect_b32 s76, s62, s64
	s_cselect_b32 s71, s85, s23
	s_cselect_b32 s70, s84, s7
	s_add_i32 s0, 0, 0x10000
	s_add_i32 s18, 0, 0x14000
	v_add_u32_e32 v106, s0, v1
	v_add_u32_e32 v154, s18, v1
	ds_read_b128 v[70:73], v106
	ds_read_b128 v[82:85], v106 offset:1024
	ds_read_b128 v[94:97], v106 offset:2048
	ds_read_b128 v[106:109], v106 offset:3072
	ds_read_b128 v[118:121], v154
	ds_read_b128 v[130:133], v154 offset:1024
	ds_read_b128 v[142:145], v154 offset:2048
	ds_read_b128 v[154:157], v154 offset:3072
	s_add_i32 m0, s29, 0xc000
	ds_read_b128 v[158:161], v237
	ds_read_b128 v[170:173], v237 offset:1024
	ds_read_b128 v[174:177], v237 offset:2048
	ds_read_b128 v[178:181], v237 offset:3072
	ds_read_b128 v[182:185], v237 offset:4096
	ds_read_b128 v[186:189], v237 offset:5120
	ds_read_b128 v[210:213], v237 offset:6144
	ds_read_b128 v[214:217], v237 offset:7168
	global_load_lds_dwordx4 v206, s[8:9]
	s_add_i32 m0, s29, 0xe000
	s_nop 0
	global_load_lds_dwordx4 v208, s[8:9]
	s_waitcnt vmcnt(8)
	s_waitcnt lgkmcnt(0)
	s_barrier
	s_waitcnt lgkmcnt(0)
	v_mfma_f32_16x16x32_bf16 v[166:169], v[70:73], v[158:161], 0
	v_mfma_f32_16x16x32_bf16 v[166:169], v[82:85], v[170:173], v[166:169]
	v_mfma_f32_16x16x32_bf16 v[162:165], v[106:109], v[170:173], 0
	v_mfma_f32_16x16x32_bf16 v[162:165], v[94:97], v[158:161], v[162:165]
	v_mfma_f32_16x16x32_bf16 v[150:153], v[118:121], v[158:161], 0
	v_mfma_f32_16x16x32_bf16 v[150:153], v[130:133], v[170:173], v[150:153]
	v_mfma_f32_16x16x32_bf16 v[146:149], v[154:157], v[170:173], 0
	v_mfma_f32_16x16x32_bf16 v[146:149], v[142:145], v[158:161], v[146:149]
	v_mfma_f32_16x16x32_bf16 v[122:125], v[142:145], v[174:177], 0
	v_mfma_f32_16x16x32_bf16 v[122:125], v[154:157], v[178:181], v[122:125]
	v_mfma_f32_16x16x32_bf16 v[126:129], v[130:133], v[178:181], 0
	v_mfma_f32_16x16x32_bf16 v[126:129], v[118:121], v[174:177], v[126:129]
	v_mfma_f32_16x16x32_bf16 v[134:137], v[94:97], v[174:177], 0
	v_mfma_f32_16x16x32_bf16 v[134:137], v[106:109], v[178:181], v[134:137]
	v_mfma_f32_16x16x32_bf16 v[138:141], v[82:85], v[178:181], 0
	v_mfma_f32_16x16x32_bf16 v[138:141], v[70:73], v[174:177], v[138:141]
	v_mfma_f32_16x16x32_bf16 v[114:117], v[70:73], v[182:185], 0
	v_mfma_f32_16x16x32_bf16 v[114:117], v[82:85], v[186:189], v[114:117]
	v_mfma_f32_16x16x32_bf16 v[110:113], v[106:109], v[186:189], 0
	v_mfma_f32_16x16x32_bf16 v[110:113], v[94:97], v[182:185], v[110:113]
	v_mfma_f32_16x16x32_bf16 v[102:105], v[118:121], v[182:185], 0
	v_mfma_f32_16x16x32_bf16 v[102:105], v[130:133], v[186:189], v[102:105]
	v_mfma_f32_16x16x32_bf16 v[98:101], v[154:157], v[186:189], 0
	v_mfma_f32_16x16x32_bf16 v[98:101], v[142:145], v[182:185], v[98:101]
	v_mfma_f32_16x16x32_bf16 v[74:77], v[142:145], v[210:213], 0
	v_mfma_f32_16x16x32_bf16 v[74:77], v[154:157], v[214:217], v[74:77]
	v_mfma_f32_16x16x32_bf16 v[78:81], v[130:133], v[214:217], 0
	v_mfma_f32_16x16x32_bf16 v[78:81], v[118:121], v[210:213], v[78:81]
	v_mfma_f32_16x16x32_bf16 v[86:89], v[94:97], v[210:213], 0
	v_mfma_f32_16x16x32_bf16 v[86:89], v[106:109], v[214:217], v[86:89]
	v_mfma_f32_16x16x32_bf16 v[90:93], v[82:85], v[214:217], 0
	v_mfma_f32_16x16x32_bf16 v[90:93], v[70:73], v[210:213], v[90:93]
	s_barrier
	s_add_i32 s0, s0, s28
	s_mov_b32 m0, s0
	ds_read_b128 v[158:161], v237 offset:16384
	ds_read_b128 v[170:173], v237 offset:17408
	ds_read_b128 v[174:177], v237 offset:18432
	ds_read_b128 v[178:181], v237 offset:19456
	ds_read_b128 v[182:185], v237 offset:20480
	ds_read_b128 v[186:189], v237 offset:21504
	ds_read_b128 v[210:213], v237 offset:22528
	ds_read_b128 v[214:217], v237 offset:23552
	global_load_lds_dwordx4 v192, s[70:71]
	s_add_i32 m0, s0, 0x2000
	s_add_u32 s0, s70, 0x160000
	s_addc_u32 s1, s71, 0
	s_add_i32 s8, s18, s28
	global_load_lds_dwordx4 v190, s[70:71]
	s_mov_b32 m0, s8
	s_nop 0
	global_load_lds_dwordx4 v192, s[0:1]
	s_add_i32 m0, s8, 0x2000
	s_nop 0
	global_load_lds_dwordx4 v190, s[0:1]
	s_mov_b32 m0, s29
	s_nop 0
	global_load_lds_dwordx4 v192, s[76:77]
	s_mov_b32 m0, s31
	s_nop 0
	global_load_lds_dwordx4 v190, s[76:77]
	s_waitcnt vmcnt(8)
	s_waitcnt lgkmcnt(0)
	s_barrier
	s_waitcnt lgkmcnt(0)
	v_mfma_f32_16x16x32_bf16 v[62:65], v[70:73], v[158:161], 0
	v_mfma_f32_16x16x32_bf16 v[62:65], v[82:85], v[170:173], v[62:65]
	v_mfma_f32_16x16x32_bf16 v[58:61], v[106:109], v[170:173], 0
	v_mfma_f32_16x16x32_bf16 v[58:61], v[94:97], v[158:161], v[58:61]
	v_mfma_f32_16x16x32_bf16 v[54:57], v[118:121], v[158:161], 0
	v_mfma_f32_16x16x32_bf16 v[54:57], v[130:133], v[170:173], v[54:57]
	v_mfma_f32_16x16x32_bf16 v[50:53], v[154:157], v[170:173], 0
	v_mfma_f32_16x16x32_bf16 v[50:53], v[142:145], v[158:161], v[50:53]
	v_mfma_f32_16x16x32_bf16 v[34:37], v[142:145], v[174:177], 0
	v_mfma_f32_16x16x32_bf16 v[34:37], v[154:157], v[178:181], v[34:37]
	v_mfma_f32_16x16x32_bf16 v[38:41], v[130:133], v[178:181], 0
	v_mfma_f32_16x16x32_bf16 v[38:41], v[118:121], v[174:177], v[38:41]
	v_mfma_f32_16x16x32_bf16 v[42:45], v[94:97], v[174:177], 0
	v_mfma_f32_16x16x32_bf16 v[42:45], v[106:109], v[178:181], v[42:45]
	v_mfma_f32_16x16x32_bf16 v[46:49], v[82:85], v[178:181], 0
	v_mfma_f32_16x16x32_bf16 v[46:49], v[70:73], v[174:177], v[46:49]
	v_mfma_f32_16x16x32_bf16 v[30:33], v[70:73], v[182:185], 0
	v_mfma_f32_16x16x32_bf16 v[30:33], v[82:85], v[186:189], v[30:33]
	v_mfma_f32_16x16x32_bf16 v[26:29], v[106:109], v[186:189], 0
	v_mfma_f32_16x16x32_bf16 v[26:29], v[94:97], v[182:185], v[26:29]
	v_mfma_f32_16x16x32_bf16 v[22:25], v[118:121], v[182:185], 0
	v_mfma_f32_16x16x32_bf16 v[22:25], v[130:133], v[186:189], v[22:25]
	v_mfma_f32_16x16x32_bf16 v[18:21], v[154:157], v[186:189], 0
	v_mfma_f32_16x16x32_bf16 v[18:21], v[142:145], v[182:185], v[18:21]
	v_mfma_f32_16x16x32_bf16 v[2:5], v[142:145], v[210:213], 0
	v_mfma_f32_16x16x32_bf16 v[2:5], v[154:157], v[214:217], v[2:5]
	v_mfma_f32_16x16x32_bf16 v[6:9], v[130:133], v[214:217], 0
	v_mfma_f32_16x16x32_bf16 v[6:9], v[118:121], v[210:213], v[6:9]
	v_mfma_f32_16x16x32_bf16 v[10:13], v[94:97], v[210:213], 0
	v_mfma_f32_16x16x32_bf16 v[10:13], v[106:109], v[214:217], v[10:13]
	v_mfma_f32_16x16x32_bf16 v[14:17], v[82:85], v[214:217], 0
	v_mfma_f32_16x16x32_bf16 v[14:17], v[70:73], v[210:213], v[14:17]
	s_barrier
	s_add_i32 s8, 0, 0x18000
	s_add_i32 s9, 0, 0x1c000
	v_add_u32_e32 v106, s8, v1
	v_add_u32_e32 v154, s9, v1
	ds_read_b128 v[70:73], v106
	ds_read_b128 v[82:85], v106 offset:1024
	ds_read_b128 v[94:97], v106 offset:2048
	ds_read_b128 v[106:109], v106 offset:3072
	ds_read_b128 v[118:121], v154
	ds_read_b128 v[130:133], v154 offset:1024
	ds_read_b128 v[142:145], v154 offset:2048
	ds_read_b128 v[154:157], v154 offset:3072
	s_add_u32 s0, s76, 0x160000
	s_addc_u32 s1, s77, 0
	s_mov_b32 m0, s33
	ds_read_b128 v[158:161], v237 offset:32768
	ds_read_b128 v[170:173], v237 offset:33792
	ds_read_b128 v[174:177], v237 offset:34816
	ds_read_b128 v[178:181], v237 offset:35840
	ds_read_b128 v[182:185], v237 offset:36864
	ds_read_b128 v[186:189], v237 offset:37888
	ds_read_b128 v[210:213], v237 offset:38912
	ds_read_b128 v[214:217], v237 offset:39936
	global_load_lds_dwordx4 v192, s[0:1]
	s_mov_b32 m0, s43
	s_nop 0
	global_load_lds_dwordx4 v190, s[0:1]
	s_waitcnt vmcnt(8)
	s_waitcnt lgkmcnt(0)
	s_barrier
	s_waitcnt lgkmcnt(0)
	v_mfma_f32_16x16x32_bf16 v[166:169], v[70:73], v[158:161], v[166:169]
	v_mfma_f32_16x16x32_bf16 v[166:169], v[82:85], v[170:173], v[166:169]
	v_mfma_f32_16x16x32_bf16 v[162:165], v[106:109], v[170:173], v[162:165]
	v_mfma_f32_16x16x32_bf16 v[162:165], v[94:97], v[158:161], v[162:165]
	v_mfma_f32_16x16x32_bf16 v[150:153], v[118:121], v[158:161], v[150:153]
	v_mfma_f32_16x16x32_bf16 v[150:153], v[130:133], v[170:173], v[150:153]
	v_mfma_f32_16x16x32_bf16 v[146:149], v[154:157], v[170:173], v[146:149]
	v_mfma_f32_16x16x32_bf16 v[146:149], v[142:145], v[158:161], v[146:149]
	v_mfma_f32_16x16x32_bf16 v[122:125], v[142:145], v[174:177], v[122:125]
	v_mfma_f32_16x16x32_bf16 v[122:125], v[154:157], v[178:181], v[122:125]
	v_mfma_f32_16x16x32_bf16 v[126:129], v[130:133], v[178:181], v[126:129]
	v_mfma_f32_16x16x32_bf16 v[126:129], v[118:121], v[174:177], v[126:129]
	v_mfma_f32_16x16x32_bf16 v[134:137], v[94:97], v[174:177], v[134:137]
	v_mfma_f32_16x16x32_bf16 v[134:137], v[106:109], v[178:181], v[134:137]
	v_mfma_f32_16x16x32_bf16 v[138:141], v[82:85], v[178:181], v[138:141]
	v_mfma_f32_16x16x32_bf16 v[138:141], v[70:73], v[174:177], v[138:141]
	v_mfma_f32_16x16x32_bf16 v[114:117], v[70:73], v[182:185], v[114:117]
	v_mfma_f32_16x16x32_bf16 v[114:117], v[82:85], v[186:189], v[114:117]
	v_mfma_f32_16x16x32_bf16 v[110:113], v[106:109], v[186:189], v[110:113]
	v_mfma_f32_16x16x32_bf16 v[110:113], v[94:97], v[182:185], v[110:113]
	v_mfma_f32_16x16x32_bf16 v[102:105], v[118:121], v[182:185], v[102:105]
	v_mfma_f32_16x16x32_bf16 v[102:105], v[130:133], v[186:189], v[102:105]
	v_mfma_f32_16x16x32_bf16 v[98:101], v[154:157], v[186:189], v[98:101]
	v_mfma_f32_16x16x32_bf16 v[98:101], v[142:145], v[182:185], v[98:101]
	v_mfma_f32_16x16x32_bf16 v[74:77], v[142:145], v[210:213], v[74:77]
	v_mfma_f32_16x16x32_bf16 v[74:77], v[154:157], v[214:217], v[74:77]
	v_mfma_f32_16x16x32_bf16 v[78:81], v[130:133], v[214:217], v[78:81]
	v_mfma_f32_16x16x32_bf16 v[78:81], v[118:121], v[210:213], v[78:81]
	v_mfma_f32_16x16x32_bf16 v[86:89], v[94:97], v[210:213], v[86:89]
	v_mfma_f32_16x16x32_bf16 v[86:89], v[106:109], v[214:217], v[86:89]
	v_mfma_f32_16x16x32_bf16 v[90:93], v[82:85], v[214:217], v[90:93]
	v_mfma_f32_16x16x32_bf16 v[90:93], v[70:73], v[210:213], v[90:93]
	s_barrier
	s_add_u32 s98, s70, 0x80
	s_addc_u32 s99, s71, 0
	s_add_u32 s100, s76, 0x80
	s_addc_u32 s101, s77, 0
	s_add_i32 s0, s8, s28
	s_mov_b32 m0, s0
	ds_read_b128 v[158:161], v237 offset:49152
	ds_read_b128 v[170:173], v237 offset:50176
	ds_read_b128 v[174:177], v237 offset:51200
	ds_read_b128 v[178:181], v237 offset:52224
	ds_read_b128 v[182:185], v237 offset:53248
	ds_read_b128 v[186:189], v237 offset:54272
	ds_read_b128 v[210:213], v237 offset:55296
	ds_read_b128 v[214:217], v237 offset:56320
	global_load_lds_dwordx4 v192, s[98:99]
	s_add_i32 m0, s0, 0x2000
	s_add_u32 s0, s70, 0x160080
	s_addc_u32 s1, s71, 0
	s_add_i32 s8, s9, s28
	global_load_lds_dwordx4 v190, s[98:99]
	s_mov_b32 m0, s8
	s_nop 0
	global_load_lds_dwordx4 v192, s[0:1]
	s_add_i32 m0, s8, 0x2000
	s_nop 0
	global_load_lds_dwordx4 v190, s[0:1]
	s_mov_b32 m0, s68
	s_nop 0
	global_load_lds_dwordx4 v192, s[100:101]
	s_mov_b32 m0, s79
	s_nop 0
	global_load_lds_dwordx4 v190, s[100:101]
	s_waitcnt vmcnt(8)
	s_waitcnt lgkmcnt(0)
	s_barrier
	s_waitcnt lgkmcnt(0)
	v_mfma_f32_16x16x32_bf16 v[62:65], v[70:73], v[158:161], v[62:65]
	v_mfma_f32_16x16x32_bf16 v[62:65], v[82:85], v[170:173], v[62:65]
	v_mfma_f32_16x16x32_bf16 v[58:61], v[106:109], v[170:173], v[58:61]
	v_mfma_f32_16x16x32_bf16 v[58:61], v[94:97], v[158:161], v[58:61]
	v_mfma_f32_16x16x32_bf16 v[54:57], v[118:121], v[158:161], v[54:57]
	v_mfma_f32_16x16x32_bf16 v[54:57], v[130:133], v[170:173], v[54:57]
	v_mfma_f32_16x16x32_bf16 v[50:53], v[154:157], v[170:173], v[50:53]
	v_mfma_f32_16x16x32_bf16 v[50:53], v[142:145], v[158:161], v[50:53]
	v_mfma_f32_16x16x32_bf16 v[34:37], v[142:145], v[174:177], v[34:37]
	v_mfma_f32_16x16x32_bf16 v[34:37], v[154:157], v[178:181], v[34:37]
	v_mfma_f32_16x16x32_bf16 v[38:41], v[130:133], v[178:181], v[38:41]
	v_mfma_f32_16x16x32_bf16 v[38:41], v[118:121], v[174:177], v[38:41]
	v_mfma_f32_16x16x32_bf16 v[42:45], v[94:97], v[174:177], v[42:45]
	v_mfma_f32_16x16x32_bf16 v[42:45], v[106:109], v[178:181], v[42:45]
	v_mfma_f32_16x16x32_bf16 v[46:49], v[82:85], v[178:181], v[46:49]
	v_mfma_f32_16x16x32_bf16 v[46:49], v[70:73], v[174:177], v[46:49]
	v_mfma_f32_16x16x32_bf16 v[30:33], v[70:73], v[182:185], v[30:33]
	v_mfma_f32_16x16x32_bf16 v[30:33], v[82:85], v[186:189], v[30:33]
	v_mfma_f32_16x16x32_bf16 v[26:29], v[106:109], v[186:189], v[26:29]
	v_mfma_f32_16x16x32_bf16 v[26:29], v[94:97], v[182:185], v[26:29]
	v_mfma_f32_16x16x32_bf16 v[22:25], v[118:121], v[182:185], v[22:25]
	v_mfma_f32_16x16x32_bf16 v[22:25], v[130:133], v[186:189], v[22:25]
	v_mfma_f32_16x16x32_bf16 v[18:21], v[154:157], v[186:189], v[18:21]
	v_mfma_f32_16x16x32_bf16 v[18:21], v[142:145], v[182:185], v[18:21]
	v_mfma_f32_16x16x32_bf16 v[2:5], v[142:145], v[210:213], v[2:5]
	v_mfma_f32_16x16x32_bf16 v[2:5], v[154:157], v[214:217], v[2:5]
	v_mfma_f32_16x16x32_bf16 v[6:9], v[130:133], v[214:217], v[6:9]
	v_mfma_f32_16x16x32_bf16 v[6:9], v[118:121], v[210:213], v[6:9]
	v_mfma_f32_16x16x32_bf16 v[10:13], v[94:97], v[210:213], v[10:13]
	v_mfma_f32_16x16x32_bf16 v[10:13], v[106:109], v[214:217], v[10:13]
	v_mfma_f32_16x16x32_bf16 v[14:17], v[82:85], v[214:217], v[14:17]
	v_mfma_f32_16x16x32_bf16 v[14:17], v[70:73], v[210:213], v[14:17]
	s_barrier
	s_add_i32 s41, s41, 2
	s_add_u32 s7, s7, 0x100
	s_addc_u32 s23, s23, 0
	s_cmpk_gt_u32 s41, 0x55
	s_mov_b64 s[8:9], s[64:65]
	s_cbranch_scc1 .LBB0_648
	s_branch .LBB0_646
